# speedup vs baseline: 1.0006x; 1.0006x over previous
; #define tidx() tidx_(wv_)
; __device__ __forceinline__ void conv_run(const float* __restrict__ src, u16* __restrict__ dst, int K, int N, int mode, int& base,
;                                          float* lds, int gi, int ng, int wv_) {
;   const int nk = K / 128, nn = N / 64, ntiles = nk * nn;
;   const int t = tidx();
;   int lt = (base & 1) ? (ng - 1 - gi) : gi;
;   base += 1;
;   float4 ra[2], rb[2];
;   auto gl = [&](int tile) {
;     const int k0 = (tile % nk) * 128, n0 = (tile / nk) * 64;
; #pragma unroll
;     for (int i = 0; i < 2; ++i) {
;       const int kl = (t >> 3) + 64 * i, c8 = (t & 7) * 8;
;       typedef float f4v __attribute__((ext_vector_type(4)));
;       const f4v* sp = (const f4v*)(src + (size_t)(k0 + kl) * N + n0 + c8);
;       const f4v va = __builtin_nontemporal_load(sp), vb = __builtin_nontemporal_load(sp + 1);
;       ra[i] = make_float4(va.x, va.y, va.z, va.w); rb[i] = make_float4(vb.x, vb.y, vb.z, vb.w);
;     }
;   };
;   __syncthreads();
;   if (lt < ntiles) gl(lt);
; __global__ void __launch_bounds__(NTHREADS) fwd_megakernel(Params p) {
;     ...
;   const int wv_ = __builtin_amdgcn_readfirstlane((int)(threadIdx.x >> 6));
;   unsigned char* ws = (unsigned char*)inp(nullptr, 34);
;   u16* shm = (u16*)lds;
;   for (int rep = 0; rep < 1 + DUP_CONV; ++rep) convert_set(ws, 0, bidx(), gridDim.x, (float*)lds, wv_);
_Z14fwd_megakernel6Params:
	v_and_b32_e32 v1, 0x3ff, v0
	s_mov_b32 s62, s2
	v_readfirstlane_b32 s63, v1
	s_and_b32 s60, s63, 0xffffffc0
	s_add_u32 s2, s0, 0x118
	s_load_dwordx2 s[78:79], s[0:1], 0x110
	s_load_dword s10, s[0:1], 0x118
	s_addc_u32 s3, s1, 0
	s_cmpk_lt_i32 s62, 0x580
	s_cselect_b64 s[4:5], -1, 0
	s_cmpk_gt_i32 s62, 0x57f
	v_writelane_b32 v251, s4, 0
	s_nop 1
	v_writelane_b32 v251, s5, 1
	s_waitcnt lgkmcnt(0)
	s_mov_b64 s[4:5], s[78:79]
	v_mbcnt_lo_u32_b32 v20, -1, 0
	v_mbcnt_hi_u32_b32 v20, -1, v20
	s_barrier
	s_cbranch_scc1 .LBB0_5
	s_load_dwordx2 s[6:7], s[0:1], 0x18
	s_ashr_i32 s8, s62, 31
	s_lshr_b32 s8, s8, 28
	s_add_i32 s11, s62, s8
	s_lshl_b32 s8, s11, 2
	s_and_b32 s11, s11, 0x1fffff0
	v_or_b32_e32 v21, s60, v20
	s_andn2_b32 s8, s8, 63
	s_sub_i32 s11, s62, s11
	v_ashrrev_i32_e32 v24, 3, v21
	v_lshlrev_b32_e32 v2, 3, v20
	s_ashr_i32 s9, s8, 31
	v_and_b32_e32 v28, 56, v2
	v_lshl_add_u32 v12, s11, 7, v24
	s_movk_i32 s11, 0x5800
	s_waitcnt lgkmcnt(0)
	v_mov_b64_e32 v[2:3], s[6:7]
	v_mad_i64_i32 v[2:3], s[12:13], v12, s11, v[2:3]
	s_lshl_b64 s[8:9], s[8:9], 2
	v_lshl_add_u64 v[2:3], v[2:3], 0, s[8:9]
	v_mov_b32_e32 v19, 0
	v_lshlrev_b32_e32 v18, 2, v28
	v_lshl_add_u64 v[10:11], v[2:3], 0, v[18:19]
	global_load_dwordx4 v[2:5], v[10:11], off nt
	global_load_dwordx4 v[6:9], v[10:11], off offset:16 nt
	v_add_u32_e32 v12, 64, v12
	v_mov_b64_e32 v[10:11], s[6:7]
	v_mad_i64_i32 v[10:11], s[12:13], v12, s11, v[10:11]
	v_lshl_add_u64 v[10:11], v[10:11], 0, s[8:9]
	v_lshl_add_u64 v[22:23], v[10:11], 0, v[18:19]
	global_load_dwordx4 v[10:13], v[22:23], off nt
	global_load_dwordx4 v[14:17], v[22:23], off offset:16 nt
	v_and_b32_e32 v22, 63, v20
	v_lshlrev_b32_e32 v23, 4, v20
	v_bfe_u32 v20, v20, 1, 4
	v_ashrrev_i32_e32 v25, 2, v21
	s_movk_i32 s8, 0x104
	v_add_u32_e32 v18, 0, v18
	v_and_or_b32 v23, v23, 16, v20
	v_and_b32_e32 v20, -16, v25
	v_mul_lo_u32 v26, v24, s8
	v_or_b32_e32 v25, 15, v25
	v_lshl_add_u32 v29, v22, 2, 0
	v_mul_lo_u32 v27, v20, s8
	v_mul_lo_u32 v30, v25, s8
	s_lshl_b32 s13, s10, 7
	v_add_u32_e32 v25, v18, v26
	v_ashrrev_i32_e32 v21, 31, v20
	s_lshl_b32 s12, s62, 7
	v_add_u32_e32 v24, s13, v24
	v_add_u32_e32 v26, 0x4100, v25
	v_lshlrev_b32_e32 v18, 2, v28
	v_add_u32_e32 v27, v29, v27
	v_add_u32_e32 v28, v29, v30
	s_movk_i32 s14, 0x7fff
	v_add_u32_e32 v29, 0x4108, v25
	v_add_u32_e32 v30, 0x4110, v25
	v_mov_b32_e32 v31, 0x60
	v_mov_b32_e32 v32, 1
	s_mov_b32 s16, s62
	s_waitcnt vmcnt(0)
	s_branch .LBB0_3

; #define tidx() tidx_(wv_)
; __device__ __forceinline__ void conv_run(const float* __restrict__ src, u16* __restrict__ dst, int K, int N, int mode, int& base,
;                                          float* lds, int gi, int ng, int wv_) {
;   const int nk = K / 128, nn = N / 64, ntiles = nk * nn;
;   const int t = tidx();
;   int lt = (base & 1) ? (ng - 1 - gi) : gi;
;   base += 1;
;   float4 ra[2], rb[2];
;   auto gl = [&](int tile) {
;     const int k0 = (tile % nk) * 128, n0 = (tile / nk) * 64;
; #pragma unroll
;     for (int i = 0; i < 2; ++i) {
;       const int kl = (t >> 3) + 64 * i, c8 = (t & 7) * 8;
;       typedef float f4v __attribute__((ext_vector_type(4)));
;       const f4v* sp = (const f4v*)(src + (size_t)(k0 + kl) * N + n0 + c8);
;       const f4v va = __builtin_nontemporal_load(sp), vb = __builtin_nontemporal_load(sp + 1);
;       ra[i] = make_float4(va.x, va.y, va.z, va.w); rb[i] = make_float4(vb.x, vb.y, vb.z, vb.w);
;     }
;   };
;   __syncthreads();
;   if (lt < ntiles) gl(lt);
;   while (lt < ntiles) {
;     const int nxt = lt + ng;
;     const int k0 = (lt % nk) * 128, n0 = (lt / nk) * 64;
;     asm volatile("s_waitcnt lgkmcnt(0)\n\ts_barrier" ::: "memory");
; #pragma unroll
;     for (int i = 0; i < 2; ++i) {
;       const int kl = (t >> 3) + 64 * i, c8 = (t & 7) * 8;
;       float* d = lds + kl * 65 + c8;
;       d[0] = ra[i].x; d[1] = ra[i].y; d[2] = ra[i].z; d[3] = ra[i].w; d[4] = rb[i].x; d[5] = rb[i].y; d[6] = rb[i].z; d[7] = rb[i].w;
;     }
;     if (nxt < ntiles) gl(nxt);
;     asm volatile("s_waitcnt lgkmcnt(0)\n\ts_barrier" ::: "memory");
;     const int nl = t & 63, kc = t >> 6;
;     const int n = n0 + nl;
;     const int row = (mode == 0) ? ((n & ~255) + perm256(n & 255)) : ((n >> 7) * 256 + perm128(n & 127) + (mode == 2 ? 128 : 0));
;     float f[16];
; #pragma unroll
;     for (int i = 0; i < 16; ++i) f[i] = lds[(kc * 16 + i) * 65 + nl];
;     uint4* dp = (uint4*)(dst + (size_t)row * K + k0 + kc * 16);
;     dp[0] = pack8(f);
;     dp[1] = pack8(f + 8);
;     lt = nxt;
;   }
.LBB0_3:
	s_add_i32 s15, s16, s10
	s_waitcnt lgkmcnt(0)
	s_barrier
	s_cmpk_gt_i32 s15, 0x57f
	s_cselect_b64 s[8:9], -1, 0
	v_add_u32_e32 v33, 0x4118, v25
	s_and_b64 vcc, exec, s[8:9]
	s_waitcnt vmcnt(5)
	ds_write2_b32 v25, v2, v3 offset1:1
	ds_write2_b32 v25, v4, v5 offset0:2 offset1:3
	s_waitcnt vmcnt(4)
	ds_write2_b32 v25, v6, v7 offset0:4 offset1:5
	ds_write2_b32 v25, v8, v9 offset0:6 offset1:7
	s_waitcnt vmcnt(3)
	ds_write2_b32 v26, v10, v11 offset1:1
	ds_write2_b32 v29, v12, v13 offset1:1
	s_waitcnt vmcnt(2)
	ds_write2_b32 v30, v14, v15 offset1:1
	ds_write2_b32 v33, v16, v17 offset1:1
	s_cbranch_vccnz .LBB0_2
	s_ashr_i32 s17, s15, 31
	s_lshr_b32 s17, s17, 28
	s_add_i32 s17, s15, s17
	s_ashr_i32 s17, s17, 4
	s_lshl_b32 s18, s17, 6
	v_add_u32_e32 v2, s12, v24
	s_lshl_b32 s17, s17, 11
	s_ashr_i32 s19, s18, 31
	v_subrev_u32_e32 v14, s17, v2
	v_mov_b64_e32 v[10:11], s[6:7]
	v_mad_i64_i32 v[2:3], s[20:21], v14, s11, v[10:11]
	s_lshl_b64 s[18:19], s[18:19], 2
	v_lshl_add_u64 v[2:3], v[2:3], 0, s[18:19]
	v_lshl_add_u64 v[12:13], v[2:3], 0, v[18:19]
	global_load_dwordx4 v[2:5], v[12:13], off nt
	global_load_dwordx4 v[6:9], v[12:13], off offset:16 nt
	v_add_u32_e32 v12, 64, v14
	v_mad_i64_i32 v[10:11], s[20:21], v12, s11, v[10:11]
	v_lshl_add_u64 v[10:11], v[10:11], 0, s[18:19]
	v_lshl_add_u64 v[34:35], v[10:11], 0, v[18:19]
	global_load_dwordx4 v[10:13], v[34:35], off nt
	global_load_dwordx4 v[14:17], v[34:35], off offset:16 nt
	s_branch .LBB0_2
.LBB0_5:
	s_not_b32 s28, s62
	s_add_i32 s16, s10, s28
	s_cmpk_gt_i32 s16, 0x57f
	v_mbcnt_lo_u32_b32 v20, -1, 0
	v_mbcnt_hi_u32_b32 v20, -1, v20
	s_barrier
	s_cbranch_scc1 .LBB0_10
	s_load_dwordx2 s[6:7], s[0:1], 0x20
	s_ashr_i32 s8, s16, 31
	s_lshr_b32 s8, s8, 28
	s_add_i32 s8, s16, s8
	s_and_b32 s9, s8, 0x1fffff0
	s_lshl_b32 s8, s8, 2
	v_or_b32_e32 v21, s60, v20
	s_sub_i32 s11, s16, s9
	s_andn2_b32 s8, s8, 63
	v_ashrrev_i32_e32 v24, 3, v21
	s_waitcnt vmcnt(5)
	v_lshlrev_b32_e32 v2, 3, v20
	s_ashr_i32 s9, s8, 31
	v_and_b32_e32 v30, 56, v2
	s_waitcnt vmcnt(3)
	v_lshl_add_u32 v12, s11, 7, v24
	s_movk_i32 s11, 0x5800
	s_waitcnt lgkmcnt(0)
	v_mov_b64_e32 v[2:3], s[6:7]
	v_mad_i64_i32 v[2:3], s[12:13], v12, s11, v[2:3]
	s_lshl_b64 s[8:9], s[8:9], 2
	v_lshl_add_u64 v[2:3], v[2:3], 0, s[8:9]
	v_mov_b32_e32 v19, 0
	v_lshlrev_b32_e32 v18, 2, v30
	v_lshl_add_u64 v[10:11], v[2:3], 0, v[18:19]
	global_load_dwordx4 v[2:5], v[10:11], off nt
	global_load_dwordx4 v[6:9], v[10:11], off offset:16 nt
	v_add_u32_e32 v12, 64, v12
	v_mov_b64_e32 v[10:11], s[6:7]
	v_mad_i64_i32 v[10:11], s[12:13], v12, s11, v[10:11]
	v_lshl_add_u64 v[10:11], v[10:11], 0, s[8:9]
	v_lshl_add_u64 v[22:23], v[10:11], 0, v[18:19]
	global_load_dwordx4 v[10:13], v[22:23], off nt
	global_load_dwordx4 v[14:17], v[22:23], off offset:16 nt
	v_and_b32_e32 v22, 63, v20
	v_lshrrev_b32_e32 v23, 1, v20
	v_lshlrev_b32_e32 v20, 4, v20
	v_and_b32_e32 v20, 16, v20
	v_ashrrev_i32_e32 v25, 2, v21
	s_movk_i32 s8, 0x104
	v_add_u32_e32 v18, 0, v18
	v_and_or_b32 v23, v23, 15, v20
	v_and_b32_e32 v20, -16, v25
	v_mul_lo_u32 v26, v24, s8
	v_or_b32_e32 v25, 15, v25
	v_lshl_add_u32 v31, v22, 2, 0
	v_mul_lo_u32 v29, v20, s8
	v_mul_lo_u32 v32, v25, s8
	s_lshl_b32 s13, s10, 7
	v_add_u32_e32 v25, v18, v26
	v_ashrrev_i32_e32 v21, 31, v20
	s_lshl_b32 s12, s16, 7
	v_add_u32_e32 v24, s13, v24
	v_add_u32_e32 v26, 0x4100, v25
	v_add_u32_e32 v27, 0x4108, v25
	v_add_u32_e32 v28, 0x4110, v25
	v_lshlrev_b32_e32 v18, 2, v30
	s_movk_i32 s14, 0x80
	v_add_u32_e32 v29, v31, v29
	v_add_u32_e32 v30, v31, v32
	s_movk_i32 s15, 0x7fff
	v_add_u32_e32 v31, 0x4118, v25
	v_mov_b32_e32 v32, 0x60
	v_mov_b32_e32 v33, 1
	s_waitcnt vmcnt(0)
	s_branch .LBB0_8

; #define tidx() tidx_(wv_)
; __device__ __forceinline__ void conv_run(const float* __restrict__ src, u16* __restrict__ dst, int K, int N, int mode, int& base,
;                                          float* lds, int gi, int ng, int wv_) {
;   const int nk = K / 128, nn = N / 64, ntiles = nk * nn;
;   const int t = tidx();
;   int lt = (base & 1) ? (ng - 1 - gi) : gi;
;   base += 1;
;   float4 ra[2], rb[2];
;   auto gl = [&](int tile) {
;     const int k0 = (tile % nk) * 128, n0 = (tile / nk) * 64;
; #pragma unroll
;     for (int i = 0; i < 2; ++i) {
;       const int kl = (t >> 3) + 64 * i, c8 = (t & 7) * 8;
;       typedef float f4v __attribute__((ext_vector_type(4)));
;       const f4v* sp = (const f4v*)(src + (size_t)(k0 + kl) * N + n0 + c8);
;       const f4v va = __builtin_nontemporal_load(sp), vb = __builtin_nontemporal_load(sp + 1);
;       ra[i] = make_float4(va.x, va.y, va.z, va.w); rb[i] = make_float4(vb.x, vb.y, vb.z, vb.w);
;     }
;   };
;   __syncthreads();
;   if (lt < ntiles) gl(lt);
;   while (lt < ntiles) {
;     const int nxt = lt + ng;
;     const int k0 = (lt % nk) * 128, n0 = (lt / nk) * 64;
;     asm volatile("s_waitcnt lgkmcnt(0)\n\ts_barrier" ::: "memory");
; #pragma unroll
;     for (int i = 0; i < 2; ++i) {
;       const int kl = (t >> 3) + 64 * i, c8 = (t & 7) * 8;
;       float* d = lds + kl * 65 + c8;
;       d[0] = ra[i].x; d[1] = ra[i].y; d[2] = ra[i].z; d[3] = ra[i].w; d[4] = rb[i].x; d[5] = rb[i].y; d[6] = rb[i].z; d[7] = rb[i].w;
;     }
;     if (nxt < ntiles) gl(nxt);
;     asm volatile("s_waitcnt lgkmcnt(0)\n\ts_barrier" ::: "memory");
;     const int nl = t & 63, kc = t >> 6;
;     const int n = n0 + nl;
;     const int row = (mode == 0) ? ((n & ~255) + perm256(n & 255)) : ((n >> 7) * 256 + perm128(n & 127) + (mode == 2 ? 128 : 0));
;     float f[16];
; #pragma unroll
;     for (int i = 0; i < 16; ++i) f[i] = lds[(kc * 16 + i) * 65 + nl];
;     uint4* dp = (uint4*)(dst + (size_t)row * K + k0 + kc * 16);
;     dp[0] = pack8(f);
;     dp[1] = pack8(f + 8);
;     lt = nxt;
;   }
.LBB0_8:
	s_add_i32 s17, s16, s10
	s_waitcnt lgkmcnt(0)
	s_barrier
	s_cmpk_gt_i32 s17, 0x57f
	s_cselect_b64 s[8:9], -1, 0
	s_and_b64 vcc, exec, s[8:9]
	s_waitcnt vmcnt(5)
	ds_write2_b32 v25, v2, v3 offset1:1
	ds_write2_b32 v25, v4, v5 offset0:2 offset1:3
	s_waitcnt vmcnt(4)
	ds_write2_b32 v25, v6, v7 offset0:4 offset1:5
	ds_write2_b32 v25, v8, v9 offset0:6 offset1:7
	s_waitcnt vmcnt(3)
	ds_write2_b32 v26, v10, v11 offset1:1
	ds_write2_b32 v27, v12, v13 offset1:1
	s_waitcnt vmcnt(2)
	ds_write2_b32 v28, v14, v15 offset1:1
	ds_write2_b32 v31, v16, v17 offset1:1
	s_cbranch_vccnz .LBB0_7
	s_ashr_i32 s18, s17, 31
	s_lshr_b32 s18, s18, 28
	s_add_i32 s18, s17, s18
	s_ashr_i32 s20, s18, 4
	s_lshl_b32 s18, s20, 6
	v_add_u32_e32 v2, s12, v24
	s_lshl_b32 s20, s20, 11
	s_ashr_i32 s19, s18, 31
	v_subrev_u32_e32 v14, s20, v2
	v_mov_b64_e32 v[10:11], s[6:7]
	v_mad_i64_i32 v[2:3], s[20:21], v14, s11, v[10:11]
	s_lshl_b64 s[18:19], s[18:19], 2
	v_lshl_add_u64 v[2:3], v[2:3], 0, s[18:19]
	v_lshl_add_u64 v[12:13], v[2:3], 0, v[18:19]
	global_load_dwordx4 v[2:5], v[12:13], off nt
	global_load_dwordx4 v[6:9], v[12:13], off offset:16 nt
	v_add_u32_e32 v12, 64, v14
	v_mad_i64_i32 v[10:11], s[20:21], v12, s11, v[10:11]
	v_lshl_add_u64 v[10:11], v[10:11], 0, s[18:19]
	v_lshl_add_u64 v[34:35], v[10:11], 0, v[18:19]
	global_load_dwordx4 v[10:13], v[34:35], off nt
	global_load_dwordx4 v[14:17], v[34:35], off offset:16 nt
	s_branch .LBB0_7
.LBB0_10:
	s_cmp_lt_i32 s62, 64
	s_cselect_b64 s[6:7], -1, 0
	v_writelane_b32 v251, s6, 2
	v_mbcnt_lo_u32_b32 v22, -1, 0
	v_mbcnt_hi_u32_b32 v22, -1, v22
	s_barrier
	s_nop 0
	v_writelane_b32 v251, s7, 3
	s_lshr_b32 s6, s62, 31
	s_add_i32 s6, s62, s6
	s_and_b32 s7, s6, 0x1fffffe
	s_sub_i32 s7, s62, s7
	s_lshl_b32 s6, s6, 5
	s_lshl_b32 s7, s7, 7
	s_andn2_b32 s6, s6, 63
	v_writelane_b32 v251, s7, 4
	s_ashr_i32 s7, s6, 31
	v_writelane_b32 v251, s6, 5
	s_cmp_gt_i32 s62, 63
	s_nop 0
	v_writelane_b32 v251, s7, 6
	s_cbranch_scc1 .LBB0_15
	v_or_b32_e32 v23, s60, v22
	v_ashrrev_i32_e32 v24, 3, v23
	v_readlane_b32 s8, v251, 4
	s_load_dwordx2 s[6:7], s[0:1], 0x68
	s_waitcnt vmcnt(5)
	v_lshlrev_b32_e32 v2, 3, v22
	s_waitcnt vmcnt(3)
	v_add_u32_e32 v10, s8, v24
	v_ashrrev_i32_e32 v11, 31, v10
	v_and_b32_e32 v26, 56, v2
	v_lshlrev_b64 v[2:3], 13, v[10:11]
	v_add_u32_e32 v10, 64, v10
	v_readlane_b32 s8, v251, 5
	v_ashrrev_i32_e32 v11, 31, v10
	s_add_u32 s4, s4, 0x8c00000
	v_readlane_b32 s9, v251, 6
	v_lshlrev_b64 v[10:11], 13, v[10:11]
	s_addc_u32 s5, s5, 0
	s_waitcnt lgkmcnt(0)
	v_lshl_add_u64 v[2:3], s[6:7], 0, v[2:3]
	s_lshl_b64 s[8:9], s[8:9], 2
	v_lshl_add_u64 v[10:11], s[6:7], 0, v[10:11]
	v_lshl_add_u64 v[2:3], v[2:3], 0, s[8:9]
	v_mov_b32_e32 v19, 0
	v_lshlrev_b32_e32 v18, 2, v26
	v_lshl_add_u64 v[10:11], v[10:11], 0, s[8:9]
	v_lshl_add_u64 v[12:13], v[2:3], 0, v[18:19]
	v_lshl_add_u64 v[20:21], v[10:11], 0, v[18:19]
	global_load_dwordx4 v[2:5], v[12:13], off nt
	global_load_dwordx4 v[6:9], v[12:13], off offset:16 nt
	s_nop 0
	global_load_dwordx4 v[10:13], v[20:21], off nt
	global_load_dwordx4 v[14:17], v[20:21], off offset:16 nt
	v_ashrrev_i32_e32 v23, 2, v23
	v_and_b32_e32 v20, -16, v23
	s_movk_i32 s8, 0x104
	v_or_b32_e32 v23, 15, v23
	v_and_b32_e32 v21, 63, v22
	v_bfe_u32 v25, v22, 2, 4
	v_mul_lo_u32 v30, v23, s8
	v_lshlrev_b32_e32 v23, 6, v22
	v_lshlrev_b32_e32 v22, 4, v22
	v_add_u32_e32 v18, 0, v18
	v_mul_lo_u32 v29, v24, s8
	v_and_b32_e32 v23, 0x80, v23
	v_and_b32_e32 v22, 16, v22
	s_lshl_b32 s12, s10, 7
	v_lshl_add_u32 v27, v21, 2, 0
	v_mul_lo_u32 v28, v20, s8
	v_or3_b32 v22, v23, v25, v22
	v_add_u32_e32 v23, s12, v24
	v_add_u32_e32 v24, v18, v29
	v_ashrrev_i32_e32 v21, 31, v20
	s_lshl_b32 s11, s62, 7
	v_add_u32_e32 v25, 0x4100, v24
	v_lshlrev_b32_e32 v18, 2, v26
	v_add_u32_e32 v26, v27, v28
	v_add_u32_e32 v27, v27, v30
	s_movk_i32 s13, 0x7fff
	v_add_u32_e32 v28, 0x4108, v24
	v_add_u32_e32 v29, 0x4110, v24
	v_mov_b32_e32 v30, 1
	s_mov_b32 s15, s62
	s_waitcnt vmcnt(0)
	s_branch .LBB0_13

; __device__ __forceinline__ void conv_run(const float* __restrict__ src, u16* __restrict__ dst, int K, int N, int mode, int& base,
;                                          float* lds, int gi, int ng, int wv_) {
;     ...
;   while (lt < ntiles) {
;     const int nxt = lt + ng;
;     const int k0 = (lt % nk) * 128, n0 = (lt / nk) * 64;
;     asm volatile("s_waitcnt lgkmcnt(0)\n\ts_barrier" ::: "memory");
; #pragma unroll
;     for (int i = 0; i < 2; ++i) {
;       const int kl = (t >> 3) + 64 * i, c8 = (t & 7) * 8;
;       float* d = lds + kl * 65 + c8;
;       d[0] = ra[i].x; d[1] = ra[i].y; d[2] = ra[i].z; d[3] = ra[i].w; d[4] = rb[i].x; d[5] = rb[i].y; d[6] = rb[i].z; d[7] = rb[i].w;
;     }
;     if (nxt < ntiles) gl(nxt);
;     asm volatile("s_waitcnt lgkmcnt(0)\n\ts_barrier" ::: "memory");
;     const int nl = t & 63, kc = t >> 6;
;     const int n = n0 + nl;
;     const int row = (mode == 0) ? ((n & ~255) + perm256(n & 255)) : ((n >> 7) * 256 + perm128(n & 127) + (mode == 2 ? 128 : 0));
;     float f[16];
; #pragma unroll
;     for (int i = 0; i < 16; ++i) f[i] = lds[(kc * 16 + i) * 65 + nl];
;     uint4* dp = (uint4*)(dst + (size_t)row * K + k0 + kc * 16);
;     dp[0] = pack8(f);
;     dp[1] = pack8(f + 8);
;     lt = nxt;
;   }
.LBB0_13:
	s_add_i32 s14, s15, s10
	s_waitcnt lgkmcnt(0)
	s_barrier
	s_cmp_gt_i32 s14, 63
	s_cselect_b64 s[8:9], -1, 0
	v_add_u32_e32 v31, 0x4118, v24
	s_and_b64 vcc, exec, s[8:9]
	s_waitcnt vmcnt(5)
	ds_write2_b32 v24, v2, v3 offset1:1
	ds_write2_b32 v24, v4, v5 offset0:2 offset1:3
	s_waitcnt vmcnt(4)
	ds_write2_b32 v24, v6, v7 offset0:4 offset1:5
	ds_write2_b32 v24, v8, v9 offset0:6 offset1:7
	s_waitcnt vmcnt(3)
	ds_write2_b32 v25, v10, v11 offset1:1
	ds_write2_b32 v28, v12, v13 offset1:1
	s_waitcnt vmcnt(2)
	ds_write2_b32 v29, v14, v15 offset1:1
	ds_write2_b32 v31, v16, v17 offset1:1
	s_cbranch_vccnz .LBB0_12
	s_lshr_b32 s16, s14, 31
	s_add_i32 s16, s14, s16
	s_ashr_i32 s18, s16, 1
	s_lshl_b32 s16, s18, 6
	v_add_u32_e32 v2, s11, v23
	s_lshl_b32 s18, s18, 8
	v_subrev_u32_e32 v10, s18, v2
	v_ashrrev_i32_e32 v11, 31, v10
	v_lshlrev_b64 v[2:3], 13, v[10:11]
	v_add_u32_e32 v10, 64, v10
	v_ashrrev_i32_e32 v11, 31, v10
	s_ashr_i32 s17, s16, 31
	v_lshlrev_b64 v[10:11], 13, v[10:11]
	v_lshl_add_u64 v[2:3], s[6:7], 0, v[2:3]
	s_lshl_b64 s[16:17], s[16:17], 2
	v_lshl_add_u64 v[10:11], s[6:7], 0, v[10:11]
	v_lshl_add_u64 v[2:3], v[2:3], 0, s[16:17]
	v_lshl_add_u64 v[10:11], v[10:11], 0, s[16:17]
	v_lshl_add_u64 v[12:13], v[2:3], 0, v[18:19]
	v_lshl_add_u64 v[32:33], v[10:11], 0, v[18:19]
	global_load_dwordx4 v[2:5], v[12:13], off nt
	global_load_dwordx4 v[6:9], v[12:13], off offset:16 nt
	s_nop 0
	global_load_dwordx4 v[10:13], v[32:33], off nt
	global_load_dwordx4 v[14:17], v[32:33], off offset:16 nt
	s_branch .LBB0_12

; #define tidx() tidx_(wv_)
; __device__ __forceinline__ void conv_run(const float* __restrict__ src, u16* __restrict__ dst, int K, int N, int mode, int& base,
;                                          float* lds, int gi, int ng, int wv_) {
;   const int nk = K / 128, nn = N / 64, ntiles = nk * nn;
;   const int t = tidx();
;   int lt = (base & 1) ? (ng - 1 - gi) : gi;
;   base += 1;
;   float4 ra[2], rb[2];
;   auto gl = [&](int tile) {
;     const int k0 = (tile % nk) * 128, n0 = (tile / nk) * 64;
; #pragma unroll
;     for (int i = 0; i < 2; ++i) {
;       const int kl = (t >> 3) + 64 * i, c8 = (t & 7) * 8;
;       typedef float f4v __attribute__((ext_vector_type(4)));
;       const f4v* sp = (const f4v*)(src + (size_t)(k0 + kl) * N + n0 + c8);
;       const f4v va = __builtin_nontemporal_load(sp), vb = __builtin_nontemporal_load(sp + 1);
;       ra[i] = make_float4(va.x, va.y, va.z, va.w); rb[i] = make_float4(vb.x, vb.y, vb.z, vb.w);
;     }
;   };
;   __syncthreads();
;   if (lt < ntiles) gl(lt);
.LBB0_321:
	v_readlane_b32 s6, v251, 39
	s_waitcnt lgkmcnt(0)
	s_mov_b64 s[2:3], s[78:79]
	v_readlane_b32 s7, v251, 40
	s_waitcnt lgkmcnt(0)
	s_barrier
	s_add_u32 s8, s2, 0x2c00000
	s_waitcnt vmcnt(0)
	v_cndmask_b32_e64 v0, 0, 1, s[6:7]
	s_addc_u32 s9, s3, 0
	v_cmp_ne_u32_e64 s[4:5], 1, v0
	s_andn2_b64 vcc, exec, s[6:7]
	v_mbcnt_lo_u32_b32 v16, -1, 0
	v_mbcnt_hi_u32_b32 v16, -1, v16
	s_barrier
	s_cbranch_vccnz .LBB0_326
	s_load_dwordx2 s[6:7], s[0:1], 0x40
	v_or_b32_e32 v17, s60, v16
	v_ashrrev_i32_e32 v20, 3, v17
	v_lshlrev_b32_e32 v0, 3, v16
	v_readlane_b32 s10, v251, 41
	v_and_b32_e32 v22, 56, v0
	s_waitcnt lgkmcnt(0)
	v_mov_b64_e32 v[0:1], s[6:7]
	v_add_u32_e32 v8, s10, v20
	s_movk_i32 s14, 0x5800
	v_mad_i64_i32 v[0:1], s[10:11], v8, s14, v[0:1]
	v_readlane_b32 s10, v251, 42
	v_readlane_b32 s11, v251, 43
	v_add_u32_e32 v10, 64, v8
	v_mov_b64_e32 v[8:9], s[6:7]
	s_lshl_b64 s[10:11], s[10:11], 2
	v_mad_i64_i32 v[8:9], s[14:15], v10, s14, v[8:9]
	v_lshl_add_u64 v[0:1], v[0:1], 0, s[10:11]
	v_lshlrev_b32_e32 v166, 2, v22
	v_lshl_add_u64 v[8:9], v[8:9], 0, s[10:11]
	v_lshl_add_u64 v[4:5], v[0:1], 0, v[166:167]
	v_lshl_add_u64 v[12:13], v[8:9], 0, v[166:167]
	global_load_dwordx4 v[0:3], v[4:5], off nt
	s_nop 0
	global_load_dwordx4 v[4:7], v[4:5], off offset:16 nt
	s_nop 0
	global_load_dwordx4 v[8:11], v[12:13], off nt
	s_nop 0
	global_load_dwordx4 v[12:15], v[12:13], off offset:16 nt
	v_and_b32_e32 v18, 63, v16
	v_lshlrev_b32_e32 v19, 4, v16
	v_bfe_u32 v16, v16, 1, 4
	v_ashrrev_i32_e32 v23, 2, v17
	v_and_or_b32 v19, v19, 16, v16
	v_and_b32_e32 v16, -16, v23
	s_movk_i32 s10, 0x104
	v_or_b32_e32 v23, 15, v23
	v_readlane_b32 s11, v251, 38
	v_add_u32_e32 v21, 0, v166
	v_lshl_add_u32 v24, v18, 2, 0
	v_mul_lo_u32 v25, v16, s10
	v_mul_lo_u32 v26, v20, s10
	v_mul_lo_u32 v23, v23, s10
	v_readlane_b32 s17, v251, 55
	s_lshl_b32 s11, s11, 7
	v_ashrrev_i32_e32 v17, 31, v16
	s_lshl_b32 s10, s17, 7
	v_add_u32_e32 v20, s11, v20
	v_add_u32_e32 v21, v21, v26
	v_lshlrev_b32_e32 v166, 2, v22
	v_add_u32_e32 v22, v24, v25
	v_add_u32_e32 v23, v24, v23
	s_waitcnt vmcnt(0)
	s_branch .LBB0_324

; #define tidx() tidx_(wv_)
; __device__ __forceinline__ void conv_run(const float* __restrict__ src, u16* __restrict__ dst, int K, int N, int mode, int& base,
;                                          float* lds, int gi, int ng, int wv_) {
;   const int nk = K / 128, nn = N / 64, ntiles = nk * nn;
;   const int t = tidx();
;   int lt = (base & 1) ? (ng - 1 - gi) : gi;
;   base += 1;
;   float4 ra[2], rb[2];
;   auto gl = [&](int tile) {
;     const int k0 = (tile % nk) * 128, n0 = (tile / nk) * 64;
; #pragma unroll
;     for (int i = 0; i < 2; ++i) {
;       const int kl = (t >> 3) + 64 * i, c8 = (t & 7) * 8;
;       typedef float f4v __attribute__((ext_vector_type(4)));
;       const f4v* sp = (const f4v*)(src + (size_t)(k0 + kl) * N + n0 + c8);
;       const f4v va = __builtin_nontemporal_load(sp), vb = __builtin_nontemporal_load(sp + 1);
;       ra[i] = make_float4(va.x, va.y, va.z, va.w); rb[i] = make_float4(vb.x, vb.y, vb.z, vb.w);
;     }
;   };
;   __syncthreads();
;   if (lt < ntiles) gl(lt);
;   while (lt < ntiles) {
;     const int nxt = lt + ng;
;     const int k0 = (lt % nk) * 128, n0 = (lt / nk) * 64;
;     asm volatile("s_waitcnt lgkmcnt(0)\n\ts_barrier" ::: "memory");
; #pragma unroll
;     for (int i = 0; i < 2; ++i) {
;       const int kl = (t >> 3) + 64 * i, c8 = (t & 7) * 8;
;       float* d = lds + kl * 65 + c8;
;       d[0] = ra[i].x; d[1] = ra[i].y; d[2] = ra[i].z; d[3] = ra[i].w; d[4] = rb[i].x; d[5] = rb[i].y; d[6] = rb[i].z; d[7] = rb[i].w;
;     }
;     if (nxt < ntiles) gl(nxt);
;     asm volatile("s_waitcnt lgkmcnt(0)\n\ts_barrier" ::: "memory");
;     const int nl = t & 63, kc = t >> 6;
;     const int n = n0 + nl;
;     const int row = (mode == 0) ? ((n & ~255) + perm256(n & 255)) : ((n >> 7) * 256 + perm128(n & 127) + (mode == 2 ? 128 : 0));
;     float f[16];
; #pragma unroll
;     for (int i = 0; i < 16; ++i) f[i] = lds[(kc * 16 + i) * 65 + nl];
;     uint4* dp = (uint4*)(dst + (size_t)row * K + k0 + kc * 16);
;     dp[0] = pack8(f);
;     dp[1] = pack8(f + 8);
;     lt = nxt;
;   }
.LBB0_324:
	v_readlane_b32 s14, v251, 38
	v_add_u32_e32 v24, 0x4100, v21
	s_add_i32 s16, s17, s14
	s_waitcnt lgkmcnt(0)
	s_barrier
	s_waitcnt vmcnt(5)
	ds_write2_b32 v21, v0, v1 offset1:1
	ds_write2_b32 v21, v2, v3 offset0:2 offset1:3
	s_waitcnt vmcnt(4)
	ds_write2_b32 v21, v4, v5 offset0:4 offset1:5
	ds_write2_b32 v21, v6, v7 offset0:6 offset1:7
	s_waitcnt vmcnt(3)
	ds_write2_b32 v24, v8, v9 offset1:1
	v_add_u32_e32 v24, 0x4108, v21
	s_cmpk_gt_i32 s16, 0x57f
	ds_write2_b32 v24, v10, v11 offset1:1
	v_add_u32_e32 v24, 0x4110, v21
	s_cselect_b64 s[14:15], -1, 0
	s_waitcnt vmcnt(2)
	ds_write2_b32 v24, v12, v13 offset1:1
	v_add_u32_e32 v24, 0x4118, v21
	s_and_b64 vcc, exec, s[14:15]
	ds_write2_b32 v24, v14, v15 offset1:1
	s_cbranch_vccnz .LBB0_323
	s_ashr_i32 s18, s16, 31
	s_lshr_b32 s18, s18, 28
	s_add_i32 s18, s16, s18
	s_ashr_i32 s28, s18, 4
	s_lshl_b32 s18, s28, 6
	v_add_u32_e32 v0, s10, v20
	s_lshl_b32 s28, s28, 11
	v_subrev_u32_e32 v10, s28, v0
	v_mov_b64_e32 v[8:9], s[6:7]
	s_movk_i32 s30, 0x5800
	s_ashr_i32 s19, s18, 31
	v_mad_i64_i32 v[0:1], s[28:29], v10, s30, v[8:9]
	v_add_u32_e32 v10, 64, v10
	s_lshl_b64 s[18:19], s[18:19], 2
	v_mad_i64_i32 v[8:9], s[28:29], v10, s30, v[8:9]
	v_lshl_add_u64 v[0:1], v[0:1], 0, s[18:19]
	v_lshl_add_u64 v[8:9], v[8:9], 0, s[18:19]
	v_lshl_add_u64 v[4:5], v[0:1], 0, v[166:167]
	v_lshl_add_u64 v[12:13], v[8:9], 0, v[166:167]
	global_load_dwordx4 v[0:3], v[4:5], off nt
	s_nop 0
	global_load_dwordx4 v[4:7], v[4:5], off offset:16 nt
	s_nop 0
	global_load_dwordx4 v[8:11], v[12:13], off nt
	s_nop 0
	global_load_dwordx4 v[12:15], v[12:13], off offset:16 nt
	s_branch .LBB0_323
.LBB0_326:
	v_readlane_b32 s10, v251, 44
	v_readlane_b32 s11, v251, 45
	s_andn2_b64 vcc, exec, s[10:11]
	v_mbcnt_lo_u32_b32 v16, -1, 0
	v_mbcnt_hi_u32_b32 v16, -1, v16
	s_waitcnt vmcnt(5)
	v_cndmask_b32_e64 v0, 0, 1, s[10:11]
	v_cmp_ne_u32_e64 s[6:7], 1, v0
	s_barrier
	s_cbranch_vccnz .LBB0_331
	s_load_dwordx2 s[14:15], s[0:1], 0x48
	v_or_b32_e32 v17, s60, v16
	v_ashrrev_i32_e32 v20, 3, v17
	v_lshlrev_b32_e32 v0, 3, v16
	v_readlane_b32 s10, v251, 46
	v_and_b32_e32 v22, 56, v0
	s_waitcnt lgkmcnt(0)
	v_mov_b64_e32 v[0:1], s[14:15]
	s_waitcnt vmcnt(3)
	v_add_u32_e32 v8, s10, v20
	s_movk_i32 s16, 0x5800
	v_mad_i64_i32 v[0:1], s[10:11], v8, s16, v[0:1]
	v_readlane_b32 s10, v251, 47
	v_readlane_b32 s11, v251, 48
	v_add_u32_e32 v10, 64, v8
	v_mov_b64_e32 v[8:9], s[14:15]
	s_lshl_b64 s[10:11], s[10:11], 2
	v_mad_i64_i32 v[8:9], s[16:17], v10, s16, v[8:9]
	v_lshl_add_u64 v[0:1], v[0:1], 0, s[10:11]
	v_lshlrev_b32_e32 v166, 2, v22
	v_lshl_add_u64 v[8:9], v[8:9], 0, s[10:11]
	v_lshl_add_u64 v[4:5], v[0:1], 0, v[166:167]
	s_waitcnt vmcnt(2)
	v_lshl_add_u64 v[12:13], v[8:9], 0, v[166:167]
	global_load_dwordx4 v[0:3], v[4:5], off nt
	s_nop 0
	global_load_dwordx4 v[4:7], v[4:5], off offset:16 nt
	s_nop 0
	global_load_dwordx4 v[8:11], v[12:13], off nt
	s_nop 0
	global_load_dwordx4 v[12:15], v[12:13], off offset:16 nt
	v_and_b32_e32 v18, 63, v16
	v_lshrrev_b32_e32 v19, 1, v16
	v_lshlrev_b32_e32 v16, 4, v16
	v_and_b32_e32 v16, 16, v16
	v_ashrrev_i32_e32 v23, 2, v17
	v_and_or_b32 v19, v19, 15, v16
	v_and_b32_e32 v16, -16, v23
	s_movk_i32 s10, 0x104
	v_or_b32_e32 v23, 15, v23
	v_readlane_b32 s11, v251, 38
	v_add_u32_e32 v21, 0, v166
	v_lshl_add_u32 v24, v18, 2, 0
	v_mul_lo_u32 v25, v16, s10
	v_mul_lo_u32 v26, v20, s10
	v_mul_lo_u32 v23, v23, s10
	v_readlane_b32 s19, v251, 52
	s_lshl_b32 s11, s11, 7
	v_ashrrev_i32_e32 v17, 31, v16
	s_lshl_b32 s10, s19, 7
	v_add_u32_e32 v20, s11, v20
	v_add_u32_e32 v21, v21, v26
	v_lshlrev_b32_e32 v166, 2, v22
	v_add_u32_e32 v22, v24, v25
	v_add_u32_e32 v23, v24, v23
	s_waitcnt vmcnt(0)
	s_branch .LBB0_329

; #define tidx() tidx_(wv_)
; __device__ __forceinline__ void conv_run(const float* __restrict__ src, u16* __restrict__ dst, int K, int N, int mode, int& base,
;                                          float* lds, int gi, int ng, int wv_) {
;   const int nk = K / 128, nn = N / 64, ntiles = nk * nn;
;   const int t = tidx();
;   int lt = (base & 1) ? (ng - 1 - gi) : gi;
;   base += 1;
;   float4 ra[2], rb[2];
;   auto gl = [&](int tile) {
;     const int k0 = (tile % nk) * 128, n0 = (tile / nk) * 64;
; #pragma unroll
;     for (int i = 0; i < 2; ++i) {
;       const int kl = (t >> 3) + 64 * i, c8 = (t & 7) * 8;
;       typedef float f4v __attribute__((ext_vector_type(4)));
;       const f4v* sp = (const f4v*)(src + (size_t)(k0 + kl) * N + n0 + c8);
;       const f4v va = __builtin_nontemporal_load(sp), vb = __builtin_nontemporal_load(sp + 1);
;       ra[i] = make_float4(va.x, va.y, va.z, va.w); rb[i] = make_float4(vb.x, vb.y, vb.z, vb.w);
;     }
;   };
;   __syncthreads();
;   if (lt < ntiles) gl(lt);
;   while (lt < ntiles) {
;     const int nxt = lt + ng;
;     const int k0 = (lt % nk) * 128, n0 = (lt / nk) * 64;
;     asm volatile("s_waitcnt lgkmcnt(0)\n\ts_barrier" ::: "memory");
; #pragma unroll
;     for (int i = 0; i < 2; ++i) {
;       const int kl = (t >> 3) + 64 * i, c8 = (t & 7) * 8;
;       float* d = lds + kl * 65 + c8;
;       d[0] = ra[i].x; d[1] = ra[i].y; d[2] = ra[i].z; d[3] = ra[i].w; d[4] = rb[i].x; d[5] = rb[i].y; d[6] = rb[i].z; d[7] = rb[i].w;
;     }
;     if (nxt < ntiles) gl(nxt);
;     asm volatile("s_waitcnt lgkmcnt(0)\n\ts_barrier" ::: "memory");
;     const int nl = t & 63, kc = t >> 6;
;     const int n = n0 + nl;
;     const int row = (mode == 0) ? ((n & ~255) + perm256(n & 255)) : ((n >> 7) * 256 + perm128(n & 127) + (mode == 2 ? 128 : 0));
;     float f[16];
; #pragma unroll
;     for (int i = 0; i < 16; ++i) f[i] = lds[(kc * 16 + i) * 65 + nl];
;     uint4* dp = (uint4*)(dst + (size_t)row * K + k0 + kc * 16);
;     dp[0] = pack8(f);
;     dp[1] = pack8(f + 8);
;     lt = nxt;
;   }
.LBB0_329:
	v_readlane_b32 s16, v251, 38
	v_add_u32_e32 v24, 0x4100, v21
	s_add_i32 s18, s19, s16
	s_waitcnt lgkmcnt(0)
	s_barrier
	s_waitcnt vmcnt(5)
	ds_write2_b32 v21, v0, v1 offset1:1
	ds_write2_b32 v21, v2, v3 offset0:2 offset1:3
	s_waitcnt vmcnt(4)
	ds_write2_b32 v21, v4, v5 offset0:4 offset1:5
	ds_write2_b32 v21, v6, v7 offset0:6 offset1:7
	s_waitcnt vmcnt(3)
	ds_write2_b32 v24, v8, v9 offset1:1
	v_add_u32_e32 v24, 0x4108, v21
	s_cmpk_gt_i32 s18, 0x57f
	ds_write2_b32 v24, v10, v11 offset1:1
	v_add_u32_e32 v24, 0x4110, v21
	s_cselect_b64 s[16:17], -1, 0
	s_waitcnt vmcnt(2)
	ds_write2_b32 v24, v12, v13 offset1:1
	v_add_u32_e32 v24, 0x4118, v21
	s_and_b64 vcc, exec, s[16:17]
	ds_write2_b32 v24, v14, v15 offset1:1
	s_cbranch_vccnz .LBB0_328
	s_ashr_i32 s28, s18, 31
	s_lshr_b32 s28, s28, 28
	s_add_i32 s28, s18, s28
	s_ashr_i32 s30, s28, 4
	s_lshl_b32 s28, s30, 6
	v_add_u32_e32 v0, s10, v20
	s_lshl_b32 s30, s30, 11
	v_subrev_u32_e32 v10, s30, v0
	v_mov_b64_e32 v[8:9], s[14:15]
	s_movk_i32 s36, 0x5800
	s_ashr_i32 s29, s28, 31
	v_mad_i64_i32 v[0:1], s[30:31], v10, s36, v[8:9]
	v_add_u32_e32 v10, 64, v10
	s_lshl_b64 s[28:29], s[28:29], 2
	v_mad_i64_i32 v[8:9], s[30:31], v10, s36, v[8:9]
	v_lshl_add_u64 v[0:1], v[0:1], 0, s[28:29]
	v_lshl_add_u64 v[8:9], v[8:9], 0, s[28:29]
	v_lshl_add_u64 v[4:5], v[0:1], 0, v[166:167]
	v_lshl_add_u64 v[12:13], v[8:9], 0, v[166:167]
	global_load_dwordx4 v[0:3], v[4:5], off nt
	s_nop 0
	global_load_dwordx4 v[4:7], v[4:5], off offset:16 nt
	s_nop 0
	global_load_dwordx4 v[8:11], v[12:13], off nt
	s_nop 0
	global_load_dwordx4 v[12:15], v[12:13], off offset:16 nt
	s_branch .LBB0_328
.LBB0_331:
	s_and_b64 vcc, exec, s[4:5]
	v_mbcnt_lo_u32_b32 v18, -1, 0
	v_mbcnt_hi_u32_b32 v18, -1, v18
	s_barrier
	s_cbranch_vccnz .LBB0_336
	v_or_b32_e32 v16, s60, v18
	v_ashrrev_i32_e32 v19, 3, v16
	v_readlane_b32 s10, v251, 49
	s_load_dwordx2 s[8:9], s[0:1], 0x50
	s_waitcnt vmcnt(5)
	v_lshlrev_b32_e32 v0, 3, v18
	s_waitcnt vmcnt(3)
	v_add_u32_e32 v8, s10, v19
	v_ashrrev_i32_e32 v9, 31, v8
	v_and_b32_e32 v22, 56, v0
	v_lshlrev_b64 v[0:1], 13, v[8:9]
	v_add_u32_e32 v8, 64, v8
	v_readlane_b32 s10, v251, 50
	v_ashrrev_i32_e32 v9, 31, v8
	s_add_u32 s14, s2, 0x6e00000
	v_readlane_b32 s11, v251, 51
	v_lshlrev_b64 v[8:9], 13, v[8:9]
	s_addc_u32 s15, s3, 0
	s_waitcnt lgkmcnt(0)
	v_lshl_add_u64 v[0:1], s[8:9], 0, v[0:1]
	s_lshl_b64 s[10:11], s[10:11], 2
	v_lshl_add_u64 v[8:9], s[8:9], 0, v[8:9]
	v_lshl_add_u64 v[0:1], v[0:1], 0, s[10:11]
	v_lshlrev_b32_e32 v166, 2, v22
	v_lshl_add_u64 v[8:9], v[8:9], 0, s[10:11]
	v_lshl_add_u64 v[4:5], v[0:1], 0, v[166:167]
	s_waitcnt vmcnt(2)
	v_lshl_add_u64 v[12:13], v[8:9], 0, v[166:167]
	global_load_dwordx4 v[0:3], v[4:5], off nt
	s_nop 0
	global_load_dwordx4 v[4:7], v[4:5], off offset:16 nt
	s_nop 0
	global_load_dwordx4 v[8:11], v[12:13], off nt
	s_nop 0
	global_load_dwordx4 v[12:15], v[12:13], off offset:16 nt
	v_ashrrev_i32_e32 v23, 2, v16
	v_and_b32_e32 v17, 63, v18
	v_bfe_u32 v21, v18, 2, 4
	v_and_b32_e32 v16, -16, v23
	s_movk_i32 s10, 0x104
	v_or_b32_e32 v23, 15, v23
	v_lshlrev_b32_e32 v27, 6, v18
	v_lshlrev_b32_e32 v18, 4, v18
	v_readlane_b32 s11, v251, 38
	v_add_u32_e32 v20, 0, v166
	v_lshl_add_u32 v24, v17, 2, 0
	v_mul_lo_u32 v25, v16, s10
	v_mul_lo_u32 v26, v19, s10
	v_mul_lo_u32 v23, v23, s10
	v_and_b32_e32 v27, 0x80, v27
	v_and_b32_e32 v18, 16, v18
	v_readlane_b32 s19, v251, 55
	s_lshl_b32 s11, s11, 7
	v_ashrrev_i32_e32 v17, 31, v16
	v_or3_b32 v18, v27, v21, v18
	s_lshl_b32 s10, s19, 7
	v_add_u32_e32 v19, s11, v19
	v_add_u32_e32 v20, v20, v26
	v_lshlrev_b32_e32 v166, 2, v22
	v_add_u32_e32 v21, v24, v25
	v_add_u32_e32 v22, v24, v23
	s_waitcnt vmcnt(0)
	s_branch .LBB0_334

; #define tidx() tidx_(wv_)
; __device__ __forceinline__ void conv_run(const float* __restrict__ src, u16* __restrict__ dst, int K, int N, int mode, int& base,
;                                          float* lds, int gi, int ng, int wv_) {
;   const int nk = K / 128, nn = N / 64, ntiles = nk * nn;
;   const int t = tidx();
;   int lt = (base & 1) ? (ng - 1 - gi) : gi;
;   base += 1;
;   float4 ra[2], rb[2];
;   auto gl = [&](int tile) {
;     const int k0 = (tile % nk) * 128, n0 = (tile / nk) * 64;
; #pragma unroll
;     for (int i = 0; i < 2; ++i) {
;       const int kl = (t >> 3) + 64 * i, c8 = (t & 7) * 8;
;       typedef float f4v __attribute__((ext_vector_type(4)));
;       const f4v* sp = (const f4v*)(src + (size_t)(k0 + kl) * N + n0 + c8);
;       const f4v va = __builtin_nontemporal_load(sp), vb = __builtin_nontemporal_load(sp + 1);
;       ra[i] = make_float4(va.x, va.y, va.z, va.w); rb[i] = make_float4(vb.x, vb.y, vb.z, vb.w);
;     }
;   };
;   __syncthreads();
;   if (lt < ntiles) gl(lt);
;   while (lt < ntiles) {
;     const int nxt = lt + ng;
;     const int k0 = (lt % nk) * 128, n0 = (lt / nk) * 64;
;     asm volatile("s_waitcnt lgkmcnt(0)\n\ts_barrier" ::: "memory");
; #pragma unroll
;     for (int i = 0; i < 2; ++i) {
;       const int kl = (t >> 3) + 64 * i, c8 = (t & 7) * 8;
;       float* d = lds + kl * 65 + c8;
;       d[0] = ra[i].x; d[1] = ra[i].y; d[2] = ra[i].z; d[3] = ra[i].w; d[4] = rb[i].x; d[5] = rb[i].y; d[6] = rb[i].z; d[7] = rb[i].w;
;     }
;     if (nxt < ntiles) gl(nxt);
;     asm volatile("s_waitcnt lgkmcnt(0)\n\ts_barrier" ::: "memory");
;     const int nl = t & 63, kc = t >> 6;
;     const int n = n0 + nl;
;     const int row = (mode == 0) ? ((n & ~255) + perm256(n & 255)) : ((n >> 7) * 256 + perm128(n & 127) + (mode == 2 ? 128 : 0));
;     float f[16];
; #pragma unroll
;     for (int i = 0; i < 16; ++i) f[i] = lds[(kc * 16 + i) * 65 + nl];
;     uint4* dp = (uint4*)(dst + (size_t)row * K + k0 + kc * 16);
;     dp[0] = pack8(f);
;     dp[1] = pack8(f + 8);
;     lt = nxt;
;   }
.LBB0_334:
	v_readlane_b32 s16, v251, 38
	v_add_u32_e32 v23, 0x4100, v20
	s_add_i32 s18, s19, s16
	s_waitcnt lgkmcnt(0)
	s_barrier
	s_waitcnt vmcnt(5)
	ds_write2_b32 v20, v0, v1 offset1:1
	ds_write2_b32 v20, v2, v3 offset0:2 offset1:3
	s_waitcnt vmcnt(4)
	ds_write2_b32 v20, v4, v5 offset0:4 offset1:5
	ds_write2_b32 v20, v6, v7 offset0:6 offset1:7
	s_waitcnt vmcnt(3)
	ds_write2_b32 v23, v8, v9 offset1:1
	v_add_u32_e32 v23, 0x4108, v20
	s_cmpk_gt_i32 s18, 0x57f
	ds_write2_b32 v23, v10, v11 offset1:1
	v_add_u32_e32 v23, 0x4110, v20
	s_cselect_b64 s[16:17], -1, 0
	s_waitcnt vmcnt(2)
	ds_write2_b32 v23, v12, v13 offset1:1
	v_add_u32_e32 v23, 0x4118, v20
	s_and_b64 vcc, exec, s[16:17]
	ds_write2_b32 v23, v14, v15 offset1:1
	s_cbranch_vccnz .LBB0_333
	s_mul_hi_i32 s28, s18, 0x2e8ba2e9
	s_lshr_b32 s29, s28, 31
	s_ashr_i32 s28, s28, 3
	s_add_i32 s30, s28, s29
	s_lshl_b32 s28, s30, 6
	s_mulk_i32 s30, 0xea00
	s_add_i32 s30, s30, s10
	v_add_u32_e32 v8, s30, v19
	v_ashrrev_i32_e32 v9, 31, v8
	v_lshlrev_b64 v[0:1], 13, v[8:9]
	v_add_u32_e32 v8, 64, v8
	v_ashrrev_i32_e32 v9, 31, v8
	s_ashr_i32 s29, s28, 31
	v_lshlrev_b64 v[8:9], 13, v[8:9]
	v_lshl_add_u64 v[0:1], s[8:9], 0, v[0:1]
	s_lshl_b64 s[28:29], s[28:29], 2
	v_lshl_add_u64 v[8:9], s[8:9], 0, v[8:9]
	v_lshl_add_u64 v[0:1], v[0:1], 0, s[28:29]
	v_lshl_add_u64 v[8:9], v[8:9], 0, s[28:29]
	v_lshl_add_u64 v[4:5], v[0:1], 0, v[166:167]
	v_lshl_add_u64 v[12:13], v[8:9], 0, v[166:167]
	global_load_dwordx4 v[0:3], v[4:5], off nt
	s_nop 0
	global_load_dwordx4 v[4:7], v[4:5], off offset:16 nt
	s_nop 0
	global_load_dwordx4 v[8:11], v[12:13], off nt
	s_nop 0
	global_load_dwordx4 v[12:15], v[12:13], off offset:16 nt
	s_branch .LBB0_333
.LBB0_336:
	v_readlane_b32 s8, v251, 53
	v_readlane_b32 s9, v251, 54
	s_andn2_b64 vcc, exec, s[8:9]
	v_mbcnt_lo_u32_b32 v18, -1, 0
	v_mbcnt_hi_u32_b32 v18, -1, v18
	s_barrier
	s_cbranch_vccnz .LBB0_341
	v_or_b32_e32 v16, s60, v18
	v_ashrrev_i32_e32 v19, 3, v16
	v_readlane_b32 s10, v251, 46
	s_load_dwordx2 s[8:9], s[0:1], 0x60
	s_waitcnt vmcnt(5)
	v_lshlrev_b32_e32 v0, 3, v18
	s_waitcnt vmcnt(3)
	v_add_u32_e32 v8, s10, v19
	v_ashrrev_i32_e32 v9, 31, v8
	v_and_b32_e32 v22, 56, v0
	v_lshlrev_b64 v[0:1], 13, v[8:9]
	v_add_u32_e32 v8, 64, v8
	v_readlane_b32 s10, v251, 47
	v_ashrrev_i32_e32 v9, 31, v8
	s_add_u32 s14, s2, 0x8400000
	v_readlane_b32 s11, v251, 48
	v_lshlrev_b64 v[8:9], 13, v[8:9]
	s_addc_u32 s15, s3, 0
	s_waitcnt lgkmcnt(0)
	v_lshl_add_u64 v[0:1], s[8:9], 0, v[0:1]
	s_lshl_b64 s[10:11], s[10:11], 2
	v_lshl_add_u64 v[8:9], s[8:9], 0, v[8:9]
	v_lshl_add_u64 v[0:1], v[0:1], 0, s[10:11]
	v_lshlrev_b32_e32 v166, 2, v22
	v_lshl_add_u64 v[8:9], v[8:9], 0, s[10:11]
	v_lshl_add_u64 v[4:5], v[0:1], 0, v[166:167]
	s_waitcnt vmcnt(2)
	v_lshl_add_u64 v[12:13], v[8:9], 0, v[166:167]
	global_load_dwordx4 v[0:3], v[4:5], off nt
	s_nop 0
	global_load_dwordx4 v[4:7], v[4:5], off offset:16 nt
	s_nop 0
	global_load_dwordx4 v[8:11], v[12:13], off nt
	s_nop 0
	global_load_dwordx4 v[12:15], v[12:13], off offset:16 nt
	v_ashrrev_i32_e32 v23, 2, v16
	v_and_b32_e32 v17, 63, v18
	v_bfe_u32 v21, v18, 2, 4
	v_and_b32_e32 v16, -16, v23
	s_movk_i32 s10, 0x104
	v_or_b32_e32 v23, 15, v23
	v_lshlrev_b32_e32 v27, 6, v18
	v_lshlrev_b32_e32 v18, 4, v18
	v_readlane_b32 s11, v251, 38
	v_add_u32_e32 v20, 0, v166
	v_lshl_add_u32 v24, v17, 2, 0
	v_mul_lo_u32 v25, v16, s10
	v_mul_lo_u32 v26, v19, s10
	v_mul_lo_u32 v23, v23, s10
	v_and_b32_e32 v27, 0x80, v27
	v_and_b32_e32 v18, 16, v18
	v_readlane_b32 s19, v251, 52
	s_lshl_b32 s11, s11, 7
	v_ashrrev_i32_e32 v17, 31, v16
	v_or3_b32 v18, v27, v21, v18
	s_lshl_b32 s10, s19, 7
	v_add_u32_e32 v19, s11, v19
	v_add_u32_e32 v20, v20, v26
	v_lshlrev_b32_e32 v166, 2, v22
	v_add_u32_e32 v21, v24, v25
	v_add_u32_e32 v22, v24, v23
	s_waitcnt vmcnt(0)
	s_branch .LBB0_339

; #define tidx() tidx_(wv_)
; __device__ __forceinline__ void conv_run(const float* __restrict__ src, u16* __restrict__ dst, int K, int N, int mode, int& base,
;                                          float* lds, int gi, int ng, int wv_) {
;   const int nk = K / 128, nn = N / 64, ntiles = nk * nn;
;   const int t = tidx();
;   int lt = (base & 1) ? (ng - 1 - gi) : gi;
;   base += 1;
;   float4 ra[2], rb[2];
;   auto gl = [&](int tile) {
;     const int k0 = (tile % nk) * 128, n0 = (tile / nk) * 64;
; #pragma unroll
;     for (int i = 0; i < 2; ++i) {
;       const int kl = (t >> 3) + 64 * i, c8 = (t & 7) * 8;
;       typedef float f4v __attribute__((ext_vector_type(4)));
;       const f4v* sp = (const f4v*)(src + (size_t)(k0 + kl) * N + n0 + c8);
;       const f4v va = __builtin_nontemporal_load(sp), vb = __builtin_nontemporal_load(sp + 1);
;       ra[i] = make_float4(va.x, va.y, va.z, va.w); rb[i] = make_float4(vb.x, vb.y, vb.z, vb.w);
;     }
;   };
;   __syncthreads();
;   if (lt < ntiles) gl(lt);
;   while (lt < ntiles) {
;     const int nxt = lt + ng;
;     const int k0 = (lt % nk) * 128, n0 = (lt / nk) * 64;
;     asm volatile("s_waitcnt lgkmcnt(0)\n\ts_barrier" ::: "memory");
; #pragma unroll
;     for (int i = 0; i < 2; ++i) {
;       const int kl = (t >> 3) + 64 * i, c8 = (t & 7) * 8;
;       float* d = lds + kl * 65 + c8;
;       d[0] = ra[i].x; d[1] = ra[i].y; d[2] = ra[i].z; d[3] = ra[i].w; d[4] = rb[i].x; d[5] = rb[i].y; d[6] = rb[i].z; d[7] = rb[i].w;
;     }
;     if (nxt < ntiles) gl(nxt);
;     asm volatile("s_waitcnt lgkmcnt(0)\n\ts_barrier" ::: "memory");
;     const int nl = t & 63, kc = t >> 6;
;     const int n = n0 + nl;
;     const int row = (mode == 0) ? ((n & ~255) + perm256(n & 255)) : ((n >> 7) * 256 + perm128(n & 127) + (mode == 2 ? 128 : 0));
;     float f[16];
; #pragma unroll
;     for (int i = 0; i < 16; ++i) f[i] = lds[(kc * 16 + i) * 65 + nl];
;     uint4* dp = (uint4*)(dst + (size_t)row * K + k0 + kc * 16);
;     dp[0] = pack8(f);
;     dp[1] = pack8(f + 8);
;     lt = nxt;
;   }
.LBB0_339:
	v_readlane_b32 s16, v251, 38
	v_add_u32_e32 v23, 0x4100, v20
	s_add_i32 s18, s19, s16
	s_waitcnt lgkmcnt(0)
	s_barrier
	s_waitcnt vmcnt(5)
	ds_write2_b32 v20, v0, v1 offset1:1
	ds_write2_b32 v20, v2, v3 offset0:2 offset1:3
	s_waitcnt vmcnt(4)
	ds_write2_b32 v20, v4, v5 offset0:4 offset1:5
	ds_write2_b32 v20, v6, v7 offset0:6 offset1:7
	s_waitcnt vmcnt(3)
	ds_write2_b32 v23, v8, v9 offset1:1
	v_add_u32_e32 v23, 0x4108, v20
	s_cmpk_gt_i32 s18, 0x1ff
	ds_write2_b32 v23, v10, v11 offset1:1
	v_add_u32_e32 v23, 0x4110, v20
	s_cselect_b64 s[16:17], -1, 0
	s_waitcnt vmcnt(2)
	ds_write2_b32 v23, v12, v13 offset1:1
	v_add_u32_e32 v23, 0x4118, v20
	s_and_b64 vcc, exec, s[16:17]
	ds_write2_b32 v23, v14, v15 offset1:1
	s_cbranch_vccnz .LBB0_338
	s_ashr_i32 s28, s18, 31
	s_lshr_b32 s28, s28, 28
	s_add_i32 s28, s18, s28
	s_ashr_i32 s30, s28, 4
	s_lshl_b32 s28, s30, 6
	v_add_u32_e32 v0, s10, v19
	s_lshl_b32 s30, s30, 11
	v_subrev_u32_e32 v8, s30, v0
	v_ashrrev_i32_e32 v9, 31, v8
	v_lshlrev_b64 v[0:1], 13, v[8:9]
	v_add_u32_e32 v8, 64, v8
	v_ashrrev_i32_e32 v9, 31, v8
	s_ashr_i32 s29, s28, 31
	v_lshlrev_b64 v[8:9], 13, v[8:9]
	v_lshl_add_u64 v[0:1], s[8:9], 0, v[0:1]
	s_lshl_b64 s[28:29], s[28:29], 2
	v_lshl_add_u64 v[8:9], s[8:9], 0, v[8:9]
	v_lshl_add_u64 v[0:1], v[0:1], 0, s[28:29]
	v_lshl_add_u64 v[8:9], v[8:9], 0, s[28:29]
	v_lshl_add_u64 v[4:5], v[0:1], 0, v[166:167]
	v_lshl_add_u64 v[12:13], v[8:9], 0, v[166:167]
	global_load_dwordx4 v[0:3], v[4:5], off nt
	s_nop 0
	global_load_dwordx4 v[4:7], v[4:5], off offset:16 nt
	s_nop 0
	global_load_dwordx4 v[8:11], v[12:13], off nt
	s_nop 0
	global_load_dwordx4 v[12:15], v[12:13], off offset:16 nt
	s_branch .LBB0_338
.LBB0_341:
	v_readlane_b32 s8, v251, 56
	v_readlane_b32 s9, v251, 57
	s_andn2_b64 vcc, exec, s[8:9]
	v_mbcnt_lo_u32_b32 v18, -1, 0
	v_mbcnt_hi_u32_b32 v18, -1, v18
	s_barrier
	s_cbranch_vccnz .LBB0_346
	v_or_b32_e32 v16, s60, v18
	v_ashrrev_i32_e32 v19, 3, v16
	v_readlane_b32 s10, v251, 41
	s_load_dwordx2 s[8:9], s[0:1], 0x78
	s_waitcnt vmcnt(5)
	v_lshlrev_b32_e32 v0, 3, v18
	s_waitcnt vmcnt(3)
	v_add_u32_e32 v8, s10, v19
	v_ashrrev_i32_e32 v9, 31, v8
	v_and_b32_e32 v22, 56, v0
	v_lshlrev_b64 v[0:1], 13, v[8:9]
	v_add_u32_e32 v8, 64, v8
	v_readlane_b32 s10, v251, 42
	v_ashrrev_i32_e32 v9, 31, v8
	s_add_u32 s2, s2, 0xa700000
	v_readlane_b32 s11, v251, 43
	v_lshlrev_b64 v[8:9], 13, v[8:9]
	s_addc_u32 s3, s3, 0
	s_waitcnt lgkmcnt(0)
	v_lshl_add_u64 v[0:1], s[8:9], 0, v[0:1]
	s_lshl_b64 s[10:11], s[10:11], 2
	v_lshl_add_u64 v[8:9], s[8:9], 0, v[8:9]
	v_lshl_add_u64 v[0:1], v[0:1], 0, s[10:11]
	v_lshlrev_b32_e32 v166, 2, v22
	v_lshl_add_u64 v[8:9], v[8:9], 0, s[10:11]
	v_lshl_add_u64 v[4:5], v[0:1], 0, v[166:167]
	s_waitcnt vmcnt(2)
	v_lshl_add_u64 v[12:13], v[8:9], 0, v[166:167]
	global_load_dwordx4 v[0:3], v[4:5], off nt
	s_nop 0
	global_load_dwordx4 v[4:7], v[4:5], off offset:16 nt
	s_nop 0
	global_load_dwordx4 v[8:11], v[12:13], off nt
	s_nop 0
	global_load_dwordx4 v[12:15], v[12:13], off offset:16 nt
	v_ashrrev_i32_e32 v23, 2, v16
	v_and_b32_e32 v17, 63, v18
	v_bfe_u32 v21, v18, 2, 4
	v_and_b32_e32 v16, -16, v23
	s_movk_i32 s10, 0x104
	v_or_b32_e32 v23, 15, v23
	v_lshlrev_b32_e32 v27, 6, v18
	v_lshlrev_b32_e32 v18, 4, v18
	v_readlane_b32 s11, v251, 38
	v_add_u32_e32 v20, 0, v166
	v_lshl_add_u32 v24, v17, 2, 0
	v_mul_lo_u32 v25, v16, s10
	v_mul_lo_u32 v26, v19, s10
	v_mul_lo_u32 v23, v23, s10
	v_and_b32_e32 v27, 0x80, v27
	v_and_b32_e32 v18, 16, v18
	v_readlane_b32 s17, v251, 55
	s_lshl_b32 s11, s11, 7
	v_ashrrev_i32_e32 v17, 31, v16
	v_or3_b32 v18, v27, v21, v18
	s_lshl_b32 s10, s17, 7
	v_add_u32_e32 v19, s11, v19
	v_add_u32_e32 v20, v20, v26
	v_lshlrev_b32_e32 v166, 2, v22
	v_add_u32_e32 v21, v24, v25
	v_add_u32_e32 v22, v24, v23
	s_waitcnt vmcnt(0)
	s_branch .LBB0_344

; #define tidx() tidx_(wv_)
; __device__ __forceinline__ void conv_run(const float* __restrict__ src, u16* __restrict__ dst, int K, int N, int mode, int& base,
;                                          float* lds, int gi, int ng, int wv_) {
;   const int nk = K / 128, nn = N / 64, ntiles = nk * nn;
;   const int t = tidx();
;   int lt = (base & 1) ? (ng - 1 - gi) : gi;
;   base += 1;
;   float4 ra[2], rb[2];
;   auto gl = [&](int tile) {
;     const int k0 = (tile % nk) * 128, n0 = (tile / nk) * 64;
; #pragma unroll
;     for (int i = 0; i < 2; ++i) {
;       const int kl = (t >> 3) + 64 * i, c8 = (t & 7) * 8;
;       typedef float f4v __attribute__((ext_vector_type(4)));
;       const f4v* sp = (const f4v*)(src + (size_t)(k0 + kl) * N + n0 + c8);
;       const f4v va = __builtin_nontemporal_load(sp), vb = __builtin_nontemporal_load(sp + 1);
;       ra[i] = make_float4(va.x, va.y, va.z, va.w); rb[i] = make_float4(vb.x, vb.y, vb.z, vb.w);
;     }
;   };
;   __syncthreads();
;   if (lt < ntiles) gl(lt);
;   while (lt < ntiles) {
;     const int nxt = lt + ng;
;     const int k0 = (lt % nk) * 128, n0 = (lt / nk) * 64;
;     asm volatile("s_waitcnt lgkmcnt(0)\n\ts_barrier" ::: "memory");
; #pragma unroll
;     for (int i = 0; i < 2; ++i) {
;       const int kl = (t >> 3) + 64 * i, c8 = (t & 7) * 8;
;       float* d = lds + kl * 65 + c8;
;       d[0] = ra[i].x; d[1] = ra[i].y; d[2] = ra[i].z; d[3] = ra[i].w; d[4] = rb[i].x; d[5] = rb[i].y; d[6] = rb[i].z; d[7] = rb[i].w;
;     }
;     if (nxt < ntiles) gl(nxt);
;     asm volatile("s_waitcnt lgkmcnt(0)\n\ts_barrier" ::: "memory");
;     const int nl = t & 63, kc = t >> 6;
;     const int n = n0 + nl;
;     const int row = (mode == 0) ? ((n & ~255) + perm256(n & 255)) : ((n >> 7) * 256 + perm128(n & 127) + (mode == 2 ? 128 : 0));
;     float f[16];
; #pragma unroll
;     for (int i = 0; i < 16; ++i) f[i] = lds[(kc * 16 + i) * 65 + nl];
;     uint4* dp = (uint4*)(dst + (size_t)row * K + k0 + kc * 16);
;     dp[0] = pack8(f);
;     dp[1] = pack8(f + 8);
;     lt = nxt;
;   }
.LBB0_344:
	v_readlane_b32 s14, v251, 38
	v_add_u32_e32 v23, 0x4100, v20
	s_add_i32 s16, s17, s14
	s_waitcnt lgkmcnt(0)
	s_barrier
	s_waitcnt vmcnt(5)
	ds_write2_b32 v20, v0, v1 offset1:1
	ds_write2_b32 v20, v2, v3 offset0:2 offset1:3
	s_waitcnt vmcnt(4)
	ds_write2_b32 v20, v4, v5 offset0:4 offset1:5
	ds_write2_b32 v20, v6, v7 offset0:6 offset1:7
	s_waitcnt vmcnt(3)
	ds_write2_b32 v23, v8, v9 offset1:1
	v_add_u32_e32 v23, 0x4108, v20
	s_cmpk_gt_i32 s16, 0x1ff
	ds_write2_b32 v23, v10, v11 offset1:1
	v_add_u32_e32 v23, 0x4110, v20
	s_cselect_b64 s[14:15], -1, 0
	s_waitcnt vmcnt(2)
	ds_write2_b32 v23, v12, v13 offset1:1
	v_add_u32_e32 v23, 0x4118, v20
	s_and_b64 vcc, exec, s[14:15]
	ds_write2_b32 v23, v14, v15 offset1:1
	s_cbranch_vccnz .LBB0_343
	s_ashr_i32 s18, s16, 31
	s_lshr_b32 s18, s18, 28
	s_add_i32 s18, s16, s18
	s_ashr_i32 s28, s18, 4
	s_lshl_b32 s18, s28, 6
	v_add_u32_e32 v0, s10, v19
	s_lshl_b32 s28, s28, 11
	v_subrev_u32_e32 v8, s28, v0
	v_ashrrev_i32_e32 v9, 31, v8
	v_lshlrev_b64 v[0:1], 13, v[8:9]
	v_add_u32_e32 v8, 64, v8
	v_ashrrev_i32_e32 v9, 31, v8
	s_ashr_i32 s19, s18, 31
	v_lshlrev_b64 v[8:9], 13, v[8:9]
	v_lshl_add_u64 v[0:1], s[8:9], 0, v[0:1]
	s_lshl_b64 s[18:19], s[18:19], 2
	v_lshl_add_u64 v[8:9], s[8:9], 0, v[8:9]
	v_lshl_add_u64 v[0:1], v[0:1], 0, s[18:19]
	v_lshl_add_u64 v[8:9], v[8:9], 0, s[18:19]
	v_lshl_add_u64 v[4:5], v[0:1], 0, v[166:167]
	v_lshl_add_u64 v[12:13], v[8:9], 0, v[166:167]
	global_load_dwordx4 v[0:3], v[4:5], off nt
	s_nop 0
	global_load_dwordx4 v[4:7], v[4:5], off offset:16 nt
	s_nop 0
	global_load_dwordx4 v[8:11], v[12:13], off nt
	s_nop 0
	global_load_dwordx4 v[12:15], v[12:13], off offset:16 nt
	s_branch .LBB0_343
.LBB0_346:
	s_mov_b64 s[2:3], s[78:79]
	s_barrier
	s_add_u32 s8, s2, 0x2b348000
	s_addc_u32 s9, s3, 0
	s_and_b64 vcc, exec, s[4:5]
	v_mbcnt_lo_u32_b32 v16, -1, 0
	v_mbcnt_hi_u32_b32 v16, -1, v16
	s_barrier
	s_cbranch_vccnz .LBB0_351
	s_load_dwordx2 s[10:11], s[0:1], 0x18
	v_or_b32_e32 v17, s60, v16
	v_ashrrev_i32_e32 v20, 3, v17
	s_waitcnt vmcnt(5)
	v_lshlrev_b32_e32 v0, 3, v16
	s_movk_i32 s16, 0x5800
	s_waitcnt lgkmcnt(0)
	s_add_u32 s14, s10, 0x2c00000
	s_addc_u32 s15, s11, 0
	v_readlane_b32 s10, v251, 41
	s_waitcnt vmcnt(3)
	v_mov_b64_e32 v[8:9], s[14:15]
	v_and_b32_e32 v22, 56, v0
	v_add_u32_e32 v10, s10, v20
	v_mad_i64_i32 v[0:1], s[10:11], v10, s16, v[8:9]
	v_readlane_b32 s10, v251, 42
	v_readlane_b32 s11, v251, 43
	v_add_u32_e32 v10, 64, v10
	s_lshl_b64 s[10:11], s[10:11], 2
	v_mad_i64_i32 v[8:9], s[16:17], v10, s16, v[8:9]
	v_lshl_add_u64 v[0:1], v[0:1], 0, s[10:11]
	v_lshlrev_b32_e32 v166, 2, v22
	v_lshl_add_u64 v[8:9], v[8:9], 0, s[10:11]
	v_lshl_add_u64 v[4:5], v[0:1], 0, v[166:167]
	s_waitcnt vmcnt(2)
	v_lshl_add_u64 v[12:13], v[8:9], 0, v[166:167]
	global_load_dwordx4 v[0:3], v[4:5], off nt
	s_nop 0
	global_load_dwordx4 v[4:7], v[4:5], off offset:16 nt
	s_nop 0
	global_load_dwordx4 v[8:11], v[12:13], off nt
	s_nop 0
	global_load_dwordx4 v[12:15], v[12:13], off offset:16 nt
	v_and_b32_e32 v18, 63, v16
	v_lshlrev_b32_e32 v19, 4, v16
	v_bfe_u32 v16, v16, 1, 4
	v_ashrrev_i32_e32 v23, 2, v17
	v_and_or_b32 v19, v19, 16, v16
	v_and_b32_e32 v16, -16, v23
	s_movk_i32 s10, 0x104
	v_or_b32_e32 v23, 15, v23
	v_readlane_b32 s11, v251, 38
	v_add_u32_e32 v21, 0, v166
	v_lshl_add_u32 v24, v18, 2, 0
	v_mul_lo_u32 v25, v16, s10
	v_mul_lo_u32 v26, v20, s10
	v_mul_lo_u32 v23, v23, s10
	v_readlane_b32 s19, v251, 55
	s_lshl_b32 s11, s11, 7
	v_ashrrev_i32_e32 v17, 31, v16
	s_lshl_b32 s10, s19, 7
	v_add_u32_e32 v20, s11, v20
	v_add_u32_e32 v21, v21, v26
	v_lshlrev_b32_e32 v166, 2, v22
	v_add_u32_e32 v22, v24, v25
	v_add_u32_e32 v23, v24, v23
	s_waitcnt vmcnt(0)
	s_branch .LBB0_349

; #define tidx() tidx_(wv_)
; __device__ __forceinline__ void conv_run(const float* __restrict__ src, u16* __restrict__ dst, int K, int N, int mode, int& base,
;                                          float* lds, int gi, int ng, int wv_) {
;   const int nk = K / 128, nn = N / 64, ntiles = nk * nn;
;   const int t = tidx();
;   int lt = (base & 1) ? (ng - 1 - gi) : gi;
;   base += 1;
;   float4 ra[2], rb[2];
;   auto gl = [&](int tile) {
;     const int k0 = (tile % nk) * 128, n0 = (tile / nk) * 64;
; #pragma unroll
;     for (int i = 0; i < 2; ++i) {
;       const int kl = (t >> 3) + 64 * i, c8 = (t & 7) * 8;
;       typedef float f4v __attribute__((ext_vector_type(4)));
;       const f4v* sp = (const f4v*)(src + (size_t)(k0 + kl) * N + n0 + c8);
;       const f4v va = __builtin_nontemporal_load(sp), vb = __builtin_nontemporal_load(sp + 1);
;       ra[i] = make_float4(va.x, va.y, va.z, va.w); rb[i] = make_float4(vb.x, vb.y, vb.z, vb.w);
;     }
;   };
;   __syncthreads();
;   if (lt < ntiles) gl(lt);
.LBB0_351:
	s_and_b64 vcc, exec, s[6:7]
	v_mbcnt_lo_u32_b32 v16, -1, 0
	v_mbcnt_hi_u32_b32 v16, -1, v16
	s_barrier
	s_cbranch_vccnz .LBB0_356
	s_load_dwordx2 s[6:7], s[0:1], 0x20
	v_or_b32_e32 v17, s60, v16
	v_ashrrev_i32_e32 v20, 3, v17
	v_readlane_b32 s10, v251, 46
	s_waitcnt vmcnt(5)
	v_lshlrev_b32_e32 v0, 3, v16
	s_waitcnt lgkmcnt(0)
	s_add_u32 s6, s6, 0x2c00000
	s_addc_u32 s7, s7, 0
	s_waitcnt vmcnt(3)
	v_add_u32_e32 v10, s10, v20
	v_mov_b64_e32 v[8:9], s[6:7]
	s_movk_i32 s14, 0x5800
	v_and_b32_e32 v22, 56, v0
	v_mad_i64_i32 v[0:1], s[10:11], v10, s14, v[8:9]
	v_readlane_b32 s10, v251, 47
	v_readlane_b32 s11, v251, 48
	v_add_u32_e32 v10, 64, v10
	s_lshl_b64 s[10:11], s[10:11], 2
	v_mad_i64_i32 v[8:9], s[14:15], v10, s14, v[8:9]
	v_lshl_add_u64 v[0:1], v[0:1], 0, s[10:11]
	v_lshlrev_b32_e32 v166, 2, v22
	v_lshl_add_u64 v[8:9], v[8:9], 0, s[10:11]
	v_lshl_add_u64 v[4:5], v[0:1], 0, v[166:167]
	s_waitcnt vmcnt(2)
	v_lshl_add_u64 v[12:13], v[8:9], 0, v[166:167]
	global_load_dwordx4 v[0:3], v[4:5], off nt
	s_nop 0
	global_load_dwordx4 v[4:7], v[4:5], off offset:16 nt
	s_nop 0
	global_load_dwordx4 v[8:11], v[12:13], off nt
	s_nop 0
	global_load_dwordx4 v[12:15], v[12:13], off offset:16 nt
	v_and_b32_e32 v18, 63, v16
	v_lshrrev_b32_e32 v19, 1, v16
	v_lshlrev_b32_e32 v16, 4, v16
	v_and_b32_e32 v16, 16, v16
	v_ashrrev_i32_e32 v23, 2, v17
	v_and_or_b32 v19, v19, 15, v16
	v_and_b32_e32 v16, -16, v23
	s_movk_i32 s10, 0x104
	v_or_b32_e32 v23, 15, v23
	v_readlane_b32 s11, v251, 38
	v_add_u32_e32 v21, 0, v166
	v_lshl_add_u32 v24, v18, 2, 0
	v_mul_lo_u32 v25, v16, s10
	v_mul_lo_u32 v26, v20, s10
	v_mul_lo_u32 v23, v23, s10
	v_readlane_b32 s17, v251, 52
	s_lshl_b32 s11, s11, 7
	v_ashrrev_i32_e32 v17, 31, v16
	s_lshl_b32 s10, s17, 7
	v_add_u32_e32 v20, s11, v20
	v_add_u32_e32 v21, v21, v26
	v_lshlrev_b32_e32 v166, 2, v22
	v_add_u32_e32 v22, v24, v25
	v_add_u32_e32 v23, v24, v23
	s_waitcnt vmcnt(0)
	s_branch .LBB0_354

; #define tidx() tidx_(wv_)
; __device__ __forceinline__ void conv_run(const float* __restrict__ src, u16* __restrict__ dst, int K, int N, int mode, int& base,
;                                          float* lds, int gi, int ng, int wv_) {
;   const int nk = K / 128, nn = N / 64, ntiles = nk * nn;
;   const int t = tidx();
;   int lt = (base & 1) ? (ng - 1 - gi) : gi;
;   base += 1;
;   float4 ra[2], rb[2];
;   auto gl = [&](int tile) {
;     const int k0 = (tile % nk) * 128, n0 = (tile / nk) * 64;
; #pragma unroll
;     for (int i = 0; i < 2; ++i) {
;       const int kl = (t >> 3) + 64 * i, c8 = (t & 7) * 8;
;       typedef float f4v __attribute__((ext_vector_type(4)));
;       const f4v* sp = (const f4v*)(src + (size_t)(k0 + kl) * N + n0 + c8);
;       const f4v va = __builtin_nontemporal_load(sp), vb = __builtin_nontemporal_load(sp + 1);
;       ra[i] = make_float4(va.x, va.y, va.z, va.w); rb[i] = make_float4(vb.x, vb.y, vb.z, vb.w);
;     }
;   };
;   __syncthreads();
;   if (lt < ntiles) gl(lt);
.LBB0_356:
	s_and_b64 vcc, exec, s[4:5]
	v_mbcnt_lo_u32_b32 v18, -1, 0
	v_mbcnt_hi_u32_b32 v18, -1, v18
	s_barrier
	s_cbranch_vccnz .LBB0_361
	s_load_dwordx2 s[4:5], s[0:1], 0x28
	v_or_b32_e32 v16, s60, v18
	v_ashrrev_i32_e32 v19, 3, v16
	v_readlane_b32 s6, v251, 49
	s_waitcnt vmcnt(5)
	v_lshlrev_b32_e32 v0, 3, v18
	v_and_b32_e32 v22, 56, v0
	s_waitcnt vmcnt(3)
	v_add_u32_e32 v8, s6, v19
	v_ashrrev_i32_e32 v9, 31, v8
	s_waitcnt lgkmcnt(0)
	s_add_u32 s4, s4, 0x2c00000
	v_lshlrev_b64 v[0:1], 13, v[8:9]
	v_add_u32_e32 v8, 64, v8
	s_addc_u32 s5, s5, 0
	v_readlane_b32 s6, v251, 50
	v_ashrrev_i32_e32 v9, 31, v8
	s_add_u32 s2, s2, 0x2df48000
	v_readlane_b32 s7, v251, 51
	v_lshlrev_b64 v[8:9], 13, v[8:9]
	s_addc_u32 s3, s3, 0
	v_lshl_add_u64 v[0:1], s[4:5], 0, v[0:1]
	s_lshl_b64 s[6:7], s[6:7], 2
	v_lshl_add_u64 v[8:9], s[4:5], 0, v[8:9]
	v_lshl_add_u64 v[0:1], v[0:1], 0, s[6:7]
	v_lshlrev_b32_e32 v166, 2, v22
	v_lshl_add_u64 v[8:9], v[8:9], 0, s[6:7]
	v_lshl_add_u64 v[4:5], v[0:1], 0, v[166:167]
	s_waitcnt vmcnt(2)
	v_lshl_add_u64 v[12:13], v[8:9], 0, v[166:167]
	global_load_dwordx4 v[0:3], v[4:5], off nt
	s_nop 0
	global_load_dwordx4 v[4:7], v[4:5], off offset:16 nt
	s_nop 0
	global_load_dwordx4 v[8:11], v[12:13], off nt
	s_nop 0
	global_load_dwordx4 v[12:15], v[12:13], off offset:16 nt
	v_ashrrev_i32_e32 v23, 2, v16
	v_and_b32_e32 v16, -16, v23
	s_movk_i32 s6, 0x104
	v_or_b32_e32 v23, 15, v23
	v_and_b32_e32 v17, 63, v18
	v_bfe_u32 v21, v18, 2, 4
	v_mul_lo_u32 v25, v16, s6
	v_mul_lo_u32 v26, v19, s6
	v_mul_lo_u32 v23, v23, s6
	v_lshlrev_b32_e32 v27, 6, v18
	v_lshlrev_b32_e32 v18, 4, v18
	v_readlane_b32 s6, v251, 38
	v_add_u32_e32 v20, 0, v166
	v_lshl_add_u32 v24, v17, 2, 0
	v_and_b32_e32 v27, 0x80, v27
	v_and_b32_e32 v18, 16, v18
	v_readlane_b32 s11, v251, 55
	s_lshl_b32 s9, s6, 7
	v_ashrrev_i32_e32 v17, 31, v16
	v_or3_b32 v18, v27, v21, v18
	s_lshl_b32 s8, s11, 7
	v_add_u32_e32 v19, s9, v19
	v_add_u32_e32 v20, v20, v26
	v_lshlrev_b32_e32 v166, 2, v22
	v_add_u32_e32 v21, v24, v25
	v_add_u32_e32 v22, v24, v23
	s_waitcnt vmcnt(0)
	s_branch .LBB0_359

; __device__ __forceinline__ void conv_run(const float* __restrict__ src, u16* __restrict__ dst, int K, int N, int mode, int& base,
;                                          float* lds, int gi, int ng, int wv_) {
;     ...
;   while (lt < ntiles) {
;     const int nxt = lt + ng;
;     const int k0 = (lt % nk) * 128, n0 = (lt / nk) * 64;
;     asm volatile("s_waitcnt lgkmcnt(0)\n\ts_barrier" ::: "memory");
; #pragma unroll
;     for (int i = 0; i < 2; ++i) {
;       const int kl = (t >> 3) + 64 * i, c8 = (t & 7) * 8;
;       float* d = lds + kl * 65 + c8;
;       d[0] = ra[i].x; d[1] = ra[i].y; d[2] = ra[i].z; d[3] = ra[i].w; d[4] = rb[i].x; d[5] = rb[i].y; d[6] = rb[i].z; d[7] = rb[i].w;
;     }
;     if (nxt < ntiles) gl(nxt);
;     asm volatile("s_waitcnt lgkmcnt(0)\n\ts_barrier" ::: "memory");
;     const int nl = t & 63, kc = t >> 6;
;     const int n = n0 + nl;
;     const int row = (mode == 0) ? ((n & ~255) + perm256(n & 255)) : ((n >> 7) * 256 + perm128(n & 127) + (mode == 2 ? 128 : 0));
;     float f[16];
; #pragma unroll
;     for (int i = 0; i < 16; ++i) f[i] = lds[(kc * 16 + i) * 65 + nl];
;     uint4* dp = (uint4*)(dst + (size_t)row * K + k0 + kc * 16);
;     dp[0] = pack8(f);
;     dp[1] = pack8(f + 8);
;     lt = nxt;
;   }
.LBB0_359:
	v_readlane_b32 s6, v251, 38
	v_add_u32_e32 v23, 0x4100, v20
	s_add_i32 s10, s11, s6
	s_waitcnt lgkmcnt(0)
	s_barrier
	s_waitcnt vmcnt(5)
	ds_write2_b32 v20, v0, v1 offset1:1
	ds_write2_b32 v20, v2, v3 offset0:2 offset1:3
	s_waitcnt vmcnt(4)
	ds_write2_b32 v20, v4, v5 offset0:4 offset1:5
	ds_write2_b32 v20, v6, v7 offset0:6 offset1:7
	s_waitcnt vmcnt(3)
	ds_write2_b32 v23, v8, v9 offset1:1
	v_add_u32_e32 v23, 0x4108, v20
	s_cmpk_gt_i32 s10, 0x57f
	ds_write2_b32 v23, v10, v11 offset1:1
	v_add_u32_e32 v23, 0x4110, v20
	s_cselect_b64 s[6:7], -1, 0
	s_waitcnt vmcnt(2)
	ds_write2_b32 v23, v12, v13 offset1:1
	v_add_u32_e32 v23, 0x4118, v20
	s_and_b64 vcc, exec, s[6:7]
	ds_write2_b32 v23, v14, v15 offset1:1
	s_cbranch_vccnz .LBB0_358
	s_mul_hi_i32 s14, s10, 0x2e8ba2e9
	s_lshr_b32 s15, s14, 31
	s_ashr_i32 s14, s14, 3
	s_add_i32 s16, s14, s15
	s_lshl_b32 s14, s16, 6
	s_mulk_i32 s16, 0xea00
	s_add_i32 s16, s16, s8
	v_add_u32_e32 v8, s16, v19
	v_ashrrev_i32_e32 v9, 31, v8
	v_lshlrev_b64 v[0:1], 13, v[8:9]
	v_add_u32_e32 v8, 64, v8
	v_ashrrev_i32_e32 v9, 31, v8
	s_ashr_i32 s15, s14, 31
	v_lshlrev_b64 v[8:9], 13, v[8:9]
	v_lshl_add_u64 v[0:1], s[4:5], 0, v[0:1]
	s_lshl_b64 s[14:15], s[14:15], 2
	v_lshl_add_u64 v[8:9], s[4:5], 0, v[8:9]
	v_lshl_add_u64 v[0:1], v[0:1], 0, s[14:15]
	v_lshl_add_u64 v[8:9], v[8:9], 0, s[14:15]
	v_lshl_add_u64 v[4:5], v[0:1], 0, v[166:167]
	v_lshl_add_u64 v[12:13], v[8:9], 0, v[166:167]
	global_load_dwordx4 v[0:3], v[4:5], off nt
	s_nop 0
	global_load_dwordx4 v[4:7], v[4:5], off offset:16 nt
	s_nop 0
	global_load_dwordx4 v[8:11], v[12:13], off nt
	s_nop 0
	global_load_dwordx4 v[12:15], v[12:13], off offset:16 nt
	s_branch .LBB0_358

; #define tidx() tidx_(wv_)
; __device__ __forceinline__ void conv_run(const float* __restrict__ src, u16* __restrict__ dst, int K, int N, int mode, int& base,
;                                          float* lds, int gi, int ng, int wv_) {
;   const int nk = K / 128, nn = N / 64, ntiles = nk * nn;
;   const int t = tidx();
;   int lt = (base & 1) ? (ng - 1 - gi) : gi;
;   base += 1;
;   float4 ra[2], rb[2];
;   auto gl = [&](int tile) {
;     const int k0 = (tile % nk) * 128, n0 = (tile / nk) * 64;
; #pragma unroll
;     for (int i = 0; i < 2; ++i) {
;       const int kl = (t >> 3) + 64 * i, c8 = (t & 7) * 8;
;       typedef float f4v __attribute__((ext_vector_type(4)));
;       const f4v* sp = (const f4v*)(src + (size_t)(k0 + kl) * N + n0 + c8);
;       const f4v va = __builtin_nontemporal_load(sp), vb = __builtin_nontemporal_load(sp + 1);
;       ra[i] = make_float4(va.x, va.y, va.z, va.w); rb[i] = make_float4(vb.x, vb.y, vb.z, vb.w);
;     }
;   };
;   __syncthreads();
;   if (lt < ntiles) gl(lt);
.LBB0_1424:
	s_cmp_eq_u32 s12, 4
	s_mov_b64 s[6:7], -1
	s_cbranch_scc0 .LBB0_1436
	v_readlane_b32 s6, v251, 0
	v_readlane_b32 s7, v251, 1
	s_andn2_b64 vcc, exec, s[6:7]
	v_mbcnt_lo_u32_b32 v18, -1, 0
	v_mbcnt_hi_u32_b32 v18, -1, v18
	s_barrier
	s_cbranch_vccnz .LBB0_1430
	v_or_b32_e32 v16, s60, v18
	v_ashrrev_i32_e32 v19, 3, v16
	v_readlane_b32 s10, v252, 7
	s_load_dwordx2 s[6:7], s[0:1], 0x28
	v_lshlrev_b32_e32 v0, 3, v18
	v_add_u32_e32 v8, s10, v19
	v_ashrrev_i32_e32 v9, 31, v8
	v_and_b32_e32 v22, 56, v0
	v_lshlrev_b64 v[0:1], 13, v[8:9]
	v_add_u32_e32 v8, 64, v8
	v_readlane_b32 s10, v252, 8
	v_ashrrev_i32_e32 v9, 31, v8
	s_add_u32 s8, s2, 0x5800000
	v_readlane_b32 s11, v252, 9
	v_lshlrev_b64 v[8:9], 13, v[8:9]
	s_addc_u32 s9, s3, 0
	s_waitcnt lgkmcnt(0)
	v_lshl_add_u64 v[0:1], s[6:7], 0, v[0:1]
	s_lshl_b64 s[10:11], s[10:11], 2
	v_lshl_add_u64 v[8:9], s[6:7], 0, v[8:9]
	v_lshl_add_u64 v[0:1], v[0:1], 0, s[10:11]
	v_lshlrev_b32_e32 v166, 2, v22
	v_lshl_add_u64 v[8:9], v[8:9], 0, s[10:11]
	v_lshl_add_u64 v[4:5], v[0:1], 0, v[166:167]
	v_lshl_add_u64 v[12:13], v[8:9], 0, v[166:167]
	global_load_dwordx4 v[0:3], v[4:5], off nt
	s_nop 0
	global_load_dwordx4 v[4:7], v[4:5], off offset:16 nt
	s_nop 0
	global_load_dwordx4 v[8:11], v[12:13], off nt
	s_nop 0
	global_load_dwordx4 v[12:15], v[12:13], off offset:16 nt
	v_ashrrev_i32_e32 v23, 2, v16
	v_and_b32_e32 v17, 63, v18
	v_bfe_u32 v21, v18, 2, 4
	v_and_b32_e32 v16, -16, v23
	s_movk_i32 s10, 0x104
	v_or_b32_e32 v23, 15, v23
	v_lshlrev_b32_e32 v27, 6, v18
	v_lshlrev_b32_e32 v18, 4, v18
	v_add_u32_e32 v20, 0, v166
	v_lshl_add_u32 v24, v17, 2, 0
	v_mul_lo_u32 v25, v16, s10
	v_mul_lo_u32 v26, v19, s10
	v_mul_lo_u32 v23, v23, s10
	v_and_b32_e32 v27, 0x80, v27
	v_and_b32_e32 v18, 16, v18
	s_lshl_b32 s13, s39, 7
	v_ashrrev_i32_e32 v17, 31, v16
	v_or3_b32 v18, v27, v21, v18
	v_add_u32_e32 v19, s13, v19
	v_add_u32_e32 v20, v20, v26
	v_lshlrev_b32_e32 v166, 2, v22
	v_add_u32_e32 v21, v24, v25
	v_add_u32_e32 v22, v24, v23
	v_readlane_b32 s14, v253, 13
	s_mov_b32 s16, s62
	s_waitcnt vmcnt(0)
	s_branch .LBB0_1428

; #define tidx() tidx_(wv_)
; __device__ __forceinline__ void conv_run(const float* __restrict__ src, u16* __restrict__ dst, int K, int N, int mode, int& base,
;                                          float* lds, int gi, int ng, int wv_) {
;   const int nk = K / 128, nn = N / 64, ntiles = nk * nn;
;   const int t = tidx();
;   int lt = (base & 1) ? (ng - 1 - gi) : gi;
;   base += 1;
;   float4 ra[2], rb[2];
;   auto gl = [&](int tile) {
;     const int k0 = (tile % nk) * 128, n0 = (tile / nk) * 64;
; #pragma unroll
;     for (int i = 0; i < 2; ++i) {
;       const int kl = (t >> 3) + 64 * i, c8 = (t & 7) * 8;
;       typedef float f4v __attribute__((ext_vector_type(4)));
;       const f4v* sp = (const f4v*)(src + (size_t)(k0 + kl) * N + n0 + c8);
;       const f4v va = __builtin_nontemporal_load(sp), vb = __builtin_nontemporal_load(sp + 1);
;       ra[i] = make_float4(va.x, va.y, va.z, va.w); rb[i] = make_float4(vb.x, vb.y, vb.z, vb.w);
;     }
;   };
;   __syncthreads();
;   if (lt < ntiles) gl(lt);
;   while (lt < ntiles) {
;     const int nxt = lt + ng;
;     const int k0 = (lt % nk) * 128, n0 = (lt / nk) * 64;
;     asm volatile("s_waitcnt lgkmcnt(0)\n\ts_barrier" ::: "memory");
; #pragma unroll
;     for (int i = 0; i < 2; ++i) {
;       const int kl = (t >> 3) + 64 * i, c8 = (t & 7) * 8;
;       float* d = lds + kl * 65 + c8;
;       d[0] = ra[i].x; d[1] = ra[i].y; d[2] = ra[i].z; d[3] = ra[i].w; d[4] = rb[i].x; d[5] = rb[i].y; d[6] = rb[i].z; d[7] = rb[i].w;
;     }
;     if (nxt < ntiles) gl(nxt);
;     asm volatile("s_waitcnt lgkmcnt(0)\n\ts_barrier" ::: "memory");
;     const int nl = t & 63, kc = t >> 6;
;     const int n = n0 + nl;
;     const int row = (mode == 0) ? ((n & ~255) + perm256(n & 255)) : ((n >> 7) * 256 + perm128(n & 127) + (mode == 2 ? 128 : 0));
;     float f[16];
; #pragma unroll
;     for (int i = 0; i < 16; ++i) f[i] = lds[(kc * 16 + i) * 65 + nl];
;     uint4* dp = (uint4*)(dst + (size_t)row * K + k0 + kc * 16);
;     dp[0] = pack8(f);
;     dp[1] = pack8(f + 8);
;     lt = nxt;
;   }
.LBB0_1428:
	v_add_u32_e32 v23, 0x4100, v20
	s_add_i32 s15, s16, s39
	s_waitcnt lgkmcnt(0)
	s_barrier
	s_waitcnt vmcnt(5)
	ds_write2_b32 v20, v0, v1 offset1:1
	ds_write2_b32 v20, v2, v3 offset0:2 offset1:3
	s_waitcnt vmcnt(4)
	ds_write2_b32 v20, v4, v5 offset0:4 offset1:5
	ds_write2_b32 v20, v6, v7 offset0:6 offset1:7
	s_waitcnt vmcnt(3)
	ds_write2_b32 v23, v8, v9 offset1:1
	v_add_u32_e32 v23, 0x4108, v20
	s_cmpk_gt_i32 s15, 0x57f
	ds_write2_b32 v23, v10, v11 offset1:1
	v_add_u32_e32 v23, 0x4110, v20
	s_cselect_b64 s[10:11], -1, 0
	s_waitcnt vmcnt(2)
	ds_write2_b32 v23, v12, v13 offset1:1
	v_add_u32_e32 v23, 0x4118, v20
	s_and_b64 vcc, exec, s[10:11]
	ds_write2_b32 v23, v14, v15 offset1:1
	s_cbranch_vccnz .LBB0_1427
	s_mul_hi_i32 s17, s15, 0x2e8ba2e9
	s_lshr_b32 s18, s17, 31
	s_ashr_i32 s17, s17, 3
	s_add_i32 s17, s17, s18
	s_lshl_b32 s18, s17, 6
	s_mulk_i32 s17, 0xea00
	s_add_i32 s17, s17, s14
	v_add_u32_e32 v8, s17, v19
	v_ashrrev_i32_e32 v9, 31, v8
	v_lshlrev_b64 v[0:1], 13, v[8:9]
	v_add_u32_e32 v8, 64, v8
	v_ashrrev_i32_e32 v9, 31, v8
	s_ashr_i32 s19, s18, 31
	v_lshlrev_b64 v[8:9], 13, v[8:9]
	v_lshl_add_u64 v[0:1], s[6:7], 0, v[0:1]
	s_lshl_b64 s[18:19], s[18:19], 2
	v_lshl_add_u64 v[8:9], s[6:7], 0, v[8:9]
	v_lshl_add_u64 v[0:1], v[0:1], 0, s[18:19]
	v_lshl_add_u64 v[8:9], v[8:9], 0, s[18:19]
	v_lshl_add_u64 v[4:5], v[0:1], 0, v[166:167]
	v_lshl_add_u64 v[12:13], v[8:9], 0, v[166:167]
	global_load_dwordx4 v[0:3], v[4:5], off nt
	s_nop 0
	global_load_dwordx4 v[4:7], v[4:5], off offset:16 nt
	s_nop 0
	global_load_dwordx4 v[8:11], v[12:13], off nt
	s_nop 0
	global_load_dwordx4 v[12:15], v[12:13], off offset:16 nt
	s_branch .LBB0_1427
.LBB0_1430:
	v_readlane_b32 s6, v252, 10
	v_readlane_b32 s7, v252, 11
	s_andn2_b64 vcc, exec, s[6:7]
	v_mbcnt_lo_u32_b32 v18, -1, 0
	v_mbcnt_hi_u32_b32 v18, -1, v18
	s_barrier
	s_cbranch_vccnz .LBB0_1435
	s_load_dwordx2 s[6:7], s[0:1], 0x70
	v_or_b32_e32 v16, s60, v18
	v_ashrrev_i32_e32 v19, 3, v16
	s_waitcnt vmcnt(5)
	v_lshlrev_b32_e32 v0, 3, v18
	v_readlane_b32 s10, v252, 12
	v_and_b32_e32 v22, 56, v0
	s_waitcnt lgkmcnt(0)
	v_mov_b64_e32 v[0:1], s[6:7]
	s_waitcnt vmcnt(3)
	v_add_u32_e32 v8, s10, v19
	s_movk_i32 s13, 0x6700
	v_mad_i64_i32 v[0:1], s[10:11], v8, s13, v[0:1]
	v_readlane_b32 s10, v252, 13
	s_add_u32 s8, s2, 0x8d00000
	v_readlane_b32 s11, v252, 14
	v_add_u32_e32 v10, 64, v8
	v_mov_b64_e32 v[8:9], s[6:7]
	s_addc_u32 s9, s3, 0
	s_lshl_b64 s[10:11], s[10:11], 2
	v_mad_i64_i32 v[8:9], s[14:15], v10, s13, v[8:9]
	v_lshl_add_u64 v[0:1], v[0:1], 0, s[10:11]
	v_lshlrev_b32_e32 v166, 2, v22
	v_lshl_add_u64 v[8:9], v[8:9], 0, s[10:11]
	v_lshl_add_u64 v[4:5], v[0:1], 0, v[166:167]
	s_waitcnt vmcnt(2)
	v_lshl_add_u64 v[12:13], v[8:9], 0, v[166:167]
	global_load_dwordx4 v[0:3], v[4:5], off nt
	s_nop 0
	global_load_dwordx4 v[4:7], v[4:5], off offset:16 nt
	s_nop 0
	global_load_dwordx4 v[8:11], v[12:13], off nt
	s_nop 0
	global_load_dwordx4 v[12:15], v[12:13], off offset:16 nt
	v_ashrrev_i32_e32 v23, 2, v16
	v_and_b32_e32 v17, 63, v18
	v_bfe_u32 v21, v18, 2, 4
	v_and_b32_e32 v16, -16, v23
	s_movk_i32 s10, 0x104
	v_or_b32_e32 v23, 15, v23
	v_lshlrev_b32_e32 v27, 6, v18
	v_lshlrev_b32_e32 v18, 4, v18
	v_add_u32_e32 v20, 0, v166
	v_lshl_add_u32 v24, v17, 2, 0
	v_mul_lo_u32 v25, v16, s10
	v_mul_lo_u32 v26, v19, s10
	v_mul_lo_u32 v23, v23, s10
	v_and_b32_e32 v27, 0x80, v27
	v_and_b32_e32 v18, 16, v18
	v_readlane_b32 s16, v252, 24
	s_lshl_b32 s14, s39, 7
	v_ashrrev_i32_e32 v17, 31, v16
	v_or3_b32 v18, v27, v21, v18
	s_lshl_b32 s13, s16, 7
	v_add_u32_e32 v19, s14, v19
	v_add_u32_e32 v20, v20, v26
	v_lshlrev_b32_e32 v166, 2, v22
	v_add_u32_e32 v21, v24, v25
	v_add_u32_e32 v22, v24, v23
	s_waitcnt vmcnt(0)
	s_branch .LBB0_1433

; __device__ __forceinline__ void conv_run(const float* __restrict__ src, u16* __restrict__ dst, int K, int N, int mode, int& base,
;                                          float* lds, int gi, int ng, int wv_) {
;     ...
;   while (lt < ntiles) {
;     const int nxt = lt + ng;
;     const int k0 = (lt % nk) * 128, n0 = (lt / nk) * 64;
;     asm volatile("s_waitcnt lgkmcnt(0)\n\ts_barrier" ::: "memory");
; #pragma unroll
;     for (int i = 0; i < 2; ++i) {
;       const int kl = (t >> 3) + 64 * i, c8 = (t & 7) * 8;
;       float* d = lds + kl * 65 + c8;
;       d[0] = ra[i].x; d[1] = ra[i].y; d[2] = ra[i].z; d[3] = ra[i].w; d[4] = rb[i].x; d[5] = rb[i].y; d[6] = rb[i].z; d[7] = rb[i].w;
;     }
;     if (nxt < ntiles) gl(nxt);
;     asm volatile("s_waitcnt lgkmcnt(0)\n\ts_barrier" ::: "memory");
;     const int nl = t & 63, kc = t >> 6;
;     const int n = n0 + nl;
;     const int row = (mode == 0) ? ((n & ~255) + perm256(n & 255)) : ((n >> 7) * 256 + perm128(n & 127) + (mode == 2 ? 128 : 0));
;     float f[16];
; #pragma unroll
;     for (int i = 0; i < 16; ++i) f[i] = lds[(kc * 16 + i) * 65 + nl];
;     uint4* dp = (uint4*)(dst + (size_t)row * K + k0 + kc * 16);
;     dp[0] = pack8(f);
;     dp[1] = pack8(f + 8);
;     lt = nxt;
;   }
.LBB0_1433:
	v_add_u32_e32 v23, 0x4100, v20
	s_add_i32 s15, s16, s39
	s_waitcnt lgkmcnt(0)
	s_barrier
	s_waitcnt vmcnt(5)
	ds_write2_b32 v20, v0, v1 offset1:1
	ds_write2_b32 v20, v2, v3 offset0:2 offset1:3
	s_waitcnt vmcnt(4)
	ds_write2_b32 v20, v4, v5 offset0:4 offset1:5
	ds_write2_b32 v20, v6, v7 offset0:6 offset1:7
	s_waitcnt vmcnt(3)
	ds_write2_b32 v23, v8, v9 offset1:1
	v_add_u32_e32 v23, 0x4108, v20
	s_cmpk_gt_i32 s15, 0x66f
	ds_write2_b32 v23, v10, v11 offset1:1
	v_add_u32_e32 v23, 0x4110, v20
	s_cselect_b64 s[10:11], -1, 0
	s_waitcnt vmcnt(2)
	ds_write2_b32 v23, v12, v13 offset1:1
	v_add_u32_e32 v23, 0x4118, v20
	s_and_b64 vcc, exec, s[10:11]
	ds_write2_b32 v23, v14, v15 offset1:1
	s_cbranch_vccnz .LBB0_1432
	s_ashr_i32 s17, s15, 31
	s_lshr_b32 s17, s17, 28
	s_add_i32 s17, s15, s17
	s_ashr_i32 s17, s17, 4
	s_lshl_b32 s18, s17, 6
	v_add_u32_e32 v0, s13, v19
	s_lshl_b32 s17, s17, 11
	v_subrev_u32_e32 v10, s17, v0
	v_mov_b64_e32 v[8:9], s[6:7]
	s_movk_i32 s17, 0x6700
	s_ashr_i32 s19, s18, 31
	v_mad_i64_i32 v[0:1], s[20:21], v10, s17, v[8:9]
	v_add_u32_e32 v10, 64, v10
	s_lshl_b64 s[18:19], s[18:19], 2
	v_mad_i64_i32 v[8:9], s[20:21], v10, s17, v[8:9]
	v_lshl_add_u64 v[0:1], v[0:1], 0, s[18:19]
	v_lshl_add_u64 v[8:9], v[8:9], 0, s[18:19]
	v_lshl_add_u64 v[4:5], v[0:1], 0, v[166:167]
	v_lshl_add_u64 v[12:13], v[8:9], 0, v[166:167]
	global_load_dwordx4 v[0:3], v[4:5], off nt
	s_nop 0
	global_load_dwordx4 v[4:7], v[4:5], off offset:16 nt
	s_nop 0
	global_load_dwordx4 v[8:11], v[12:13], off nt
	s_nop 0
	global_load_dwordx4 v[12:15], v[12:13], off offset:16 nt
	v_readlane_b32 s20, v253, 44
	v_readlane_b32 s21, v253, 45
	s_branch .LBB0_1432

; #define tidx() tidx_(wv_)
; __device__ __forceinline__ void conv_run(const float* __restrict__ src, u16* __restrict__ dst, int K, int N, int mode, int& base,
;                                          float* lds, int gi, int ng, int wv_) {
;   const int nk = K / 128, nn = N / 64, ntiles = nk * nn;
;   const int t = tidx();
;   int lt = (base & 1) ? (ng - 1 - gi) : gi;
;   base += 1;
;   float4 ra[2], rb[2];
;   auto gl = [&](int tile) {
;     const int k0 = (tile % nk) * 128, n0 = (tile / nk) * 64;
; #pragma unroll
;     for (int i = 0; i < 2; ++i) {
;       const int kl = (t >> 3) + 64 * i, c8 = (t & 7) * 8;
;       typedef float f4v __attribute__((ext_vector_type(4)));
;       const f4v* sp = (const f4v*)(src + (size_t)(k0 + kl) * N + n0 + c8);
;       const f4v va = __builtin_nontemporal_load(sp), vb = __builtin_nontemporal_load(sp + 1);
;       ra[i] = make_float4(va.x, va.y, va.z, va.w); rb[i] = make_float4(vb.x, vb.y, vb.z, vb.w);
;     }
;   };
;   __syncthreads();
;   if (lt < ntiles) gl(lt);
.LBB0_1438:
	v_readlane_b32 s8, v251, 0
	v_readlane_b32 s9, v251, 1
	s_add_u32 s6, s2, 0xb540000
	s_addc_u32 s7, s3, 0
	s_waitcnt vmcnt(5)
	v_cndmask_b32_e64 v0, 0, 1, s[8:9]
	v_cmp_ne_u32_e64 s[4:5], 1, v0
	s_andn2_b64 vcc, exec, s[8:9]
	v_mbcnt_lo_u32_b32 v16, -1, 0
	v_mbcnt_hi_u32_b32 v16, -1, v16
	s_barrier
	s_cbranch_vccnz .LBB0_1443
	s_load_dwordx2 s[8:9], s[0:1], 0x40
	v_or_b32_e32 v17, s60, v16
	v_ashrrev_i32_e32 v20, 3, v17
	v_readlane_b32 s10, v252, 19
	v_lshlrev_b32_e32 v0, 3, v16
	s_waitcnt lgkmcnt(0)
	s_add_u32 s8, s8, 0x2c00000
	s_addc_u32 s9, s9, 0
	s_waitcnt vmcnt(3)
	v_add_u32_e32 v10, s10, v20
	v_mov_b64_e32 v[8:9], s[8:9]
	s_movk_i32 s13, 0x5800
	v_and_b32_e32 v22, 56, v0
	v_mad_i64_i32 v[0:1], s[10:11], v10, s13, v[8:9]
	v_readlane_b32 s10, v252, 20
	v_readlane_b32 s11, v252, 21
	v_add_u32_e32 v10, 64, v10
	s_lshl_b64 s[10:11], s[10:11], 2
	v_mad_i64_i32 v[8:9], s[14:15], v10, s13, v[8:9]
	v_lshl_add_u64 v[0:1], v[0:1], 0, s[10:11]
	v_lshlrev_b32_e32 v166, 2, v22
	v_lshl_add_u64 v[8:9], v[8:9], 0, s[10:11]
	v_lshl_add_u64 v[4:5], v[0:1], 0, v[166:167]
	s_waitcnt vmcnt(2)
	v_lshl_add_u64 v[12:13], v[8:9], 0, v[166:167]
	global_load_dwordx4 v[0:3], v[4:5], off nt
	s_nop 0
	global_load_dwordx4 v[4:7], v[4:5], off offset:16 nt
	s_nop 0
	global_load_dwordx4 v[8:11], v[12:13], off nt
	s_nop 0
	global_load_dwordx4 v[12:15], v[12:13], off offset:16 nt
	v_and_b32_e32 v18, 63, v16
	v_lshlrev_b32_e32 v19, 4, v16
	v_bfe_u32 v16, v16, 1, 4
	v_ashrrev_i32_e32 v23, 2, v17
	v_and_or_b32 v19, v19, 16, v16
	v_and_b32_e32 v16, -16, v23
	s_movk_i32 s10, 0x104
	v_or_b32_e32 v23, 15, v23
	v_add_u32_e32 v21, 0, v166
	v_lshl_add_u32 v24, v18, 2, 0
	v_mul_lo_u32 v25, v16, s10
	v_mul_lo_u32 v26, v20, s10
	v_mul_lo_u32 v23, v23, s10
	s_lshl_b32 s13, s39, 7
	v_ashrrev_i32_e32 v17, 31, v16
	v_add_u32_e32 v20, s13, v20
	v_add_u32_e32 v21, v21, v26
	v_lshlrev_b32_e32 v166, 2, v22
	v_add_u32_e32 v22, v24, v25
	v_add_u32_e32 v23, v24, v23
	v_readlane_b32 s14, v253, 13
	s_mov_b32 s16, s62
	s_waitcnt vmcnt(0)
	s_branch .LBB0_1441

; #define tidx() tidx_(wv_)
; __device__ __forceinline__ void conv_run(const float* __restrict__ src, u16* __restrict__ dst, int K, int N, int mode, int& base,
;                                          float* lds, int gi, int ng, int wv_) {
;   const int nk = K / 128, nn = N / 64, ntiles = nk * nn;
;   const int t = tidx();
;   int lt = (base & 1) ? (ng - 1 - gi) : gi;
;   base += 1;
;   float4 ra[2], rb[2];
;   auto gl = [&](int tile) {
;     const int k0 = (tile % nk) * 128, n0 = (tile / nk) * 64;
; #pragma unroll
;     for (int i = 0; i < 2; ++i) {
;       const int kl = (t >> 3) + 64 * i, c8 = (t & 7) * 8;
;       typedef float f4v __attribute__((ext_vector_type(4)));
;       const f4v* sp = (const f4v*)(src + (size_t)(k0 + kl) * N + n0 + c8);
;       const f4v va = __builtin_nontemporal_load(sp), vb = __builtin_nontemporal_load(sp + 1);
;       ra[i] = make_float4(va.x, va.y, va.z, va.w); rb[i] = make_float4(vb.x, vb.y, vb.z, vb.w);
;     }
;   };
;   __syncthreads();
;   if (lt < ntiles) gl(lt);
;   while (lt < ntiles) {
;     const int nxt = lt + ng;
;     const int k0 = (lt % nk) * 128, n0 = (lt / nk) * 64;
;     asm volatile("s_waitcnt lgkmcnt(0)\n\ts_barrier" ::: "memory");
; #pragma unroll
;     for (int i = 0; i < 2; ++i) {
;       const int kl = (t >> 3) + 64 * i, c8 = (t & 7) * 8;
;       float* d = lds + kl * 65 + c8;
;       d[0] = ra[i].x; d[1] = ra[i].y; d[2] = ra[i].z; d[3] = ra[i].w; d[4] = rb[i].x; d[5] = rb[i].y; d[6] = rb[i].z; d[7] = rb[i].w;
;     }
;     if (nxt < ntiles) gl(nxt);
;     asm volatile("s_waitcnt lgkmcnt(0)\n\ts_barrier" ::: "memory");
;     const int nl = t & 63, kc = t >> 6;
;     const int n = n0 + nl;
;     const int row = (mode == 0) ? ((n & ~255) + perm256(n & 255)) : ((n >> 7) * 256 + perm128(n & 127) + (mode == 2 ? 128 : 0));
;     float f[16];
; #pragma unroll
;     for (int i = 0; i < 16; ++i) f[i] = lds[(kc * 16 + i) * 65 + nl];
;     uint4* dp = (uint4*)(dst + (size_t)row * K + k0 + kc * 16);
;     dp[0] = pack8(f);
;     dp[1] = pack8(f + 8);
;     lt = nxt;
;   }
.LBB0_1441:
	s_nop 0
	v_add_u32_e32 v24, 0x4100, v21
	s_add_i32 s15, s16, s39
	s_waitcnt lgkmcnt(0)
	s_barrier
	s_waitcnt vmcnt(5)
	ds_write2_b32 v21, v0, v1 offset1:1
	ds_write2_b32 v21, v2, v3 offset0:2 offset1:3
	s_waitcnt vmcnt(4)
	ds_write2_b32 v21, v4, v5 offset0:4 offset1:5
	ds_write2_b32 v21, v6, v7 offset0:6 offset1:7
	s_waitcnt vmcnt(3)
	ds_write2_b32 v24, v8, v9 offset1:1
	v_add_u32_e32 v24, 0x4108, v21
	s_cmpk_gt_i32 s15, 0x57f
	ds_write2_b32 v24, v10, v11 offset1:1
	v_add_u32_e32 v24, 0x4110, v21
	s_cselect_b64 s[10:11], -1, 0
	s_waitcnt vmcnt(2)
	ds_write2_b32 v24, v12, v13 offset1:1
	v_add_u32_e32 v24, 0x4118, v21
	s_and_b64 vcc, exec, s[10:11]
	ds_write2_b32 v24, v14, v15 offset1:1
	s_cbranch_vccnz .LBB0_1440
	s_ashr_i32 s17, s15, 31
	s_lshr_b32 s17, s17, 28
	s_add_i32 s17, s15, s17
	s_ashr_i32 s17, s17, 4
	s_lshl_b32 s18, s17, 6
	v_add_u32_e32 v0, s14, v20
	s_lshl_b32 s17, s17, 11
	v_subrev_u32_e32 v10, s17, v0
	v_mov_b64_e32 v[8:9], s[8:9]
	s_movk_i32 s17, 0x5800
	s_ashr_i32 s19, s18, 31
	v_mad_i64_i32 v[0:1], s[20:21], v10, s17, v[8:9]
	v_add_u32_e32 v10, 64, v10
	s_lshl_b64 s[18:19], s[18:19], 2
	v_mad_i64_i32 v[8:9], s[20:21], v10, s17, v[8:9]
	v_lshl_add_u64 v[0:1], v[0:1], 0, s[18:19]
	v_lshl_add_u64 v[8:9], v[8:9], 0, s[18:19]
	v_lshl_add_u64 v[4:5], v[0:1], 0, v[166:167]
	v_lshl_add_u64 v[12:13], v[8:9], 0, v[166:167]
	global_load_dwordx4 v[0:3], v[4:5], off nt
	s_nop 0
	global_load_dwordx4 v[4:7], v[4:5], off offset:16 nt
	s_nop 0
	global_load_dwordx4 v[8:11], v[12:13], off nt
	s_nop 0
	global_load_dwordx4 v[12:15], v[12:13], off offset:16 nt
	v_readlane_b32 s20, v253, 44
	v_readlane_b32 s21, v253, 45
	s_branch .LBB0_1440
.LBB0_1443:
	v_readlane_b32 s8, v252, 25
	v_readlane_b32 s9, v252, 26
	s_andn2_b64 vcc, exec, s[8:9]
	v_mbcnt_lo_u32_b32 v16, -1, 0
	v_mbcnt_hi_u32_b32 v16, -1, v16
	s_barrier
	s_cbranch_vccnz .LBB0_1448
	s_load_dwordx2 s[8:9], s[0:1], 0x48
	v_or_b32_e32 v17, s60, v16
	v_ashrrev_i32_e32 v20, 3, v17
	v_readlane_b32 s10, v252, 12
	s_waitcnt vmcnt(5)
	v_lshlrev_b32_e32 v0, 3, v16
	s_waitcnt lgkmcnt(0)
	s_add_u32 s8, s8, 0x2c00000
	s_addc_u32 s9, s9, 0
	s_waitcnt vmcnt(3)
	v_add_u32_e32 v10, s10, v20
	v_mov_b64_e32 v[8:9], s[8:9]
	s_movk_i32 s13, 0x5800
	v_and_b32_e32 v22, 56, v0
	v_mad_i64_i32 v[0:1], s[10:11], v10, s13, v[8:9]
	v_readlane_b32 s10, v252, 13
	v_readlane_b32 s11, v252, 14
	v_add_u32_e32 v10, 64, v10
	s_lshl_b64 s[10:11], s[10:11], 2
	v_mad_i64_i32 v[8:9], s[14:15], v10, s13, v[8:9]
	v_lshl_add_u64 v[0:1], v[0:1], 0, s[10:11]
	v_lshlrev_b32_e32 v166, 2, v22
	v_lshl_add_u64 v[8:9], v[8:9], 0, s[10:11]
	v_lshl_add_u64 v[4:5], v[0:1], 0, v[166:167]
	s_waitcnt vmcnt(2)
	v_lshl_add_u64 v[12:13], v[8:9], 0, v[166:167]
	global_load_dwordx4 v[0:3], v[4:5], off nt
	s_nop 0
	global_load_dwordx4 v[4:7], v[4:5], off offset:16 nt
	s_nop 0
	global_load_dwordx4 v[8:11], v[12:13], off nt
	s_nop 0
	global_load_dwordx4 v[12:15], v[12:13], off offset:16 nt
	v_and_b32_e32 v18, 63, v16
	v_lshrrev_b32_e32 v19, 1, v16
	v_lshlrev_b32_e32 v16, 4, v16
	v_and_b32_e32 v16, 16, v16
	v_ashrrev_i32_e32 v23, 2, v17
	v_and_or_b32 v19, v19, 15, v16
	v_and_b32_e32 v16, -16, v23
	s_movk_i32 s10, 0x104
	v_or_b32_e32 v23, 15, v23
	v_add_u32_e32 v21, 0, v166
	v_lshl_add_u32 v24, v18, 2, 0
	v_mul_lo_u32 v25, v16, s10
	v_mul_lo_u32 v26, v20, s10
	v_mul_lo_u32 v23, v23, s10
	v_readlane_b32 s16, v252, 24
	s_lshl_b32 s14, s39, 7
	v_ashrrev_i32_e32 v17, 31, v16
	s_lshl_b32 s13, s16, 7
	v_add_u32_e32 v20, s14, v20
	v_add_u32_e32 v21, v21, v26
	v_lshlrev_b32_e32 v166, 2, v22
	v_add_u32_e32 v22, v24, v25
	v_add_u32_e32 v23, v24, v23
	s_waitcnt vmcnt(0)
	s_branch .LBB0_1446

; #define tidx() tidx_(wv_)
; __device__ __forceinline__ void conv_run(const float* __restrict__ src, u16* __restrict__ dst, int K, int N, int mode, int& base,
;                                          float* lds, int gi, int ng, int wv_) {
;   const int nk = K / 128, nn = N / 64, ntiles = nk * nn;
;   const int t = tidx();
;   int lt = (base & 1) ? (ng - 1 - gi) : gi;
;   base += 1;
;   float4 ra[2], rb[2];
;   auto gl = [&](int tile) {
;     const int k0 = (tile % nk) * 128, n0 = (tile / nk) * 64;
; #pragma unroll
;     for (int i = 0; i < 2; ++i) {
;       const int kl = (t >> 3) + 64 * i, c8 = (t & 7) * 8;
;       typedef float f4v __attribute__((ext_vector_type(4)));
;       const f4v* sp = (const f4v*)(src + (size_t)(k0 + kl) * N + n0 + c8);
;       const f4v va = __builtin_nontemporal_load(sp), vb = __builtin_nontemporal_load(sp + 1);
;       ra[i] = make_float4(va.x, va.y, va.z, va.w); rb[i] = make_float4(vb.x, vb.y, vb.z, vb.w);
;     }
;   };
;   __syncthreads();
;   if (lt < ntiles) gl(lt);
;   while (lt < ntiles) {
;     const int nxt = lt + ng;
;     const int k0 = (lt % nk) * 128, n0 = (lt / nk) * 64;
;     asm volatile("s_waitcnt lgkmcnt(0)\n\ts_barrier" ::: "memory");
; #pragma unroll
;     for (int i = 0; i < 2; ++i) {
;       const int kl = (t >> 3) + 64 * i, c8 = (t & 7) * 8;
;       float* d = lds + kl * 65 + c8;
;       d[0] = ra[i].x; d[1] = ra[i].y; d[2] = ra[i].z; d[3] = ra[i].w; d[4] = rb[i].x; d[5] = rb[i].y; d[6] = rb[i].z; d[7] = rb[i].w;
;     }
;     if (nxt < ntiles) gl(nxt);
;     asm volatile("s_waitcnt lgkmcnt(0)\n\ts_barrier" ::: "memory");
;     const int nl = t & 63, kc = t >> 6;
;     const int n = n0 + nl;
;     const int row = (mode == 0) ? ((n & ~255) + perm256(n & 255)) : ((n >> 7) * 256 + perm128(n & 127) + (mode == 2 ? 128 : 0));
;     float f[16];
; #pragma unroll
;     for (int i = 0; i < 16; ++i) f[i] = lds[(kc * 16 + i) * 65 + nl];
;     uint4* dp = (uint4*)(dst + (size_t)row * K + k0 + kc * 16);
;     dp[0] = pack8(f);
;     dp[1] = pack8(f + 8);
;     lt = nxt;
;   }
.LBB0_1446:
	s_nop 0
	v_add_u32_e32 v24, 0x4100, v21
	s_add_i32 s15, s16, s39
	s_waitcnt lgkmcnt(0)
	s_barrier
	s_waitcnt vmcnt(5)
	ds_write2_b32 v21, v0, v1 offset1:1
	ds_write2_b32 v21, v2, v3 offset0:2 offset1:3
	s_waitcnt vmcnt(4)
	ds_write2_b32 v21, v4, v5 offset0:4 offset1:5
	ds_write2_b32 v21, v6, v7 offset0:6 offset1:7
	s_waitcnt vmcnt(3)
	ds_write2_b32 v24, v8, v9 offset1:1
	v_add_u32_e32 v24, 0x4108, v21
	s_cmpk_gt_i32 s15, 0x57f
	ds_write2_b32 v24, v10, v11 offset1:1
	v_add_u32_e32 v24, 0x4110, v21
	s_cselect_b64 s[10:11], -1, 0
	s_waitcnt vmcnt(2)
	ds_write2_b32 v24, v12, v13 offset1:1
	v_add_u32_e32 v24, 0x4118, v21
	s_and_b64 vcc, exec, s[10:11]
	ds_write2_b32 v24, v14, v15 offset1:1
	s_cbranch_vccnz .LBB0_1445
	s_ashr_i32 s17, s15, 31
	s_lshr_b32 s17, s17, 28
	s_add_i32 s17, s15, s17
	s_ashr_i32 s17, s17, 4
	s_lshl_b32 s18, s17, 6
	v_add_u32_e32 v0, s13, v20
	s_lshl_b32 s17, s17, 11
	v_subrev_u32_e32 v10, s17, v0
	v_mov_b64_e32 v[8:9], s[8:9]
	s_movk_i32 s17, 0x5800
	s_ashr_i32 s19, s18, 31
	v_mad_i64_i32 v[0:1], s[20:21], v10, s17, v[8:9]
	v_add_u32_e32 v10, 64, v10
	s_lshl_b64 s[18:19], s[18:19], 2
	v_mad_i64_i32 v[8:9], s[20:21], v10, s17, v[8:9]
	v_lshl_add_u64 v[0:1], v[0:1], 0, s[18:19]
	v_lshl_add_u64 v[8:9], v[8:9], 0, s[18:19]
	v_lshl_add_u64 v[4:5], v[0:1], 0, v[166:167]
	v_lshl_add_u64 v[12:13], v[8:9], 0, v[166:167]
	global_load_dwordx4 v[0:3], v[4:5], off nt
	s_nop 0
	global_load_dwordx4 v[4:7], v[4:5], off offset:16 nt
	s_nop 0
	global_load_dwordx4 v[8:11], v[12:13], off nt
	s_nop 0
	global_load_dwordx4 v[12:15], v[12:13], off offset:16 nt
	v_readlane_b32 s20, v253, 44
	v_readlane_b32 s21, v253, 45
	s_branch .LBB0_1445
.LBB0_1448:
	s_and_b64 vcc, exec, s[4:5]
	v_mbcnt_lo_u32_b32 v18, -1, 0
	v_mbcnt_hi_u32_b32 v18, -1, v18
	s_barrier
	s_cbranch_vccnz .LBB0_1453
	s_load_dwordx2 s[4:5], s[0:1], 0x50
	v_or_b32_e32 v16, s60, v18
	v_ashrrev_i32_e32 v19, 3, v16
	v_readlane_b32 s8, v252, 7
	s_waitcnt vmcnt(5)
	v_lshlrev_b32_e32 v0, 3, v18
	v_and_b32_e32 v22, 56, v0
	s_waitcnt vmcnt(3)
	v_add_u32_e32 v8, s8, v19
	v_ashrrev_i32_e32 v9, 31, v8
	s_waitcnt lgkmcnt(0)
	s_add_u32 s4, s4, 0x2c00000
	v_lshlrev_b64 v[0:1], 13, v[8:9]
	v_add_u32_e32 v8, 64, v8
	s_addc_u32 s5, s5, 0
	v_readlane_b32 s8, v252, 8
	v_ashrrev_i32_e32 v9, 31, v8
	s_add_u32 s6, s2, 0xe140000
	v_readlane_b32 s9, v252, 9
	v_lshlrev_b64 v[8:9], 13, v[8:9]
	s_addc_u32 s7, s3, 0
	v_lshl_add_u64 v[0:1], s[4:5], 0, v[0:1]
	s_lshl_b64 s[8:9], s[8:9], 2
	v_lshl_add_u64 v[8:9], s[4:5], 0, v[8:9]
	v_lshl_add_u64 v[0:1], v[0:1], 0, s[8:9]
	v_lshlrev_b32_e32 v166, 2, v22
	v_lshl_add_u64 v[8:9], v[8:9], 0, s[8:9]
	v_lshl_add_u64 v[4:5], v[0:1], 0, v[166:167]
	s_waitcnt vmcnt(2)
	v_lshl_add_u64 v[12:13], v[8:9], 0, v[166:167]
	global_load_dwordx4 v[0:3], v[4:5], off nt
	s_nop 0
	global_load_dwordx4 v[4:7], v[4:5], off offset:16 nt
	s_nop 0
	global_load_dwordx4 v[8:11], v[12:13], off nt
	s_nop 0
	global_load_dwordx4 v[12:15], v[12:13], off offset:16 nt
	v_ashrrev_i32_e32 v23, 2, v16
	v_and_b32_e32 v17, 63, v18
	v_bfe_u32 v21, v18, 2, 4
	v_and_b32_e32 v16, -16, v23
	s_movk_i32 s8, 0x104
	v_or_b32_e32 v23, 15, v23
	v_lshlrev_b32_e32 v27, 6, v18
	v_lshlrev_b32_e32 v18, 4, v18
	v_add_u32_e32 v20, 0, v166
	v_lshl_add_u32 v24, v17, 2, 0
	v_mul_lo_u32 v25, v16, s8
	v_mul_lo_u32 v26, v19, s8
	v_mul_lo_u32 v23, v23, s8
	v_and_b32_e32 v27, 0x80, v27
	v_and_b32_e32 v18, 16, v18
	s_lshl_b32 s10, s39, 7
	v_ashrrev_i32_e32 v17, 31, v16
	v_or3_b32 v18, v27, v21, v18
	v_add_u32_e32 v19, s10, v19
	v_add_u32_e32 v20, v20, v26
	v_lshlrev_b32_e32 v166, 2, v22
	v_add_u32_e32 v21, v24, v25
	v_add_u32_e32 v22, v24, v23
	v_readlane_b32 s11, v253, 13
	s_mov_b32 s14, s62
	s_waitcnt vmcnt(0)
	s_branch .LBB0_1451

; __device__ __forceinline__ void conv_run(const float* __restrict__ src, u16* __restrict__ dst, int K, int N, int mode, int& base,
;                                          float* lds, int gi, int ng, int wv_) {
;     ...
;   while (lt < ntiles) {
;     const int nxt = lt + ng;
;     const int k0 = (lt % nk) * 128, n0 = (lt / nk) * 64;
;     asm volatile("s_waitcnt lgkmcnt(0)\n\ts_barrier" ::: "memory");
; #pragma unroll
;     for (int i = 0; i < 2; ++i) {
;       const int kl = (t >> 3) + 64 * i, c8 = (t & 7) * 8;
;       float* d = lds + kl * 65 + c8;
;       d[0] = ra[i].x; d[1] = ra[i].y; d[2] = ra[i].z; d[3] = ra[i].w; d[4] = rb[i].x; d[5] = rb[i].y; d[6] = rb[i].z; d[7] = rb[i].w;
;     }
;     if (nxt < ntiles) gl(nxt);
;     asm volatile("s_waitcnt lgkmcnt(0)\n\ts_barrier" ::: "memory");
;     const int nl = t & 63, kc = t >> 6;
;     const int n = n0 + nl;
;     const int row = (mode == 0) ? ((n & ~255) + perm256(n & 255)) : ((n >> 7) * 256 + perm128(n & 127) + (mode == 2 ? 128 : 0));
;     float f[16];
; #pragma unroll
;     for (int i = 0; i < 16; ++i) f[i] = lds[(kc * 16 + i) * 65 + nl];
;     uint4* dp = (uint4*)(dst + (size_t)row * K + k0 + kc * 16);
;     dp[0] = pack8(f);
;     dp[1] = pack8(f + 8);
;     lt = nxt;
;   }
.LBB0_1451:
	v_add_u32_e32 v23, 0x4100, v20
	s_add_i32 s13, s14, s39
	s_waitcnt lgkmcnt(0)
	s_barrier
	s_waitcnt vmcnt(5)
	ds_write2_b32 v20, v0, v1 offset1:1
	ds_write2_b32 v20, v2, v3 offset0:2 offset1:3
	s_waitcnt vmcnt(4)
	ds_write2_b32 v20, v4, v5 offset0:4 offset1:5
	ds_write2_b32 v20, v6, v7 offset0:6 offset1:7
	s_waitcnt vmcnt(3)
	ds_write2_b32 v23, v8, v9 offset1:1
	v_add_u32_e32 v23, 0x4108, v20
	s_cmpk_gt_i32 s13, 0x57f
	ds_write2_b32 v23, v10, v11 offset1:1
	v_add_u32_e32 v23, 0x4110, v20
	s_cselect_b64 s[8:9], -1, 0
	s_waitcnt vmcnt(2)
	ds_write2_b32 v23, v12, v13 offset1:1
	v_add_u32_e32 v23, 0x4118, v20
	s_and_b64 vcc, exec, s[8:9]
	ds_write2_b32 v23, v14, v15 offset1:1
	s_cbranch_vccnz .LBB0_1450
	s_mul_hi_i32 s15, s13, 0x2e8ba2e9
	s_lshr_b32 s16, s15, 31
	s_ashr_i32 s15, s15, 3
	s_add_i32 s15, s15, s16
	s_lshl_b32 s16, s15, 6
	s_mulk_i32 s15, 0xea00
	s_add_i32 s15, s15, s11
	v_add_u32_e32 v8, s15, v19
	v_ashrrev_i32_e32 v9, 31, v8
	v_lshlrev_b64 v[0:1], 13, v[8:9]
	v_add_u32_e32 v8, 64, v8
	v_ashrrev_i32_e32 v9, 31, v8
	s_ashr_i32 s17, s16, 31
	v_lshlrev_b64 v[8:9], 13, v[8:9]
	v_lshl_add_u64 v[0:1], s[4:5], 0, v[0:1]
	s_lshl_b64 s[16:17], s[16:17], 2
	v_lshl_add_u64 v[8:9], s[4:5], 0, v[8:9]
	v_lshl_add_u64 v[0:1], v[0:1], 0, s[16:17]
	v_lshl_add_u64 v[8:9], v[8:9], 0, s[16:17]
	v_lshl_add_u64 v[4:5], v[0:1], 0, v[166:167]
	v_lshl_add_u64 v[12:13], v[8:9], 0, v[166:167]
	global_load_dwordx4 v[0:3], v[4:5], off nt
	s_nop 0
	global_load_dwordx4 v[4:7], v[4:5], off offset:16 nt
	s_nop 0
	global_load_dwordx4 v[8:11], v[12:13], off nt
	s_nop 0
	global_load_dwordx4 v[12:15], v[12:13], off offset:16 nt
	s_branch .LBB0_1450

; #define tidx() tidx_(wv_)
; __device__ __forceinline__ void conv_run(const float* __restrict__ src, u16* __restrict__ dst, int K, int N, int mode, int& base,
;                                          float* lds, int gi, int ng, int wv_) {
;   const int nk = K / 128, nn = N / 64, ntiles = nk * nn;
;   const int t = tidx();
;   int lt = (base & 1) ? (ng - 1 - gi) : gi;
;   base += 1;
;   float4 ra[2], rb[2];
;   auto gl = [&](int tile) {
;     const int k0 = (tile % nk) * 128, n0 = (tile / nk) * 64;
; #pragma unroll
;     for (int i = 0; i < 2; ++i) {
;       const int kl = (t >> 3) + 64 * i, c8 = (t & 7) * 8;
;       typedef float f4v __attribute__((ext_vector_type(4)));
;       const f4v* sp = (const f4v*)(src + (size_t)(k0 + kl) * N + n0 + c8);
;       const f4v va = __builtin_nontemporal_load(sp), vb = __builtin_nontemporal_load(sp + 1);
;       ra[i] = make_float4(va.x, va.y, va.z, va.w); rb[i] = make_float4(vb.x, vb.y, vb.z, vb.w);
;     }
;   };
;   __syncthreads();
;   if (lt < ntiles) gl(lt);
.LBB0_1454:
	v_readlane_b32 s4, v251, 2
	v_readlane_b32 s5, v251, 3
	s_andn2_b64 vcc, exec, s[4:5]
	v_mbcnt_lo_u32_b32 v18, -1, 0
	v_mbcnt_hi_u32_b32 v18, -1, v18
	s_barrier
	s_cbranch_vccnz .LBB0_1459
	s_load_dwordx2 s[4:5], s[0:1], 0x68
	v_or_b32_e32 v16, s60, v18
	v_ashrrev_i32_e32 v19, 3, v16
	v_readlane_b32 s8, v251, 4
	s_waitcnt vmcnt(5)
	v_lshlrev_b32_e32 v0, 3, v18
	v_and_b32_e32 v22, 56, v0
	s_waitcnt vmcnt(3)
	v_add_u32_e32 v8, s8, v19
	v_ashrrev_i32_e32 v9, 31, v8
	s_waitcnt lgkmcnt(0)
	s_add_u32 s4, s4, 0x200000
	v_lshlrev_b64 v[0:1], 13, v[8:9]
	v_add_u32_e32 v8, 64, v8
	s_addc_u32 s5, s5, 0
	v_readlane_b32 s8, v251, 5
	v_ashrrev_i32_e32 v9, 31, v8
	s_add_u32 s6, s2, 0xff40000
	v_readlane_b32 s9, v251, 6
	v_lshlrev_b64 v[8:9], 13, v[8:9]
	s_addc_u32 s7, s3, 0
	v_lshl_add_u64 v[0:1], s[4:5], 0, v[0:1]
	s_lshl_b64 s[8:9], s[8:9], 2
	v_lshl_add_u64 v[8:9], s[4:5], 0, v[8:9]
	v_lshl_add_u64 v[0:1], v[0:1], 0, s[8:9]
	v_lshlrev_b32_e32 v166, 2, v22
	v_lshl_add_u64 v[8:9], v[8:9], 0, s[8:9]
	v_lshl_add_u64 v[4:5], v[0:1], 0, v[166:167]
	s_waitcnt vmcnt(2)
	v_lshl_add_u64 v[12:13], v[8:9], 0, v[166:167]
	global_load_dwordx4 v[0:3], v[4:5], off nt
	s_nop 0
	global_load_dwordx4 v[4:7], v[4:5], off offset:16 nt
	s_nop 0
	global_load_dwordx4 v[8:11], v[12:13], off nt
	s_nop 0
	global_load_dwordx4 v[12:15], v[12:13], off offset:16 nt
	v_ashrrev_i32_e32 v23, 2, v16
	v_and_b32_e32 v17, 63, v18
	v_bfe_u32 v21, v18, 2, 4
	v_and_b32_e32 v16, -16, v23
	s_movk_i32 s8, 0x104
	v_or_b32_e32 v23, 15, v23
	v_lshlrev_b32_e32 v27, 6, v18
	v_lshlrev_b32_e32 v18, 4, v18
	v_add_u32_e32 v20, 0, v166
	v_lshl_add_u32 v24, v17, 2, 0
	v_mul_lo_u32 v25, v16, s8
	v_mul_lo_u32 v26, v19, s8
	v_mul_lo_u32 v23, v23, s8
	v_and_b32_e32 v27, 0x80, v27
	v_and_b32_e32 v18, 16, v18
	s_lshl_b32 s10, s39, 7
	v_ashrrev_i32_e32 v17, 31, v16
	v_or3_b32 v18, v27, v21, v18
	v_add_u32_e32 v19, s10, v19
	v_add_u32_e32 v20, v20, v26
	v_lshlrev_b32_e32 v166, 2, v22
	v_add_u32_e32 v21, v24, v25
	v_add_u32_e32 v22, v24, v23
	v_readlane_b32 s11, v253, 13
	s_mov_b32 s14, s62
	s_waitcnt vmcnt(0)
	s_branch .LBB0_1457

; #define tidx() tidx_(wv_)
; __device__ __forceinline__ void conv_run(const float* __restrict__ src, u16* __restrict__ dst, int K, int N, int mode, int& base,
;                                          float* lds, int gi, int ng, int wv_) {
;   const int nk = K / 128, nn = N / 64, ntiles = nk * nn;
;   const int t = tidx();
;   int lt = (base & 1) ? (ng - 1 - gi) : gi;
;   base += 1;
;   float4 ra[2], rb[2];
;   auto gl = [&](int tile) {
;     const int k0 = (tile % nk) * 128, n0 = (tile / nk) * 64;
; #pragma unroll
;     for (int i = 0; i < 2; ++i) {
;       const int kl = (t >> 3) + 64 * i, c8 = (t & 7) * 8;
;       typedef float f4v __attribute__((ext_vector_type(4)));
;       const f4v* sp = (const f4v*)(src + (size_t)(k0 + kl) * N + n0 + c8);
;       const f4v va = __builtin_nontemporal_load(sp), vb = __builtin_nontemporal_load(sp + 1);
;       ra[i] = make_float4(va.x, va.y, va.z, va.w); rb[i] = make_float4(vb.x, vb.y, vb.z, vb.w);
;     }
;   };
;   __syncthreads();
;   if (lt < ntiles) gl(lt);
;   while (lt < ntiles) {
;     const int nxt = lt + ng;
;     const int k0 = (lt % nk) * 128, n0 = (lt / nk) * 64;
;     asm volatile("s_waitcnt lgkmcnt(0)\n\ts_barrier" ::: "memory");
; #pragma unroll
;     for (int i = 0; i < 2; ++i) {
;       const int kl = (t >> 3) + 64 * i, c8 = (t & 7) * 8;
;       float* d = lds + kl * 65 + c8;
;       d[0] = ra[i].x; d[1] = ra[i].y; d[2] = ra[i].z; d[3] = ra[i].w; d[4] = rb[i].x; d[5] = rb[i].y; d[6] = rb[i].z; d[7] = rb[i].w;
;     }
;     if (nxt < ntiles) gl(nxt);
;     asm volatile("s_waitcnt lgkmcnt(0)\n\ts_barrier" ::: "memory");
;     const int nl = t & 63, kc = t >> 6;
;     const int n = n0 + nl;
;     const int row = (mode == 0) ? ((n & ~255) + perm256(n & 255)) : ((n >> 7) * 256 + perm128(n & 127) + (mode == 2 ? 128 : 0));
;     float f[16];
; #pragma unroll
;     for (int i = 0; i < 16; ++i) f[i] = lds[(kc * 16 + i) * 65 + nl];
;     uint4* dp = (uint4*)(dst + (size_t)row * K + k0 + kc * 16);
;     dp[0] = pack8(f);
;     dp[1] = pack8(f + 8);
;     lt = nxt;
;   }
.LBB0_1457:
	v_add_u32_e32 v23, 0x4100, v20
	s_add_i32 s13, s14, s39
	s_waitcnt lgkmcnt(0)
	s_barrier
	s_waitcnt vmcnt(5)
	ds_write2_b32 v20, v0, v1 offset1:1
	ds_write2_b32 v20, v2, v3 offset0:2 offset1:3
	s_waitcnt vmcnt(4)
	ds_write2_b32 v20, v4, v5 offset0:4 offset1:5
	ds_write2_b32 v20, v6, v7 offset0:6 offset1:7
	s_waitcnt vmcnt(3)
	ds_write2_b32 v23, v8, v9 offset1:1
	v_add_u32_e32 v23, 0x4108, v20
	s_cmp_gt_i32 s13, 63
	ds_write2_b32 v23, v10, v11 offset1:1
	v_add_u32_e32 v23, 0x4110, v20
	s_cselect_b64 s[8:9], -1, 0
	s_waitcnt vmcnt(2)
	ds_write2_b32 v23, v12, v13 offset1:1
	v_add_u32_e32 v23, 0x4118, v20
	s_and_b64 vcc, exec, s[8:9]
	ds_write2_b32 v23, v14, v15 offset1:1
	s_cbranch_vccnz .LBB0_1456
	s_lshr_b32 s15, s13, 31
	s_add_i32 s15, s13, s15
	s_ashr_i32 s15, s15, 1
	s_lshl_b32 s16, s15, 6
	v_add_u32_e32 v0, s11, v19
	s_lshl_b32 s15, s15, 8
	v_subrev_u32_e32 v8, s15, v0
	v_ashrrev_i32_e32 v9, 31, v8
	v_lshlrev_b64 v[0:1], 13, v[8:9]
	v_add_u32_e32 v8, 64, v8
	v_ashrrev_i32_e32 v9, 31, v8
	s_ashr_i32 s17, s16, 31
	v_lshlrev_b64 v[8:9], 13, v[8:9]
	v_lshl_add_u64 v[0:1], s[4:5], 0, v[0:1]
	s_lshl_b64 s[16:17], s[16:17], 2
	v_lshl_add_u64 v[8:9], s[4:5], 0, v[8:9]
	v_lshl_add_u64 v[0:1], v[0:1], 0, s[16:17]
	v_lshl_add_u64 v[8:9], v[8:9], 0, s[16:17]
	v_lshl_add_u64 v[4:5], v[0:1], 0, v[166:167]
	v_lshl_add_u64 v[12:13], v[8:9], 0, v[166:167]
	global_load_dwordx4 v[0:3], v[4:5], off nt
	s_nop 0
	global_load_dwordx4 v[4:7], v[4:5], off offset:16 nt
	s_nop 0
	global_load_dwordx4 v[8:11], v[12:13], off nt
	s_nop 0
	global_load_dwordx4 v[12:15], v[12:13], off offset:16 nt
	s_branch .LBB0_1456
.LBB0_1459:
	v_readlane_b32 s4, v252, 15
	v_readlane_b32 s5, v252, 16
	s_andn2_b64 vcc, exec, s[4:5]
	v_mbcnt_lo_u32_b32 v18, -1, 0
	v_mbcnt_hi_u32_b32 v18, -1, v18
	s_barrier
	s_cbranch_vccnz .LBB0_1464
	s_load_dwordx2 s[4:5], s[0:1], 0xe0
	v_or_b32_e32 v16, s60, v18
	v_ashrrev_i32_e32 v19, 3, v16
	s_waitcnt vmcnt(5)
	v_lshlrev_b32_e32 v0, 3, v18
	v_readlane_b32 s8, v252, 12
	v_and_b32_e32 v22, 56, v0
	s_waitcnt lgkmcnt(0)
	v_mov_b64_e32 v[0:1], s[4:5]
	s_waitcnt vmcnt(3)
	v_add_u32_e32 v8, s8, v19
	s_movk_i32 s10, 0x4400
	v_mad_i64_i32 v[0:1], s[8:9], v8, s10, v[0:1]
	v_readlane_b32 s8, v252, 13
	s_add_u32 s6, s2, 0x10040000
	v_readlane_b32 s9, v252, 14
	v_add_u32_e32 v10, 64, v8
	v_mov_b64_e32 v[8:9], s[4:5]
	s_addc_u32 s7, s3, 0
	s_lshl_b64 s[8:9], s[8:9], 2
	v_mad_i64_i32 v[8:9], s[10:11], v10, s10, v[8:9]
	v_lshl_add_u64 v[0:1], v[0:1], 0, s[8:9]
	v_lshlrev_b32_e32 v166, 2, v22
	v_lshl_add_u64 v[8:9], v[8:9], 0, s[8:9]
	v_lshl_add_u64 v[4:5], v[0:1], 0, v[166:167]
	s_waitcnt vmcnt(2)
	v_lshl_add_u64 v[12:13], v[8:9], 0, v[166:167]
	global_load_dwordx4 v[0:3], v[4:5], off nt
	s_nop 0
	global_load_dwordx4 v[4:7], v[4:5], off offset:16 nt
	s_nop 0
	global_load_dwordx4 v[8:11], v[12:13], off nt
	s_nop 0
	global_load_dwordx4 v[12:15], v[12:13], off offset:16 nt
	v_ashrrev_i32_e32 v23, 2, v16
	v_and_b32_e32 v17, 63, v18
	v_bfe_u32 v21, v18, 2, 4
	v_and_b32_e32 v16, -16, v23
	s_movk_i32 s8, 0x104
	v_or_b32_e32 v23, 15, v23
	v_lshlrev_b32_e32 v27, 6, v18
	v_lshlrev_b32_e32 v18, 4, v18
	v_add_u32_e32 v20, 0, v166
	v_lshl_add_u32 v24, v17, 2, 0
	v_mul_lo_u32 v25, v16, s8
	v_mul_lo_u32 v26, v19, s8
	v_mul_lo_u32 v23, v23, s8
	v_and_b32_e32 v27, 0x80, v27
	v_and_b32_e32 v18, 16, v18
	v_readlane_b32 s14, v252, 24
	s_lshl_b32 s11, s39, 7
	v_ashrrev_i32_e32 v17, 31, v16
	v_or3_b32 v18, v27, v21, v18
	s_lshl_b32 s10, s14, 7
	v_add_u32_e32 v19, s11, v19
	v_add_u32_e32 v20, v20, v26
	v_lshlrev_b32_e32 v166, 2, v22
	v_add_u32_e32 v21, v24, v25
	v_add_u32_e32 v22, v24, v23
	s_waitcnt vmcnt(0)
	s_branch .LBB0_1462

; #define tidx() tidx_(wv_)
; __device__ __forceinline__ void conv_run(const float* __restrict__ src, u16* __restrict__ dst, int K, int N, int mode, int& base,
;                                          float* lds, int gi, int ng, int wv_) {
;   const int nk = K / 128, nn = N / 64, ntiles = nk * nn;
;   const int t = tidx();
;   int lt = (base & 1) ? (ng - 1 - gi) : gi;
;   base += 1;
;   float4 ra[2], rb[2];
;   auto gl = [&](int tile) {
;     const int k0 = (tile % nk) * 128, n0 = (tile / nk) * 64;
; #pragma unroll
;     for (int i = 0; i < 2; ++i) {
;       const int kl = (t >> 3) + 64 * i, c8 = (t & 7) * 8;
;       typedef float f4v __attribute__((ext_vector_type(4)));
;       const f4v* sp = (const f4v*)(src + (size_t)(k0 + kl) * N + n0 + c8);
;       const f4v va = __builtin_nontemporal_load(sp), vb = __builtin_nontemporal_load(sp + 1);
;       ra[i] = make_float4(va.x, va.y, va.z, va.w); rb[i] = make_float4(vb.x, vb.y, vb.z, vb.w);
;     }
;   };
;   __syncthreads();
;   if (lt < ntiles) gl(lt);
;   while (lt < ntiles) {
;     const int nxt = lt + ng;
;     const int k0 = (lt % nk) * 128, n0 = (lt / nk) * 64;
;     asm volatile("s_waitcnt lgkmcnt(0)\n\ts_barrier" ::: "memory");
; #pragma unroll
;     for (int i = 0; i < 2; ++i) {
;       const int kl = (t >> 3) + 64 * i, c8 = (t & 7) * 8;
;       float* d = lds + kl * 65 + c8;
;       d[0] = ra[i].x; d[1] = ra[i].y; d[2] = ra[i].z; d[3] = ra[i].w; d[4] = rb[i].x; d[5] = rb[i].y; d[6] = rb[i].z; d[7] = rb[i].w;
;     }
;     if (nxt < ntiles) gl(nxt);
;     asm volatile("s_waitcnt lgkmcnt(0)\n\ts_barrier" ::: "memory");
;     const int nl = t & 63, kc = t >> 6;
;     const int n = n0 + nl;
;     const int row = (mode == 0) ? ((n & ~255) + perm256(n & 255)) : ((n >> 7) * 256 + perm128(n & 127) + (mode == 2 ? 128 : 0));
;     float f[16];
; #pragma unroll
;     for (int i = 0; i < 16; ++i) f[i] = lds[(kc * 16 + i) * 65 + nl];
;     uint4* dp = (uint4*)(dst + (size_t)row * K + k0 + kc * 16);
;     dp[0] = pack8(f);
;     dp[1] = pack8(f + 8);
;     lt = nxt;
;   }
.LBB0_1462:
	v_add_u32_e32 v23, 0x4100, v20
	s_add_i32 s13, s14, s39
	s_waitcnt lgkmcnt(0)
	s_barrier
	s_waitcnt vmcnt(5)
	ds_write2_b32 v20, v0, v1 offset1:1
	ds_write2_b32 v20, v2, v3 offset0:2 offset1:3
	s_waitcnt vmcnt(4)
	ds_write2_b32 v20, v4, v5 offset0:4 offset1:5
	ds_write2_b32 v20, v6, v7 offset0:6 offset1:7
	s_waitcnt vmcnt(3)
	ds_write2_b32 v23, v8, v9 offset1:1
	v_add_u32_e32 v23, 0x4108, v20
	s_cmpk_gt_i32 s13, 0x43f
	ds_write2_b32 v23, v10, v11 offset1:1
	v_add_u32_e32 v23, 0x4110, v20
	s_cselect_b64 s[8:9], -1, 0
	s_waitcnt vmcnt(2)
	ds_write2_b32 v23, v12, v13 offset1:1
	v_add_u32_e32 v23, 0x4118, v20
	s_and_b64 vcc, exec, s[8:9]
	ds_write2_b32 v23, v14, v15 offset1:1
	s_cbranch_vccnz .LBB0_1461
	s_ashr_i32 s15, s13, 31
	s_lshr_b32 s15, s15, 28
	s_add_i32 s15, s13, s15
	s_ashr_i32 s15, s15, 4
	s_lshl_b32 s16, s15, 6
	v_add_u32_e32 v0, s10, v19
	s_lshl_b32 s15, s15, 11
	v_subrev_u32_e32 v10, s15, v0
	v_mov_b64_e32 v[8:9], s[4:5]
	s_movk_i32 s15, 0x4400
	s_ashr_i32 s17, s16, 31
	v_mad_i64_i32 v[0:1], s[18:19], v10, s15, v[8:9]
	v_add_u32_e32 v10, 64, v10
	s_lshl_b64 s[16:17], s[16:17], 2
	v_mad_i64_i32 v[8:9], s[18:19], v10, s15, v[8:9]
	v_lshl_add_u64 v[0:1], v[0:1], 0, s[16:17]
	v_lshl_add_u64 v[8:9], v[8:9], 0, s[16:17]
	v_lshl_add_u64 v[4:5], v[0:1], 0, v[166:167]
	v_lshl_add_u64 v[12:13], v[8:9], 0, v[166:167]
	global_load_dwordx4 v[0:3], v[4:5], off nt
	s_nop 0
	global_load_dwordx4 v[4:7], v[4:5], off offset:16 nt
	s_nop 0
	global_load_dwordx4 v[8:11], v[12:13], off nt
	s_nop 0
	global_load_dwordx4 v[12:15], v[12:13], off offset:16 nt
	s_branch .LBB0_1461
.LBB0_1464:
	v_readlane_b32 s4, v252, 17
	v_readlane_b32 s5, v252, 18
	s_andn2_b64 vcc, exec, s[4:5]
	v_mbcnt_lo_u32_b32 v18, -1, 0
	v_mbcnt_hi_u32_b32 v18, -1, v18
	s_barrier
	s_cbranch_vccnz .LBB0_1469
	v_or_b32_e32 v16, s60, v18
	v_ashrrev_i32_e32 v19, 3, v16
	v_readlane_b32 s8, v252, 19
	s_load_dwordx2 s[4:5], s[0:1], 0xe8
	s_waitcnt vmcnt(5)
	v_lshlrev_b32_e32 v0, 3, v18
	s_waitcnt vmcnt(3)
	v_add_u32_e32 v8, s8, v19
	v_ashrrev_i32_e32 v9, 31, v8
	v_and_b32_e32 v22, 56, v0
	v_lshlrev_b64 v[0:1], 13, v[8:9]
	v_add_u32_e32 v8, 64, v8
	v_readlane_b32 s8, v252, 20
	v_ashrrev_i32_e32 v9, 31, v8
	s_add_u32 s6, s2, 0x11140000
	v_readlane_b32 s9, v252, 21
	v_lshlrev_b64 v[8:9], 13, v[8:9]
	s_addc_u32 s7, s3, 0
	s_waitcnt lgkmcnt(0)
	v_lshl_add_u64 v[0:1], s[4:5], 0, v[0:1]
	s_lshl_b64 s[8:9], s[8:9], 2
	v_lshl_add_u64 v[8:9], s[4:5], 0, v[8:9]
	v_lshl_add_u64 v[0:1], v[0:1], 0, s[8:9]
	v_lshlrev_b32_e32 v166, 2, v22
	v_lshl_add_u64 v[8:9], v[8:9], 0, s[8:9]
	v_lshl_add_u64 v[4:5], v[0:1], 0, v[166:167]
	s_waitcnt vmcnt(2)
	v_lshl_add_u64 v[12:13], v[8:9], 0, v[166:167]
	global_load_dwordx4 v[0:3], v[4:5], off nt
	s_nop 0
	global_load_dwordx4 v[4:7], v[4:5], off offset:16 nt
	s_nop 0
	global_load_dwordx4 v[8:11], v[12:13], off nt
	s_nop 0
	global_load_dwordx4 v[12:15], v[12:13], off offset:16 nt
	v_ashrrev_i32_e32 v23, 2, v16
	v_and_b32_e32 v17, 63, v18
	v_bfe_u32 v21, v18, 2, 4
	v_and_b32_e32 v16, -16, v23
	s_movk_i32 s8, 0x104
	v_or_b32_e32 v23, 15, v23
	v_lshlrev_b32_e32 v27, 6, v18
	v_lshlrev_b32_e32 v18, 4, v18
	v_add_u32_e32 v20, 0, v166
	v_lshl_add_u32 v24, v17, 2, 0
	v_mul_lo_u32 v25, v16, s8
	v_mul_lo_u32 v26, v19, s8
	v_mul_lo_u32 v23, v23, s8
	v_and_b32_e32 v27, 0x80, v27
	v_and_b32_e32 v18, 16, v18
	s_lshl_b32 s10, s39, 7
	v_ashrrev_i32_e32 v17, 31, v16
	v_or3_b32 v18, v27, v21, v18
	v_add_u32_e32 v19, s10, v19
	v_add_u32_e32 v20, v20, v26
	v_lshlrev_b32_e32 v166, 2, v22
	v_add_u32_e32 v21, v24, v25
	v_add_u32_e32 v22, v24, v23
	v_readlane_b32 s11, v253, 13
	s_mov_b32 s14, s62
	s_waitcnt vmcnt(0)
	s_branch .LBB0_1467

; #define tidx() tidx_(wv_)
; __device__ __forceinline__ void conv_run(const float* __restrict__ src, u16* __restrict__ dst, int K, int N, int mode, int& base,
;                                          float* lds, int gi, int ng, int wv_) {
;   const int nk = K / 128, nn = N / 64, ntiles = nk * nn;
;   const int t = tidx();
;   int lt = (base & 1) ? (ng - 1 - gi) : gi;
;   base += 1;
;   float4 ra[2], rb[2];
;   auto gl = [&](int tile) {
;     const int k0 = (tile % nk) * 128, n0 = (tile / nk) * 64;
; #pragma unroll
;     for (int i = 0; i < 2; ++i) {
;       const int kl = (t >> 3) + 64 * i, c8 = (t & 7) * 8;
;       typedef float f4v __attribute__((ext_vector_type(4)));
;       const f4v* sp = (const f4v*)(src + (size_t)(k0 + kl) * N + n0 + c8);
;       const f4v va = __builtin_nontemporal_load(sp), vb = __builtin_nontemporal_load(sp + 1);
;       ra[i] = make_float4(va.x, va.y, va.z, va.w); rb[i] = make_float4(vb.x, vb.y, vb.z, vb.w);
;     }
;   };
;   __syncthreads();
;   if (lt < ntiles) gl(lt);
;   while (lt < ntiles) {
;     const int nxt = lt + ng;
;     const int k0 = (lt % nk) * 128, n0 = (lt / nk) * 64;
;     asm volatile("s_waitcnt lgkmcnt(0)\n\ts_barrier" ::: "memory");
; #pragma unroll
;     for (int i = 0; i < 2; ++i) {
;       const int kl = (t >> 3) + 64 * i, c8 = (t & 7) * 8;
;       float* d = lds + kl * 65 + c8;
;       d[0] = ra[i].x; d[1] = ra[i].y; d[2] = ra[i].z; d[3] = ra[i].w; d[4] = rb[i].x; d[5] = rb[i].y; d[6] = rb[i].z; d[7] = rb[i].w;
;     }
;     if (nxt < ntiles) gl(nxt);
;     asm volatile("s_waitcnt lgkmcnt(0)\n\ts_barrier" ::: "memory");
;     const int nl = t & 63, kc = t >> 6;
;     const int n = n0 + nl;
;     const int row = (mode == 0) ? ((n & ~255) + perm256(n & 255)) : ((n >> 7) * 256 + perm128(n & 127) + (mode == 2 ? 128 : 0));
;     float f[16];
; #pragma unroll
;     for (int i = 0; i < 16; ++i) f[i] = lds[(kc * 16 + i) * 65 + nl];
;     uint4* dp = (uint4*)(dst + (size_t)row * K + k0 + kc * 16);
;     dp[0] = pack8(f);
;     dp[1] = pack8(f + 8);
;     lt = nxt;
;   }
.LBB0_1467:
	v_add_u32_e32 v23, 0x4100, v20
	s_add_i32 s13, s14, s39
	s_waitcnt lgkmcnt(0)
	s_barrier
	s_waitcnt vmcnt(5)
	ds_write2_b32 v20, v0, v1 offset1:1
	ds_write2_b32 v20, v2, v3 offset0:2 offset1:3
	s_waitcnt vmcnt(4)
	ds_write2_b32 v20, v4, v5 offset0:4 offset1:5
	ds_write2_b32 v20, v6, v7 offset0:6 offset1:7
	s_waitcnt vmcnt(3)
	ds_write2_b32 v23, v8, v9 offset1:1
	v_add_u32_e32 v23, 0x4108, v20
	s_cmpk_gt_i32 s13, 0x1ff
	ds_write2_b32 v23, v10, v11 offset1:1
	v_add_u32_e32 v23, 0x4110, v20
	s_cselect_b64 s[8:9], -1, 0
	s_waitcnt vmcnt(2)
	ds_write2_b32 v23, v12, v13 offset1:1
	v_add_u32_e32 v23, 0x4118, v20
	s_and_b64 vcc, exec, s[8:9]
	ds_write2_b32 v23, v14, v15 offset1:1
	s_cbranch_vccnz .LBB0_1466
	s_ashr_i32 s15, s13, 31
	s_lshr_b32 s15, s15, 28
	s_add_i32 s15, s13, s15
	s_ashr_i32 s15, s15, 4
	s_lshl_b32 s16, s15, 6
	v_add_u32_e32 v0, s11, v19
	s_lshl_b32 s15, s15, 11
	v_subrev_u32_e32 v8, s15, v0
	v_ashrrev_i32_e32 v9, 31, v8
	v_lshlrev_b64 v[0:1], 13, v[8:9]
	v_add_u32_e32 v8, 64, v8
	v_ashrrev_i32_e32 v9, 31, v8
	s_ashr_i32 s17, s16, 31
	v_lshlrev_b64 v[8:9], 13, v[8:9]
	v_lshl_add_u64 v[0:1], s[4:5], 0, v[0:1]
	s_lshl_b64 s[16:17], s[16:17], 2
	v_lshl_add_u64 v[8:9], s[4:5], 0, v[8:9]
	v_lshl_add_u64 v[0:1], v[0:1], 0, s[16:17]
	v_lshl_add_u64 v[8:9], v[8:9], 0, s[16:17]
	v_lshl_add_u64 v[4:5], v[0:1], 0, v[166:167]
	v_lshl_add_u64 v[12:13], v[8:9], 0, v[166:167]
	global_load_dwordx4 v[0:3], v[4:5], off nt
	s_nop 0
	global_load_dwordx4 v[4:7], v[4:5], off offset:16 nt
	s_nop 0
	global_load_dwordx4 v[8:11], v[12:13], off nt
	s_nop 0
	global_load_dwordx4 v[12:15], v[12:13], off offset:16 nt
	s_branch .LBB0_1466
.LBB0_1469:
	v_readlane_b32 s4, v252, 22
	v_readlane_b32 s5, v252, 23
	s_andn2_b64 vcc, exec, s[4:5]
	v_readlane_b32 s16, v253, 40
	v_readlane_b32 s14, v253, 42
	v_readlane_b32 s13, v253, 53
	v_mbcnt_lo_u32_b32 v18, -1, 0
	v_mbcnt_hi_u32_b32 v18, -1, v18
	s_barrier
	v_readlane_b32 s17, v253, 41
	v_readlane_b32 s15, v253, 43
	s_cbranch_vccnz .LBB0_1475
	s_load_dwordx2 s[4:5], s[0:1], 0x60
	v_or_b32_e32 v16, s60, v18
	v_ashrrev_i32_e32 v19, 3, v16
	v_readlane_b32 s6, v252, 12
	s_waitcnt vmcnt(5)
	v_lshlrev_b32_e32 v0, 3, v18
	v_and_b32_e32 v22, 56, v0
	s_waitcnt vmcnt(3)
	v_add_u32_e32 v8, s6, v19
	v_ashrrev_i32_e32 v9, 31, v8
	s_waitcnt lgkmcnt(0)
	s_add_u32 s4, s4, 0x1000000
	v_lshlrev_b64 v[0:1], 13, v[8:9]
	v_add_u32_e32 v8, 64, v8
	s_addc_u32 s5, s5, 0
	v_readlane_b32 s6, v252, 13
	v_ashrrev_i32_e32 v9, 31, v8
	s_add_u32 s2, s2, 0xf740000
	v_readlane_b32 s7, v252, 14
	v_lshlrev_b64 v[8:9], 13, v[8:9]
	s_addc_u32 s3, s3, 0
	v_lshl_add_u64 v[0:1], s[4:5], 0, v[0:1]
	s_lshl_b64 s[6:7], s[6:7], 2
	v_lshl_add_u64 v[8:9], s[4:5], 0, v[8:9]
	v_lshl_add_u64 v[0:1], v[0:1], 0, s[6:7]
	v_lshlrev_b32_e32 v166, 2, v22
	v_lshl_add_u64 v[8:9], v[8:9], 0, s[6:7]
	v_lshl_add_u64 v[4:5], v[0:1], 0, v[166:167]
	s_waitcnt vmcnt(2)
	v_lshl_add_u64 v[12:13], v[8:9], 0, v[166:167]
	global_load_dwordx4 v[0:3], v[4:5], off nt
	s_nop 0
	global_load_dwordx4 v[4:7], v[4:5], off offset:16 nt
	s_nop 0
	global_load_dwordx4 v[8:11], v[12:13], off nt
	s_nop 0
	global_load_dwordx4 v[12:15], v[12:13], off offset:16 nt
	v_ashrrev_i32_e32 v23, 2, v16
	v_and_b32_e32 v17, 63, v18
	v_bfe_u32 v21, v18, 2, 4
	v_and_b32_e32 v16, -16, v23
	s_movk_i32 s6, 0x104
	v_or_b32_e32 v23, 15, v23
	v_lshlrev_b32_e32 v27, 6, v18
	v_lshlrev_b32_e32 v18, 4, v18
	v_add_u32_e32 v20, 0, v166
	v_lshl_add_u32 v24, v17, 2, 0
	v_mul_lo_u32 v25, v16, s6
	v_mul_lo_u32 v26, v19, s6
	v_mul_lo_u32 v23, v23, s6
	v_and_b32_e32 v27, 0x80, v27
	v_and_b32_e32 v18, 16, v18
	v_readlane_b32 s11, v252, 24
	s_lshl_b32 s9, s39, 7
	v_ashrrev_i32_e32 v17, 31, v16
	v_or3_b32 v18, v27, v21, v18
	s_lshl_b32 s8, s11, 7
	v_add_u32_e32 v19, s9, v19
	v_add_u32_e32 v20, v20, v26
	v_lshlrev_b32_e32 v166, 2, v22
	v_add_u32_e32 v21, v24, v25
	v_add_u32_e32 v22, v24, v23
	s_waitcnt vmcnt(0)
	s_branch .LBB0_1472

; __device__ __forceinline__ void conv_run(const float* __restrict__ src, u16* __restrict__ dst, int K, int N, int mode, int& base,
;                                          float* lds, int gi, int ng, int wv_) {
;     ...
;   while (lt < ntiles) {
;     const int nxt = lt + ng;
;     const int k0 = (lt % nk) * 128, n0 = (lt / nk) * 64;
;     asm volatile("s_waitcnt lgkmcnt(0)\n\ts_barrier" ::: "memory");
; #pragma unroll
;     for (int i = 0; i < 2; ++i) {
;       const int kl = (t >> 3) + 64 * i, c8 = (t & 7) * 8;
;       float* d = lds + kl * 65 + c8;
;       d[0] = ra[i].x; d[1] = ra[i].y; d[2] = ra[i].z; d[3] = ra[i].w; d[4] = rb[i].x; d[5] = rb[i].y; d[6] = rb[i].z; d[7] = rb[i].w;
;     }
;     if (nxt < ntiles) gl(nxt);
;     asm volatile("s_waitcnt lgkmcnt(0)\n\ts_barrier" ::: "memory");
;     const int nl = t & 63, kc = t >> 6;
;     const int n = n0 + nl;
;     const int row = (mode == 0) ? ((n & ~255) + perm256(n & 255)) : ((n >> 7) * 256 + perm128(n & 127) + (mode == 2 ? 128 : 0));
;     float f[16];
; #pragma unroll
;     for (int i = 0; i < 16; ++i) f[i] = lds[(kc * 16 + i) * 65 + nl];
;     uint4* dp = (uint4*)(dst + (size_t)row * K + k0 + kc * 16);
;     dp[0] = pack8(f);
;     dp[1] = pack8(f + 8);
;     lt = nxt;
;   }
.LBB0_1472:
	v_add_u32_e32 v23, 0x4100, v20
	s_add_i32 s10, s11, s39
	s_waitcnt lgkmcnt(0)
	s_barrier
	s_waitcnt vmcnt(5)
	ds_write2_b32 v20, v0, v1 offset1:1
	ds_write2_b32 v20, v2, v3 offset0:2 offset1:3
	s_waitcnt vmcnt(4)
	ds_write2_b32 v20, v4, v5 offset0:4 offset1:5
	ds_write2_b32 v20, v6, v7 offset0:6 offset1:7
	s_waitcnt vmcnt(3)
	ds_write2_b32 v23, v8, v9 offset1:1
	v_add_u32_e32 v23, 0x4108, v20
	s_cmpk_gt_i32 s10, 0x1ff
	ds_write2_b32 v23, v10, v11 offset1:1
	v_add_u32_e32 v23, 0x4110, v20
	s_cselect_b64 s[6:7], -1, 0
	s_waitcnt vmcnt(2)
	ds_write2_b32 v23, v12, v13 offset1:1
	v_add_u32_e32 v23, 0x4118, v20
	s_and_b64 vcc, exec, s[6:7]
	ds_write2_b32 v23, v14, v15 offset1:1
	s_cbranch_vccnz .LBB0_1471
	s_ashr_i32 s13, s10, 31
	s_lshr_b32 s13, s13, 28
	s_add_i32 s13, s10, s13
	s_ashr_i32 s13, s13, 4
	s_lshl_b32 s14, s13, 6
	v_add_u32_e32 v0, s8, v19
	s_lshl_b32 s13, s13, 11
	v_subrev_u32_e32 v8, s13, v0
	v_ashrrev_i32_e32 v9, 31, v8
	v_lshlrev_b64 v[0:1], 13, v[8:9]
	v_add_u32_e32 v8, 64, v8
	v_ashrrev_i32_e32 v9, 31, v8
	s_ashr_i32 s15, s14, 31
	v_lshlrev_b64 v[8:9], 13, v[8:9]
	v_lshl_add_u64 v[0:1], s[4:5], 0, v[0:1]
	s_lshl_b64 s[14:15], s[14:15], 2
	v_lshl_add_u64 v[8:9], s[4:5], 0, v[8:9]
	v_lshl_add_u64 v[0:1], v[0:1], 0, s[14:15]
	v_lshl_add_u64 v[8:9], v[8:9], 0, s[14:15]
	v_lshl_add_u64 v[4:5], v[0:1], 0, v[166:167]
	v_lshl_add_u64 v[12:13], v[8:9], 0, v[166:167]
	global_load_dwordx4 v[0:3], v[4:5], off nt
	s_nop 0
	global_load_dwordx4 v[4:7], v[4:5], off offset:16 nt
	s_nop 0
	global_load_dwordx4 v[8:11], v[12:13], off nt
	s_nop 0
	global_load_dwordx4 v[12:15], v[12:13], off offset:16 nt
	s_branch .LBB0_1471

; #define tidx() tidx_(wv_)
; __device__ __forceinline__ void conv_run(const float* __restrict__ src, u16* __restrict__ dst, int K, int N, int mode, int& base,
;                                          float* lds, int gi, int ng, int wv_) {
;   const int nk = K / 128, nn = N / 64, ntiles = nk * nn;
;   const int t = tidx();
;   int lt = (base & 1) ? (ng - 1 - gi) : gi;
;   base += 1;
;   float4 ra[2], rb[2];
;   auto gl = [&](int tile) {
;     const int k0 = (tile % nk) * 128, n0 = (tile / nk) * 64;
; #pragma unroll
;     for (int i = 0; i < 2; ++i) {
;       const int kl = (t >> 3) + 64 * i, c8 = (t & 7) * 8;
;       typedef float f4v __attribute__((ext_vector_type(4)));
;       const f4v* sp = (const f4v*)(src + (size_t)(k0 + kl) * N + n0 + c8);
;       const f4v va = __builtin_nontemporal_load(sp), vb = __builtin_nontemporal_load(sp + 1);
;       ra[i] = make_float4(va.x, va.y, va.z, va.w); rb[i] = make_float4(vb.x, vb.y, vb.z, vb.w);
;     }
;   };
;   __syncthreads();
;   if (lt < ntiles) gl(lt);
.LBB0_1481:
	s_cmp_eq_u32 s12, 4
	s_mov_b64 s[6:7], -1
	s_cbranch_scc0 .LBB0_1492
	v_readlane_b32 s6, v252, 29
	v_readlane_b32 s7, v252, 30
	s_andn2_b64 vcc, exec, s[6:7]
	v_mbcnt_lo_u32_b32 v18, -1, 0
	v_mbcnt_hi_u32_b32 v18, -1, v18
	s_barrier
	s_cbranch_vccnz .LBB0_1487
	v_or_b32_e32 v16, s60, v18
	v_ashrrev_i32_e32 v19, 3, v16
	v_readlane_b32 s10, v252, 31
	s_load_dwordx2 s[6:7], s[0:1], 0x28
	v_lshlrev_b32_e32 v0, 3, v18
	v_add_u32_e32 v8, s10, v19
	v_ashrrev_i32_e32 v9, 31, v8
	v_and_b32_e32 v22, 56, v0
	v_lshlrev_b64 v[0:1], 13, v[8:9]
	v_add_u32_e32 v8, 64, v8
	v_ashrrev_i32_e32 v9, 31, v8
	s_add_u32 s8, s2, 0x5800000
	v_readlane_b32 s10, v252, 32
	v_lshlrev_b64 v[8:9], 13, v[8:9]
	s_addc_u32 s9, s3, 0
	s_waitcnt lgkmcnt(0)
	v_lshl_add_u64 v[0:1], s[6:7], 0, v[0:1]
	s_lshl_b32 s84, s10, 2
	v_lshl_add_u64 v[8:9], s[6:7], 0, v[8:9]
	v_lshl_add_u64 v[0:1], v[0:1], 0, s[84:85]
	v_lshlrev_b32_e32 v166, 2, v22
	v_lshl_add_u64 v[8:9], v[8:9], 0, s[84:85]
	v_lshl_add_u64 v[4:5], v[0:1], 0, v[166:167]
	v_lshl_add_u64 v[12:13], v[8:9], 0, v[166:167]
	global_load_dwordx4 v[0:3], v[4:5], off nt
	s_nop 0
	global_load_dwordx4 v[4:7], v[4:5], off offset:16 nt
	s_nop 0
	global_load_dwordx4 v[8:11], v[12:13], off nt
	s_nop 0
	global_load_dwordx4 v[12:15], v[12:13], off offset:16 nt
	v_ashrrev_i32_e32 v23, 2, v16
	v_and_b32_e32 v17, 63, v18
	v_bfe_u32 v21, v18, 2, 4
	v_and_b32_e32 v16, -16, v23
	s_movk_i32 s10, 0x104
	v_or_b32_e32 v23, 15, v23
	v_lshlrev_b32_e32 v27, 6, v18
	v_lshlrev_b32_e32 v18, 4, v18
	v_add_u32_e32 v20, 0, v166
	v_lshl_add_u32 v24, v17, 2, 0
	v_mul_lo_u32 v25, v16, s10
	v_mul_lo_u32 v26, v19, s10
	v_mul_lo_u32 v23, v23, s10
	v_and_b32_e32 v27, 0x80, v27
	v_and_b32_e32 v18, 16, v18
	v_readlane_b32 s14, v253, 6
	v_ashrrev_i32_e32 v17, 31, v16
	v_or3_b32 v18, v27, v21, v18
	v_add_u32_e32 v19, s14, v19
	v_add_u32_e32 v20, v20, v26
	v_lshlrev_b32_e32 v166, 2, v22
	v_add_u32_e32 v21, v24, v25
	v_add_u32_e32 v22, v24, v23
	s_mov_b32 s13, s62
	v_readlane_b32 s16, v253, 5
	s_waitcnt vmcnt(0)
	s_branch .LBB0_1485

; __device__ __forceinline__ void conv_run(const float* __restrict__ src, u16* __restrict__ dst, int K, int N, int mode, int& base,
;                                          float* lds, int gi, int ng, int wv_) {
;     ...
;   auto gl = [&](int tile) {
;     const int k0 = (tile % nk) * 128, n0 = (tile / nk) * 64;
; #pragma unroll
;     for (int i = 0; i < 2; ++i) {
;       const int kl = (t >> 3) + 64 * i, c8 = (t & 7) * 8;
;       typedef float f4v __attribute__((ext_vector_type(4)));
;       const f4v* sp = (const f4v*)(src + (size_t)(k0 + kl) * N + n0 + c8);
;       const f4v va = __builtin_nontemporal_load(sp), vb = __builtin_nontemporal_load(sp + 1);
;       ra[i] = make_float4(va.x, va.y, va.z, va.w); rb[i] = make_float4(vb.x, vb.y, vb.z, vb.w);
;     }
;   };
;   __syncthreads();
;   if (lt < ntiles) gl(lt);
;   while (lt < ntiles) {
;     const int nxt = lt + ng;
;     const int k0 = (lt % nk) * 128, n0 = (lt / nk) * 64;
;     asm volatile("s_waitcnt lgkmcnt(0)\n\ts_barrier" ::: "memory");
; #pragma unroll
;     for (int i = 0; i < 2; ++i) {
;       const int kl = (t >> 3) + 64 * i, c8 = (t & 7) * 8;
;       float* d = lds + kl * 65 + c8;
;       d[0] = ra[i].x; d[1] = ra[i].y; d[2] = ra[i].z; d[3] = ra[i].w; d[4] = rb[i].x; d[5] = rb[i].y; d[6] = rb[i].z; d[7] = rb[i].w;
;     }
;     if (nxt < ntiles) gl(nxt);
;     asm volatile("s_waitcnt lgkmcnt(0)\n\ts_barrier" ::: "memory");
; __device__ __forceinline__ void convert_set(unsigned char* ws, int set, int gi, int ng, float* lds, int wv_) {
;     ...
;     conv_run(inp(ws, 5), (u16*)(ws + OFF_W2_00), F_, D_, 0, base, lds, gi, ng, wv_);
;     conv_run(inp(ws, 14), (u16*)(ws + OFF_WABI), D_, ABC_, 0, base, lds, gi, ng, wv_);
.LBB0_1485:
	v_add_u32_e32 v23, 0x4100, v20
	s_add_i32 s15, s16, 0x80
	s_waitcnt lgkmcnt(0)
	s_barrier
	s_waitcnt vmcnt(5)
	ds_write2_b32 v20, v0, v1 offset1:1
	ds_write2_b32 v20, v2, v3 offset0:2 offset1:3
	s_waitcnt vmcnt(4)
	ds_write2_b32 v20, v4, v5 offset0:4 offset1:5
	ds_write2_b32 v20, v6, v7 offset0:6 offset1:7
	s_waitcnt vmcnt(3)
	ds_write2_b32 v23, v8, v9 offset1:1
	v_add_u32_e32 v23, 0x4108, v20
	s_cmpk_gt_i32 s16, 0x4ff
	ds_write2_b32 v23, v10, v11 offset1:1
	v_add_u32_e32 v23, 0x4110, v20
	s_cselect_b64 s[10:11], -1, 0
	s_waitcnt vmcnt(2)
	ds_write2_b32 v23, v12, v13 offset1:1
	v_add_u32_e32 v23, 0x4118, v20
	s_and_b64 vcc, exec, s[10:11]
	ds_write2_b32 v23, v14, v15 offset1:1
	s_cbranch_vccnz .LBB0_1484
	s_mul_hi_u32 s17, s13, 0xba2e8ba3
	s_lshr_b32 s17, s17, 5
	s_mulk_i32 s17, 0x1600
	v_subrev_u32_e32 v8, s17, v19
	s_mul_hi_u32 s17, s15, 0xba2e8ba3
	v_add_u32_e32 v0, 0x4000, v8
	v_add_u32_e32 v8, 0x4040, v8
	s_lshl_b32 s17, s17, 1
	v_ashrrev_i32_e32 v1, 31, v0
	v_ashrrev_i32_e32 v9, 31, v8
	s_and_b32 s84, s17, 0xffffffc0
	v_lshlrev_b64 v[0:1], 13, v[0:1]
	v_lshlrev_b64 v[8:9], 13, v[8:9]
	v_lshl_add_u64 v[0:1], s[6:7], 0, v[0:1]
	s_lshl_b64 s[18:19], s[84:85], 2
	v_lshl_add_u64 v[8:9], s[6:7], 0, v[8:9]
	v_lshl_add_u64 v[0:1], v[0:1], 0, s[18:19]
	v_lshl_add_u64 v[8:9], v[8:9], 0, s[18:19]
	v_lshl_add_u64 v[4:5], v[0:1], 0, v[166:167]
	v_lshl_add_u64 v[12:13], v[8:9], 0, v[166:167]
	global_load_dwordx4 v[0:3], v[4:5], off nt
	s_nop 0
	global_load_dwordx4 v[4:7], v[4:5], off offset:16 nt
	s_nop 0
	global_load_dwordx4 v[8:11], v[12:13], off nt
	s_nop 0
	global_load_dwordx4 v[12:15], v[12:13], off offset:16 nt
	s_branch .LBB0_1484
.LBB0_1487:
	s_load_dwordx2 s[6:7], s[0:1], 0x70
	v_mbcnt_lo_u32_b32 v19, -1, 0
	v_mbcnt_hi_u32_b32 v19, -1, v19
	v_readlane_b32 s10, v252, 34
	v_or_b32_e32 v16, s60, v19
	v_ashrrev_i32_e32 v18, 3, v16
	s_waitcnt vmcnt(5)
	v_lshlrev_b32_e32 v0, 3, v19
	v_and_b32_e32 v22, 56, v0
	s_waitcnt vmcnt(3)
	v_add_u32_e32 v8, s10, v18
	s_waitcnt lgkmcnt(0)
	v_mov_b64_e32 v[0:1], s[6:7]
	s_movk_i32 s13, 0x6700
	v_mad_i64_i32 v[0:1], s[10:11], v8, s13, v[0:1]
	v_readlane_b32 s10, v252, 35
	s_add_u32 s8, s2, 0x8d00000
	v_readlane_b32 s11, v252, 36
	v_add_u32_e32 v10, 64, v8
	v_mov_b64_e32 v[8:9], s[6:7]
	s_addc_u32 s9, s3, 0
	s_lshl_b64 s[10:11], s[10:11], 2
	v_mad_i64_i32 v[8:9], s[14:15], v10, s13, v[8:9]
	v_lshl_add_u64 v[0:1], v[0:1], 0, s[10:11]
	v_lshlrev_b32_e32 v166, 2, v22
	v_lshl_add_u64 v[8:9], v[8:9], 0, s[10:11]
	v_lshl_add_u64 v[4:5], v[0:1], 0, v[166:167]
	s_waitcnt vmcnt(2)
	v_lshl_add_u64 v[12:13], v[8:9], 0, v[166:167]
	s_barrier
	global_load_dwordx4 v[0:3], v[4:5], off nt
	s_nop 0
	global_load_dwordx4 v[4:7], v[4:5], off offset:16 nt
	s_nop 0
	global_load_dwordx4 v[8:11], v[12:13], off nt
	s_nop 0
	global_load_dwordx4 v[12:15], v[12:13], off offset:16 nt
	v_ashrrev_i32_e32 v23, 2, v16
	v_and_b32_e32 v17, 63, v19
	v_bfe_u32 v21, v19, 2, 4
	v_and_b32_e32 v16, -16, v23
	s_movk_i32 s10, 0x104
	v_or_b32_e32 v23, 15, v23
	v_lshlrev_b32_e32 v27, 6, v19
	v_lshlrev_b32_e32 v19, 4, v19
	v_add_u32_e32 v20, 0, v166
	v_lshl_add_u32 v24, v17, 2, 0
	v_mul_lo_u32 v25, v16, s10
	v_mul_lo_u32 v26, v18, s10
	v_mul_lo_u32 v23, v23, s10
	v_and_b32_e32 v27, 0x80, v27
	v_and_b32_e32 v19, 16, v19
	v_readlane_b32 s15, v252, 33
	v_ashrrev_i32_e32 v17, 31, v16
	v_or3_b32 v19, v27, v21, v19
	s_lshl_b32 s13, s15, 7
	v_add_u32_e32 v20, v20, v26
	v_lshlrev_b32_e32 v166, 2, v22
	v_add_u32_e32 v21, v24, v25
	v_add_u32_e32 v22, v24, v23
	s_waitcnt vmcnt(0)
	s_branch .LBB0_1489

; __device__ __forceinline__ void conv_run(const float* __restrict__ src, u16* __restrict__ dst, int K, int N, int mode, int& base,
;                                          float* lds, int gi, int ng, int wv_) {
;     ...
;   while (lt < ntiles) {
;     const int nxt = lt + ng;
;     const int k0 = (lt % nk) * 128, n0 = (lt / nk) * 64;
;     asm volatile("s_waitcnt lgkmcnt(0)\n\ts_barrier" ::: "memory");
; #pragma unroll
;     for (int i = 0; i < 2; ++i) {
;       const int kl = (t >> 3) + 64 * i, c8 = (t & 7) * 8;
;       float* d = lds + kl * 65 + c8;
;       d[0] = ra[i].x; d[1] = ra[i].y; d[2] = ra[i].z; d[3] = ra[i].w; d[4] = rb[i].x; d[5] = rb[i].y; d[6] = rb[i].z; d[7] = rb[i].w;
;     }
;     if (nxt < ntiles) gl(nxt);
;     asm volatile("s_waitcnt lgkmcnt(0)\n\ts_barrier" ::: "memory");
.LBB0_1489:
	v_add_u32_e32 v23, 0x4100, v20
	s_add_i32 s14, s15, 0x80
	s_waitcnt lgkmcnt(0)
	s_barrier
	s_waitcnt vmcnt(5)
	ds_write2_b32 v20, v0, v1 offset1:1
	ds_write2_b32 v20, v2, v3 offset0:2 offset1:3
	s_waitcnt vmcnt(4)
	ds_write2_b32 v20, v4, v5 offset0:4 offset1:5
	ds_write2_b32 v20, v6, v7 offset0:6 offset1:7
	s_waitcnt vmcnt(3)
	ds_write2_b32 v23, v8, v9 offset1:1
	v_add_u32_e32 v23, 0x4108, v20
	s_cmpk_gt_i32 s15, 0x5ef
	ds_write2_b32 v23, v10, v11 offset1:1
	v_add_u32_e32 v23, 0x4110, v20
	s_cselect_b64 s[10:11], -1, 0
	s_waitcnt vmcnt(2)
	ds_write2_b32 v23, v12, v13 offset1:1
	v_add_u32_e32 v23, 0x4118, v20
	s_and_b64 vcc, exec, s[10:11]
	ds_write2_b32 v23, v14, v15 offset1:1
	s_cbranch_vccnz .LBB0_1488
	s_ashr_i32 s16, s14, 31
	s_lshr_b32 s16, s16, 28
	s_add_i32 s16, s14, s16
	s_ashr_i32 s18, s16, 4
	s_lshl_b32 s16, s18, 6
	v_add_u32_e32 v0, s13, v18
	s_lshl_b32 s18, s18, 11
	v_subrev_u32_e32 v10, s18, v0
	s_ashr_i32 s17, s16, 31
	v_add_u32_e32 v0, 0x4000, v10
	v_mov_b64_e32 v[8:9], s[6:7]
	s_movk_i32 s22, 0x6700
	v_add_u32_e32 v10, 0x4040, v10
	v_mad_i64_i32 v[0:1], s[18:19], v0, s22, v[8:9]
	s_lshl_b64 s[16:17], s[16:17], 2
	v_mad_i64_i32 v[8:9], s[18:19], v10, s22, v[8:9]
	v_lshl_add_u64 v[0:1], v[0:1], 0, s[16:17]
	v_lshl_add_u64 v[8:9], v[8:9], 0, s[16:17]
	v_lshl_add_u64 v[4:5], v[0:1], 0, v[166:167]
	v_lshl_add_u64 v[12:13], v[8:9], 0, v[166:167]
	global_load_dwordx4 v[0:3], v[4:5], off nt
	s_nop 0
	global_load_dwordx4 v[4:7], v[4:5], off offset:16 nt
	s_nop 0
	global_load_dwordx4 v[8:11], v[12:13], off nt
	s_nop 0
	global_load_dwordx4 v[12:15], v[12:13], off offset:16 nt
	s_branch .LBB0_1488

; #define tidx() tidx_(wv_)
; __device__ __forceinline__ void conv_run(const float* __restrict__ src, u16* __restrict__ dst, int K, int N, int mode, int& base,
;                                          float* lds, int gi, int ng, int wv_) {
;   const int nk = K / 128, nn = N / 64, ntiles = nk * nn;
;   const int t = tidx();
;   int lt = (base & 1) ? (ng - 1 - gi) : gi;
;   base += 1;
;   float4 ra[2], rb[2];
;   auto gl = [&](int tile) {
;     const int k0 = (tile % nk) * 128, n0 = (tile / nk) * 64;
; #pragma unroll
;     for (int i = 0; i < 2; ++i) {
;       const int kl = (t >> 3) + 64 * i, c8 = (t & 7) * 8;
;       typedef float f4v __attribute__((ext_vector_type(4)));
;       const f4v* sp = (const f4v*)(src + (size_t)(k0 + kl) * N + n0 + c8);
;       const f4v va = __builtin_nontemporal_load(sp), vb = __builtin_nontemporal_load(sp + 1);
;       ra[i] = make_float4(va.x, va.y, va.z, va.w); rb[i] = make_float4(vb.x, vb.y, vb.z, vb.w);
;     }
;   };
;   __syncthreads();
;   if (lt < ntiles) gl(lt);
; __device__ __forceinline__ void convert_set(unsigned char* ws, int set, int gi, int ng, float* lds, int wv_) {
;     ...
;     conv_run(inp(ws, 8) + fw, (u16*)(ws + OFF_W13_11), D_, F_, 1, base, lds, gi, ng, wv_);
.LBB0_1494:
	v_readlane_b32 s8, v252, 29
	v_readlane_b32 s9, v252, 30
	s_add_u32 s6, s2, 0xb540000
	s_addc_u32 s7, s3, 0
	s_waitcnt vmcnt(5)
	v_cndmask_b32_e64 v0, 0, 1, s[8:9]
	v_cmp_ne_u32_e64 s[4:5], 1, v0
	s_andn2_b64 vcc, exec, s[8:9]
	v_mbcnt_lo_u32_b32 v16, -1, 0
	v_mbcnt_hi_u32_b32 v16, -1, v16
	s_barrier
	s_cbranch_vccnz .LBB0_1499
	s_load_dwordx2 s[8:9], s[0:1], 0x40
	v_or_b32_e32 v17, s60, v16
	v_ashrrev_i32_e32 v20, 3, v17
	v_lshlrev_b32_e32 v0, 3, v16
	v_readlane_b32 s12, v252, 43
	s_waitcnt lgkmcnt(0)
	s_add_u32 s8, s8, 0x2c00000
	s_addc_u32 s9, s9, 0
	v_readlane_b32 s14, v253, 26
	v_add_u32_e32 v21, 64, v20
	v_and_b32_e32 v18, 56, v0
	v_add_u32_e32 v0, s12, v20
	s_waitcnt vmcnt(3)
	v_mov_b64_e32 v[8:9], s[8:9]
	s_movk_i32 s13, 0x5800
	v_readlane_b32 s15, v253, 27
	v_add_u32_e32 v10, s12, v21
	v_mad_i64_i32 v[0:1], s[10:11], v0, s13, v[8:9]
	s_mov_b32 s15, s85
	v_mad_i64_i32 v[8:9], s[10:11], v10, s13, v[8:9]
	v_lshl_add_u64 v[0:1], v[0:1], 0, s[14:15]
	v_lshlrev_b32_e32 v166, 2, v18
	v_lshl_add_u64 v[8:9], v[8:9], 0, s[14:15]
	v_lshl_add_u64 v[4:5], v[0:1], 0, v[166:167]
	s_waitcnt vmcnt(2)
	v_lshl_add_u64 v[12:13], v[8:9], 0, v[166:167]
	global_load_dwordx4 v[0:3], v[4:5], off nt
	s_nop 0
	global_load_dwordx4 v[4:7], v[4:5], off offset:16 nt
	s_nop 0
	global_load_dwordx4 v[8:11], v[12:13], off nt
	s_nop 0
	global_load_dwordx4 v[12:15], v[12:13], off offset:16 nt
	s_mov_b32 s10, s14
	v_writelane_b32 v253, s10, 26
	v_and_b32_e32 v23, 63, v16
	v_lshlrev_b32_e32 v22, 4, v16
	v_bfe_u32 v16, v16, 1, 4
	v_ashrrev_i32_e32 v24, 2, v17
	v_writelane_b32 v253, s11, 27
	v_and_or_b32 v22, v22, 16, v16
	v_and_b32_e32 v16, -16, v24
	s_movk_i32 s10, 0x104
	v_or_b32_e32 v24, 15, v24
	v_add_u32_e32 v19, 0, v166
	v_lshl_add_u32 v26, v23, 2, 0
	v_mul_lo_u32 v25, v16, s10
	v_mul_lo_u32 v27, v20, s10
	v_mul_lo_u32 v28, v24, s10
	v_readlane_b32 s10, v253, 0
	v_ashrrev_i32_e32 v17, 31, v16
	v_add_u32_e32 v24, v19, v27
	v_add_u32_e32 v23, s10, v23
	v_lshlrev_b32_e32 v18, 2, v18
	v_add_u32_e32 v25, v26, v25
	v_add_u32_e32 v26, v26, v28
	v_readlane_b32 s12, v253, 15
	v_readlane_b32 s13, v252, 63
	v_readlane_b32 s14, v253, 14
	v_readlane_b32 s15, v253, 5
	s_waitcnt vmcnt(0)
	s_branch .LBB0_1497

; __device__ __forceinline__ void conv_run(const float* __restrict__ src, u16* __restrict__ dst, int K, int N, int mode, int& base,
;                                          float* lds, int gi, int ng, int wv_) {
;     ...
;   auto gl = [&](int tile) {
;     const int k0 = (tile % nk) * 128, n0 = (tile / nk) * 64;
; #pragma unroll
;     for (int i = 0; i < 2; ++i) {
;       const int kl = (t >> 3) + 64 * i, c8 = (t & 7) * 8;
;       typedef float f4v __attribute__((ext_vector_type(4)));
;       const f4v* sp = (const f4v*)(src + (size_t)(k0 + kl) * N + n0 + c8);
;       const f4v va = __builtin_nontemporal_load(sp), vb = __builtin_nontemporal_load(sp + 1);
;       ra[i] = make_float4(va.x, va.y, va.z, va.w); rb[i] = make_float4(vb.x, vb.y, vb.z, vb.w);
;     }
;   };
;   __syncthreads();
;   if (lt < ntiles) gl(lt);
;   while (lt < ntiles) {
;     const int nxt = lt + ng;
;     const int k0 = (lt % nk) * 128, n0 = (lt / nk) * 64;
;     asm volatile("s_waitcnt lgkmcnt(0)\n\ts_barrier" ::: "memory");
; #pragma unroll
;     for (int i = 0; i < 2; ++i) {
;       const int kl = (t >> 3) + 64 * i, c8 = (t & 7) * 8;
;       float* d = lds + kl * 65 + c8;
;       d[0] = ra[i].x; d[1] = ra[i].y; d[2] = ra[i].z; d[3] = ra[i].w; d[4] = rb[i].x; d[5] = rb[i].y; d[6] = rb[i].z; d[7] = rb[i].w;
;     }
;     if (nxt < ntiles) gl(nxt);
;     asm volatile("s_waitcnt lgkmcnt(0)\n\ts_barrier" ::: "memory");
; __device__ __forceinline__ void convert_set(unsigned char* ws, int set, int gi, int ng, float* lds, int wv_) {
;     ...
;     conv_run(inp(ws, 9) + fw, (u16*)(ws + OFF_W13_11), D_, F_, 2, base, lds, gi, ng, wv_);
.LBB0_1497:
	v_add_u32_e32 v19, 0x4100, v24
	s_and_b32 s16, s14, 0x780
	s_waitcnt lgkmcnt(0)
	s_barrier
	s_waitcnt vmcnt(5)
	ds_write2_b32 v24, v0, v1 offset1:1
	ds_write2_b32 v24, v2, v3 offset0:2 offset1:3
	s_waitcnt vmcnt(4)
	ds_write2_b32 v24, v4, v5 offset0:4 offset1:5
	ds_write2_b32 v24, v6, v7 offset0:6 offset1:7
	s_waitcnt vmcnt(3)
	ds_write2_b32 v19, v8, v9 offset1:1
	v_add_u32_e32 v19, 0x4108, v24
	s_cmpk_gt_i32 s15, 0x4ff
	ds_write2_b32 v19, v10, v11 offset1:1
	v_add_u32_e32 v19, 0x4110, v24
	s_cselect_b64 s[10:11], -1, 0
	s_waitcnt vmcnt(2)
	ds_write2_b32 v19, v12, v13 offset1:1
	v_add_u32_e32 v19, 0x4118, v24
	s_and_b64 vcc, exec, s[10:11]
	ds_write2_b32 v19, v14, v15 offset1:1
	s_cbranch_vccnz .LBB0_1496
	v_add_u32_e32 v0, s16, v20
	v_mov_b64_e32 v[8:9], s[8:9]
	s_movk_i32 s17, 0x5800
	s_and_b32 s84, s12, 0x7fffffc0
	v_mad_i64_i32 v[0:1], s[18:19], v0, s17, v[8:9]
	v_add_u32_e32 v10, s16, v21
	s_lshl_b64 s[18:19], s[84:85], 2
	v_mad_i64_i32 v[8:9], s[20:21], v10, s17, v[8:9]
	v_lshl_add_u64 v[0:1], v[0:1], 0, s[18:19]
	v_mov_b32_e32 v19, v167
	v_lshl_add_u64 v[8:9], v[8:9], 0, s[18:19]
	v_lshl_add_u64 v[4:5], v[0:1], 0, v[18:19]
	v_lshl_add_u64 v[12:13], v[8:9], 0, v[18:19]
	global_load_dwordx4 v[0:3], v[4:5], off nt
	s_nop 0
	global_load_dwordx4 v[4:7], v[4:5], off offset:16 nt
	s_nop 0
	global_load_dwordx4 v[8:11], v[12:13], off nt
	s_nop 0
	global_load_dwordx4 v[12:15], v[12:13], off offset:16 nt
	v_readlane_b32 s20, v253, 44
	v_readlane_b32 s21, v253, 45
	s_branch .LBB0_1496
.LBB0_1499:
	s_load_dwordx2 s[8:9], s[0:1], 0x48
	v_mbcnt_lo_u32_b32 v16, -1, 0
	v_mbcnt_hi_u32_b32 v16, -1, v16
	v_readlane_b32 s10, v252, 34
	v_or_b32_e32 v17, s60, v16
	v_ashrrev_i32_e32 v18, 3, v17
	s_waitcnt lgkmcnt(0)
	s_add_u32 s8, s8, 0x2c00000
	s_addc_u32 s9, s9, 0
	s_waitcnt vmcnt(5)
	v_lshlrev_b32_e32 v0, 3, v16
	s_waitcnt vmcnt(3)
	v_add_u32_e32 v10, s10, v18
	v_mov_b64_e32 v[8:9], s[8:9]
	s_movk_i32 s12, 0x5800
	v_and_b32_e32 v22, 56, v0
	v_mad_i64_i32 v[0:1], s[10:11], v10, s12, v[8:9]
	v_readlane_b32 s10, v252, 35
	v_readlane_b32 s11, v252, 36
	v_add_u32_e32 v10, 64, v10
	s_lshl_b64 s[10:11], s[10:11], 2
	v_mad_i64_i32 v[8:9], s[12:13], v10, s12, v[8:9]
	v_lshl_add_u64 v[0:1], v[0:1], 0, s[10:11]
	v_lshlrev_b32_e32 v166, 2, v22
	v_lshl_add_u64 v[8:9], v[8:9], 0, s[10:11]
	v_lshl_add_u64 v[4:5], v[0:1], 0, v[166:167]
	s_waitcnt vmcnt(2)
	v_lshl_add_u64 v[12:13], v[8:9], 0, v[166:167]
	s_barrier
	global_load_dwordx4 v[0:3], v[4:5], off nt
	s_nop 0
	global_load_dwordx4 v[4:7], v[4:5], off offset:16 nt
	s_nop 0
	global_load_dwordx4 v[8:11], v[12:13], off nt
	s_nop 0
	global_load_dwordx4 v[12:15], v[12:13], off offset:16 nt
	v_and_b32_e32 v19, 63, v16
	v_lshrrev_b32_e32 v20, 1, v16
	v_lshlrev_b32_e32 v16, 4, v16
	v_and_b32_e32 v16, 16, v16
	v_ashrrev_i32_e32 v23, 2, v17
	v_and_or_b32 v20, v20, 15, v16
	v_and_b32_e32 v16, -16, v23
	s_movk_i32 s10, 0x104
	v_or_b32_e32 v23, 15, v23
	v_add_u32_e32 v21, 0, v166
	v_lshl_add_u32 v24, v19, 2, 0
	v_mul_lo_u32 v25, v16, s10
	v_mul_lo_u32 v26, v18, s10
	v_mul_lo_u32 v23, v23, s10
	v_readlane_b32 s14, v252, 33
	v_ashrrev_i32_e32 v17, 31, v16
	s_lshl_b32 s12, s14, 7
	v_add_u32_e32 v21, v21, v26
	v_lshlrev_b32_e32 v166, 2, v22
	v_add_u32_e32 v22, v24, v25
	v_add_u32_e32 v23, v24, v23
	s_waitcnt vmcnt(0)
	s_branch .LBB0_1501

; __device__ __forceinline__ void conv_run(const float* __restrict__ src, u16* __restrict__ dst, int K, int N, int mode, int& base,
;                                          float* lds, int gi, int ng, int wv_) {
;     ...
;   auto gl = [&](int tile) {
;     const int k0 = (tile % nk) * 128, n0 = (tile / nk) * 64;
; #pragma unroll
;     for (int i = 0; i < 2; ++i) {
;       const int kl = (t >> 3) + 64 * i, c8 = (t & 7) * 8;
;       typedef float f4v __attribute__((ext_vector_type(4)));
;       const f4v* sp = (const f4v*)(src + (size_t)(k0 + kl) * N + n0 + c8);
;       const f4v va = __builtin_nontemporal_load(sp), vb = __builtin_nontemporal_load(sp + 1);
;       ra[i] = make_float4(va.x, va.y, va.z, va.w); rb[i] = make_float4(vb.x, vb.y, vb.z, vb.w);
;     }
;   };
;   __syncthreads();
;   if (lt < ntiles) gl(lt);
;   while (lt < ntiles) {
;     const int nxt = lt + ng;
;     const int k0 = (lt % nk) * 128, n0 = (lt / nk) * 64;
;     asm volatile("s_waitcnt lgkmcnt(0)\n\ts_barrier" ::: "memory");
; #pragma unroll
;     for (int i = 0; i < 2; ++i) {
;       const int kl = (t >> 3) + 64 * i, c8 = (t & 7) * 8;
;       float* d = lds + kl * 65 + c8;
;       d[0] = ra[i].x; d[1] = ra[i].y; d[2] = ra[i].z; d[3] = ra[i].w; d[4] = rb[i].x; d[5] = rb[i].y; d[6] = rb[i].z; d[7] = rb[i].w;
;     }
;     if (nxt < ntiles) gl(nxt);
;     asm volatile("s_waitcnt lgkmcnt(0)\n\ts_barrier" ::: "memory");
; __device__ __forceinline__ void convert_set(unsigned char* ws, int set, int gi, int ng, float* lds, int wv_) {
;     ...
;     conv_run(inp(ws, 10) + fw, (u16*)(ws + OFF_W2_11), F_, D_, 0, base, lds, gi, ng, wv_);
.LBB0_1501:
	s_nop 0
	v_add_u32_e32 v24, 0x4100, v21
	s_add_i32 s13, s14, 0x80
	s_waitcnt lgkmcnt(0)
	s_barrier
	s_waitcnt vmcnt(5)
	ds_write2_b32 v21, v0, v1 offset1:1
	ds_write2_b32 v21, v2, v3 offset0:2 offset1:3
	s_waitcnt vmcnt(4)
	ds_write2_b32 v21, v4, v5 offset0:4 offset1:5
	ds_write2_b32 v21, v6, v7 offset0:6 offset1:7
	s_waitcnt vmcnt(3)
	ds_write2_b32 v24, v8, v9 offset1:1
	v_add_u32_e32 v24, 0x4108, v21
	s_cmpk_gt_i32 s14, 0x4ff
	ds_write2_b32 v24, v10, v11 offset1:1
	v_add_u32_e32 v24, 0x4110, v21
	s_cselect_b64 s[10:11], -1, 0
	s_waitcnt vmcnt(2)
	ds_write2_b32 v24, v12, v13 offset1:1
	v_add_u32_e32 v24, 0x4118, v21
	s_and_b64 vcc, exec, s[10:11]
	ds_write2_b32 v24, v14, v15 offset1:1
	s_cbranch_vccnz .LBB0_1500
	s_ashr_i32 s15, s13, 31
	s_lshr_b32 s15, s15, 28
	s_add_i32 s15, s13, s15
	s_ashr_i32 s15, s15, 4
	s_lshl_b32 s16, s15, 6
	v_add_u32_e32 v0, s12, v18
	s_lshl_b32 s15, s15, 11
	v_subrev_u32_e32 v10, s15, v0
	s_ashr_i32 s17, s16, 31
	v_add_u32_e32 v0, 0x4000, v10
	v_mov_b64_e32 v[8:9], s[8:9]
	s_movk_i32 s15, 0x5800
	v_add_u32_e32 v10, 0x4040, v10
	v_mad_i64_i32 v[0:1], s[18:19], v0, s15, v[8:9]
	s_lshl_b64 s[16:17], s[16:17], 2
	v_mad_i64_i32 v[8:9], s[18:19], v10, s15, v[8:9]
	v_lshl_add_u64 v[0:1], v[0:1], 0, s[16:17]
	v_lshl_add_u64 v[8:9], v[8:9], 0, s[16:17]
	v_lshl_add_u64 v[4:5], v[0:1], 0, v[166:167]
	v_lshl_add_u64 v[12:13], v[8:9], 0, v[166:167]
	global_load_dwordx4 v[0:3], v[4:5], off nt
	s_nop 0
	global_load_dwordx4 v[4:7], v[4:5], off offset:16 nt
	s_nop 0
	global_load_dwordx4 v[8:11], v[12:13], off nt
	s_nop 0
	global_load_dwordx4 v[12:15], v[12:13], off offset:16 nt
	s_branch .LBB0_1500
.LBB0_1503:
	s_and_b64 vcc, exec, s[4:5]
	v_readlane_b32 s16, v253, 40
	v_mbcnt_lo_u32_b32 v18, -1, 0
	v_mbcnt_hi_u32_b32 v18, -1, v18
	s_barrier
	v_readlane_b32 s17, v253, 41
	s_cbranch_vccnz .LBB0_1508
	s_load_dwordx2 s[4:5], s[0:1], 0x50
	v_or_b32_e32 v16, s60, v18
	v_ashrrev_i32_e32 v19, 3, v16
	v_readlane_b32 s8, v252, 31
	s_waitcnt vmcnt(5)
	v_lshlrev_b32_e32 v0, 3, v18
	v_and_b32_e32 v22, 56, v0
	s_waitcnt vmcnt(3)
	v_add_u32_e32 v8, s8, v19
	v_ashrrev_i32_e32 v9, 31, v8
	s_waitcnt lgkmcnt(0)
	s_add_u32 s4, s4, 0x2c00000
	v_lshlrev_b64 v[0:1], 13, v[8:9]
	v_add_u32_e32 v8, 64, v8
	s_addc_u32 s5, s5, 0
	v_ashrrev_i32_e32 v9, 31, v8
	s_add_u32 s6, s2, 0xe140000
	v_readlane_b32 s8, v252, 32
	v_lshlrev_b64 v[8:9], 13, v[8:9]
	s_addc_u32 s7, s3, 0
	v_lshl_add_u64 v[0:1], s[4:5], 0, v[0:1]
	s_lshl_b32 s84, s8, 2
	v_lshl_add_u64 v[8:9], s[4:5], 0, v[8:9]
	v_lshl_add_u64 v[0:1], v[0:1], 0, s[84:85]
	v_lshlrev_b32_e32 v166, 2, v22
	v_lshl_add_u64 v[8:9], v[8:9], 0, s[84:85]
	v_lshl_add_u64 v[4:5], v[0:1], 0, v[166:167]
	s_waitcnt vmcnt(2)
	v_lshl_add_u64 v[12:13], v[8:9], 0, v[166:167]
	global_load_dwordx4 v[0:3], v[4:5], off nt
	s_nop 0
	global_load_dwordx4 v[4:7], v[4:5], off offset:16 nt
	s_nop 0
	global_load_dwordx4 v[8:11], v[12:13], off nt
	s_nop 0
	global_load_dwordx4 v[12:15], v[12:13], off offset:16 nt
	v_ashrrev_i32_e32 v23, 2, v16
	v_and_b32_e32 v17, 63, v18
	v_bfe_u32 v21, v18, 2, 4
	v_and_b32_e32 v16, -16, v23
	s_movk_i32 s8, 0x104
	v_or_b32_e32 v23, 15, v23
	v_lshlrev_b32_e32 v27, 6, v18
	v_lshlrev_b32_e32 v18, 4, v18
	v_add_u32_e32 v20, 0, v166
	v_lshl_add_u32 v24, v17, 2, 0
	v_mul_lo_u32 v25, v16, s8
	v_mul_lo_u32 v26, v19, s8
	v_mul_lo_u32 v23, v23, s8
	v_and_b32_e32 v27, 0x80, v27
	v_and_b32_e32 v18, 16, v18
	v_readlane_b32 s8, v253, 13
	v_ashrrev_i32_e32 v17, 31, v16
	v_or3_b32 v18, v27, v21, v18
	v_add_u32_e32 v19, s8, v19
	v_add_u32_e32 v20, v20, v26
	v_lshlrev_b32_e32 v166, 2, v22
	v_add_u32_e32 v21, v24, v25
	v_add_u32_e32 v22, v24, v23
	s_mov_b32 s10, s62
	v_readlane_b32 s11, v253, 14
	v_readlane_b32 s13, v253, 5
	s_waitcnt vmcnt(0)
	s_branch .LBB0_1506

; __device__ __forceinline__ void conv_run(const float* __restrict__ src, u16* __restrict__ dst, int K, int N, int mode, int& base,
;                                          float* lds, int gi, int ng, int wv_) {
;     ...
;   while (lt < ntiles) {
;     const int nxt = lt + ng;
;     const int k0 = (lt % nk) * 128, n0 = (lt / nk) * 64;
;     asm volatile("s_waitcnt lgkmcnt(0)\n\ts_barrier" ::: "memory");
; #pragma unroll
;     for (int i = 0; i < 2; ++i) {
;       const int kl = (t >> 3) + 64 * i, c8 = (t & 7) * 8;
;       float* d = lds + kl * 65 + c8;
;       d[0] = ra[i].x; d[1] = ra[i].y; d[2] = ra[i].z; d[3] = ra[i].w; d[4] = rb[i].x; d[5] = rb[i].y; d[6] = rb[i].z; d[7] = rb[i].w;
;     }
;     if (nxt < ntiles) gl(nxt);
;     asm volatile("s_waitcnt lgkmcnt(0)\n\ts_barrier" ::: "memory");
.LBB0_1506:
	v_add_u32_e32 v23, 0x4100, v20
	s_add_i32 s12, s13, 0x80
	s_waitcnt lgkmcnt(0)
	s_barrier
	s_waitcnt vmcnt(5)
	ds_write2_b32 v20, v0, v1 offset1:1
	ds_write2_b32 v20, v2, v3 offset0:2 offset1:3
	s_waitcnt vmcnt(4)
	ds_write2_b32 v20, v4, v5 offset0:4 offset1:5
	ds_write2_b32 v20, v6, v7 offset0:6 offset1:7
	s_waitcnt vmcnt(3)
	ds_write2_b32 v23, v8, v9 offset1:1
	v_add_u32_e32 v23, 0x4108, v20
	s_cmpk_gt_i32 s13, 0x4ff
	ds_write2_b32 v23, v10, v11 offset1:1
	v_add_u32_e32 v23, 0x4110, v20
	s_cselect_b64 s[8:9], -1, 0
	s_waitcnt vmcnt(2)
	ds_write2_b32 v23, v12, v13 offset1:1
	v_add_u32_e32 v23, 0x4118, v20
	s_and_b64 vcc, exec, s[8:9]
	ds_write2_b32 v23, v14, v15 offset1:1
	s_cbranch_vccnz .LBB0_1505
	s_mul_hi_u32 s14, s10, 0xba2e8ba3
	s_lshr_b32 s14, s14, 5
	s_mulk_i32 s14, 0x1600
	v_subrev_u32_e32 v8, s14, v19
	v_ashrrev_i32_e32 v9, 31, v8
	s_mul_hi_u32 s14, s12, 0xba2e8ba3
	v_lshlrev_b64 v[0:1], 13, v[8:9]
	v_add_u32_e32 v8, 64, v8
	s_lshl_b32 s14, s14, 1
	v_ashrrev_i32_e32 v9, 31, v8
	s_and_b32 s84, s14, 0xffffffc0
	v_lshlrev_b64 v[8:9], 13, v[8:9]
	v_lshl_add_u64 v[0:1], s[4:5], 0, v[0:1]
	s_lshl_b64 s[14:15], s[84:85], 2
	v_lshl_add_u64 v[8:9], s[4:5], 0, v[8:9]
	v_lshl_add_u64 v[0:1], v[0:1], 0, s[14:15]
	v_lshl_add_u64 v[8:9], v[8:9], 0, s[14:15]
	v_lshl_add_u64 v[4:5], v[0:1], 0, v[166:167]
	v_lshl_add_u64 v[12:13], v[8:9], 0, v[166:167]
	global_load_dwordx4 v[0:3], v[4:5], off nt
	s_nop 0
	global_load_dwordx4 v[4:7], v[4:5], off offset:16 nt
	s_nop 0
	global_load_dwordx4 v[8:11], v[12:13], off nt
	s_nop 0
	global_load_dwordx4 v[12:15], v[12:13], off offset:16 nt
	s_branch .LBB0_1505

; #define tidx() tidx_(wv_)
; __device__ __forceinline__ void conv_run(const float* __restrict__ src, u16* __restrict__ dst, int K, int N, int mode, int& base,
;                                          float* lds, int gi, int ng, int wv_) {
;   const int nk = K / 128, nn = N / 64, ntiles = nk * nn;
;   const int t = tidx();
;   int lt = (base & 1) ? (ng - 1 - gi) : gi;
;   base += 1;
;   float4 ra[2], rb[2];
;   auto gl = [&](int tile) {
;     const int k0 = (tile % nk) * 128, n0 = (tile / nk) * 64;
; #pragma unroll
;     for (int i = 0; i < 2; ++i) {
;       const int kl = (t >> 3) + 64 * i, c8 = (t & 7) * 8;
;       typedef float f4v __attribute__((ext_vector_type(4)));
;       const f4v* sp = (const f4v*)(src + (size_t)(k0 + kl) * N + n0 + c8);
;       const f4v va = __builtin_nontemporal_load(sp), vb = __builtin_nontemporal_load(sp + 1);
;       ra[i] = make_float4(va.x, va.y, va.z, va.w); rb[i] = make_float4(vb.x, vb.y, vb.z, vb.w);
;     }
;   };
;   __syncthreads();
;   if (lt < ntiles) gl(lt);
; __device__ __forceinline__ void convert_set(unsigned char* ws, int set, int gi, int ng, float* lds, int wv_) {
;     ...
;     conv_run(inp(ws, 28), (u16*)(ws + OFF_WCDI), D_, CDC_, 0, base, lds, gi, ng, wv_);
.LBB0_1511:
	s_load_dwordx2 s[6:7], s[0:1], 0xe0
	v_mbcnt_lo_u32_b32 v19, -1, 0
	v_mbcnt_hi_u32_b32 v19, -1, v19
	v_readlane_b32 s4, v252, 34
	v_or_b32_e32 v16, s60, v19
	v_ashrrev_i32_e32 v18, 3, v16
	v_lshlrev_b32_e32 v0, 3, v19
	v_and_b32_e32 v22, 56, v0
	s_waitcnt vmcnt(3)
	v_add_u32_e32 v8, s4, v18
	s_waitcnt lgkmcnt(0)
	v_mov_b64_e32 v[0:1], s[6:7]
	s_movk_i32 s10, 0x4400
	v_mad_i64_i32 v[0:1], s[4:5], v8, s10, v[0:1]
	v_readlane_b32 s4, v252, 35
	s_add_u32 s8, s2, 0x10040000
	v_readlane_b32 s5, v252, 36
	v_add_u32_e32 v10, 64, v8
	v_mov_b64_e32 v[8:9], s[6:7]
	s_addc_u32 s9, s3, 0
	s_lshl_b64 s[4:5], s[4:5], 2
	v_mad_i64_i32 v[8:9], s[10:11], v10, s10, v[8:9]
	v_lshl_add_u64 v[0:1], v[0:1], 0, s[4:5]
	v_lshlrev_b32_e32 v166, 2, v22
	v_lshl_add_u64 v[8:9], v[8:9], 0, s[4:5]
	v_lshl_add_u64 v[4:5], v[0:1], 0, v[166:167]
	s_waitcnt vmcnt(2)
	v_lshl_add_u64 v[12:13], v[8:9], 0, v[166:167]
	s_barrier
	global_load_dwordx4 v[0:3], v[4:5], off nt
	s_nop 0
	global_load_dwordx4 v[4:7], v[4:5], off offset:16 nt
	s_nop 0
	global_load_dwordx4 v[8:11], v[12:13], off nt
	s_nop 0
	global_load_dwordx4 v[12:15], v[12:13], off offset:16 nt
	v_ashrrev_i32_e32 v23, 2, v16
	v_and_b32_e32 v17, 63, v19
	v_bfe_u32 v21, v19, 2, 4
	v_and_b32_e32 v16, -16, v23
	s_movk_i32 s10, 0x104
	v_or_b32_e32 v23, 15, v23
	v_lshlrev_b32_e32 v27, 6, v19
	v_lshlrev_b32_e32 v19, 4, v19
	v_readlane_b32 s15, v252, 33
	v_add_u32_e32 v20, 0, v166
	v_lshl_add_u32 v24, v17, 2, 0
	v_mul_lo_u32 v25, v16, s10
	v_mul_lo_u32 v26, v18, s10
	v_mul_lo_u32 v23, v23, s10
	v_and_b32_e32 v27, 0x80, v27
	v_and_b32_e32 v19, 16, v19
	s_lshl_b32 s12, s15, 7
	v_ashrrev_i32_e32 v17, 31, v16
	v_or3_b32 v19, v27, v21, v19
	v_add_u32_e32 v20, v20, v26
	v_lshlrev_b32_e32 v166, 2, v22
	v_add_u32_e32 v21, v24, v25
	v_add_u32_e32 v22, v24, v23
	s_mov_b32 s13, s12
	s_waitcnt vmcnt(0)
	s_branch .LBB0_1513

; __device__ __forceinline__ void conv_run(const float* __restrict__ src, u16* __restrict__ dst, int K, int N, int mode, int& base,
;                                          float* lds, int gi, int ng, int wv_) {
;     ...
;   auto gl = [&](int tile) {
;     const int k0 = (tile % nk) * 128, n0 = (tile / nk) * 64;
; #pragma unroll
;     for (int i = 0; i < 2; ++i) {
;       const int kl = (t >> 3) + 64 * i, c8 = (t & 7) * 8;
;       typedef float f4v __attribute__((ext_vector_type(4)));
;       const f4v* sp = (const f4v*)(src + (size_t)(k0 + kl) * N + n0 + c8);
;       const f4v va = __builtin_nontemporal_load(sp), vb = __builtin_nontemporal_load(sp + 1);
;       ra[i] = make_float4(va.x, va.y, va.z, va.w); rb[i] = make_float4(vb.x, vb.y, vb.z, vb.w);
;     }
;   };
;   __syncthreads();
;   if (lt < ntiles) gl(lt);
;   while (lt < ntiles) {
;     const int nxt = lt + ng;
;     const int k0 = (lt % nk) * 128, n0 = (lt / nk) * 64;
;     asm volatile("s_waitcnt lgkmcnt(0)\n\ts_barrier" ::: "memory");
; #pragma unroll
;     for (int i = 0; i < 2; ++i) {
;       const int kl = (t >> 3) + 64 * i, c8 = (t & 7) * 8;
;       float* d = lds + kl * 65 + c8;
;       d[0] = ra[i].x; d[1] = ra[i].y; d[2] = ra[i].z; d[3] = ra[i].w; d[4] = rb[i].x; d[5] = rb[i].y; d[6] = rb[i].z; d[7] = rb[i].w;
;     }
;     if (nxt < ntiles) gl(nxt);
;     asm volatile("s_waitcnt lgkmcnt(0)\n\ts_barrier" ::: "memory");
; __device__ __forceinline__ void convert_set(unsigned char* ws, int set, int gi, int ng, float* lds, int wv_) {
;     ...
;     conv_run(inp(ws, 29), (u16*)(ws + OFF_WCDO), D_, D_, 0, base, lds, gi, ng, wv_);
.LBB0_1513:
	v_add_u32_e32 v23, 0x4100, v20
	s_add_i32 s14, s15, 0x80
	s_waitcnt lgkmcnt(0)
	s_barrier
	s_waitcnt vmcnt(5)
	ds_write2_b32 v20, v0, v1 offset1:1
	ds_write2_b32 v20, v2, v3 offset0:2 offset1:3
	s_waitcnt vmcnt(4)
	ds_write2_b32 v20, v4, v5 offset0:4 offset1:5
	ds_write2_b32 v20, v6, v7 offset0:6 offset1:7
	s_waitcnt vmcnt(3)
	ds_write2_b32 v23, v8, v9 offset1:1
	v_add_u32_e32 v23, 0x4108, v20
	s_cmpk_gt_i32 s15, 0x3bf
	ds_write2_b32 v23, v10, v11 offset1:1
	v_add_u32_e32 v23, 0x4110, v20
	s_cselect_b64 s[10:11], -1, 0
	s_waitcnt vmcnt(2)
	ds_write2_b32 v23, v12, v13 offset1:1
	v_add_u32_e32 v23, 0x4118, v20
	s_and_b64 vcc, exec, s[10:11]
	ds_write2_b32 v23, v14, v15 offset1:1
	s_cbranch_vccnz .LBB0_1512
	s_ashr_i32 s16, s14, 31
	s_lshr_b32 s16, s16, 28
	s_add_i32 s16, s14, s16
	s_ashr_i32 s18, s16, 4
	s_lshl_b32 s16, s18, 6
	v_add_u32_e32 v0, s13, v18
	s_lshl_b32 s18, s18, 11
	v_subrev_u32_e32 v10, s18, v0
	s_ashr_i32 s17, s16, 31
	v_add_u32_e32 v0, 0x4000, v10
	v_mov_b64_e32 v[8:9], s[6:7]
	s_movk_i32 s22, 0x4400
	v_add_u32_e32 v10, 0x4040, v10
	v_mad_i64_i32 v[0:1], s[18:19], v0, s22, v[8:9]
	s_lshl_b64 s[16:17], s[16:17], 2
	v_mad_i64_i32 v[8:9], s[18:19], v10, s22, v[8:9]
	v_lshl_add_u64 v[0:1], v[0:1], 0, s[16:17]
	v_lshl_add_u64 v[8:9], v[8:9], 0, s[16:17]
	v_lshl_add_u64 v[4:5], v[0:1], 0, v[166:167]
	v_lshl_add_u64 v[12:13], v[8:9], 0, v[166:167]
	global_load_dwordx4 v[0:3], v[4:5], off nt
	s_nop 0
	global_load_dwordx4 v[4:7], v[4:5], off offset:16 nt
	s_nop 0
	global_load_dwordx4 v[8:11], v[12:13], off nt
	s_nop 0
	global_load_dwordx4 v[12:15], v[12:13], off offset:16 nt
	s_branch .LBB0_1512
.LBB0_1515:
	v_readlane_b32 s6, v252, 40
	v_readlane_b32 s7, v252, 41
	s_andn2_b64 vcc, exec, s[6:7]
	v_mbcnt_lo_u32_b32 v19, -1, 0
	v_mbcnt_hi_u32_b32 v19, -1, v19
	s_barrier
	s_cbranch_vccnz .LBB0_1520
	v_or_b32_e32 v16, s60, v19
	v_ashrrev_i32_e32 v18, 3, v16
	v_readlane_b32 s8, v252, 42
	s_load_dwordx2 s[6:7], s[0:1], 0xe8
	s_waitcnt vmcnt(5)
	v_lshlrev_b32_e32 v0, 3, v19
	s_waitcnt vmcnt(3)
	v_add_u32_e32 v8, s8, v18
	v_ashrrev_i32_e32 v9, 31, v8
	v_and_b32_e32 v22, 56, v0
	v_lshlrev_b64 v[0:1], 13, v[8:9]
	v_add_u32_e32 v8, 64, v8
	v_ashrrev_i32_e32 v9, 31, v8
	v_readlane_b32 s8, v253, 1
	v_lshlrev_b64 v[8:9], 13, v[8:9]
	s_waitcnt lgkmcnt(0)
	v_lshl_add_u64 v[0:1], s[6:7], 0, v[0:1]
	v_readlane_b32 s9, v253, 2
	v_lshl_add_u64 v[8:9], s[6:7], 0, v[8:9]
	v_lshlrev_b32_e32 v166, 2, v22
	v_lshl_add_u64 v[0:1], v[0:1], 0, s[8:9]
	v_lshl_add_u64 v[8:9], v[8:9], 0, s[8:9]
	v_lshl_add_u64 v[4:5], v[0:1], 0, v[166:167]
	s_waitcnt vmcnt(2)
	v_lshl_add_u64 v[12:13], v[8:9], 0, v[166:167]
	global_load_dwordx4 v[0:3], v[4:5], off nt
	s_nop 0
	global_load_dwordx4 v[4:7], v[4:5], off offset:16 nt
	s_nop 0
	global_load_dwordx4 v[8:11], v[12:13], off nt
	s_nop 0
	global_load_dwordx4 v[12:15], v[12:13], off offset:16 nt
	v_ashrrev_i32_e32 v23, 2, v16
	v_and_b32_e32 v17, 63, v19
	v_bfe_u32 v21, v19, 2, 4
	v_and_b32_e32 v16, -16, v23
	s_movk_i32 s10, 0x104
	v_or_b32_e32 v23, 15, v23
	v_lshlrev_b32_e32 v27, 6, v19
	v_lshlrev_b32_e32 v19, 4, v19
	s_add_u32 s8, s2, 0x11140000
	v_add_u32_e32 v20, 0, v166
	v_lshl_add_u32 v24, v17, 2, 0
	v_mul_lo_u32 v25, v16, s10
	v_mul_lo_u32 v26, v18, s10
	v_mul_lo_u32 v23, v23, s10
	v_and_b32_e32 v27, 0x80, v27
	v_and_b32_e32 v19, 16, v19
	s_addc_u32 s9, s3, 0
	v_ashrrev_i32_e32 v17, 31, v16
	v_or3_b32 v19, v27, v21, v19
	v_add_u32_e32 v20, v20, v26
	v_lshlrev_b32_e32 v166, 2, v22
	v_add_u32_e32 v21, v24, v25
	v_add_u32_e32 v22, v24, v23
	v_readlane_b32 s13, v253, 6
	v_readlane_b32 s15, v253, 5
	s_waitcnt vmcnt(0)
	s_branch .LBB0_1518

; __device__ __forceinline__ void conv_run(const float* __restrict__ src, u16* __restrict__ dst, int K, int N, int mode, int& base,
;                                          float* lds, int gi, int ng, int wv_) {
;     ...
;   auto gl = [&](int tile) {
;     const int k0 = (tile % nk) * 128, n0 = (tile / nk) * 64;
; #pragma unroll
;     for (int i = 0; i < 2; ++i) {
;       const int kl = (t >> 3) + 64 * i, c8 = (t & 7) * 8;
;       typedef float f4v __attribute__((ext_vector_type(4)));
;       const f4v* sp = (const f4v*)(src + (size_t)(k0 + kl) * N + n0 + c8);
;       const f4v va = __builtin_nontemporal_load(sp), vb = __builtin_nontemporal_load(sp + 1);
;       ra[i] = make_float4(va.x, va.y, va.z, va.w); rb[i] = make_float4(vb.x, vb.y, vb.z, vb.w);
;     }
;   };
;   __syncthreads();
;   if (lt < ntiles) gl(lt);
;   while (lt < ntiles) {
;     const int nxt = lt + ng;
;     const int k0 = (lt % nk) * 128, n0 = (lt / nk) * 64;
;     asm volatile("s_waitcnt lgkmcnt(0)\n\ts_barrier" ::: "memory");
; #pragma unroll
;     for (int i = 0; i < 2; ++i) {
;       const int kl = (t >> 3) + 64 * i, c8 = (t & 7) * 8;
;       float* d = lds + kl * 65 + c8;
;       d[0] = ra[i].x; d[1] = ra[i].y; d[2] = ra[i].z; d[3] = ra[i].w; d[4] = rb[i].x; d[5] = rb[i].y; d[6] = rb[i].z; d[7] = rb[i].w;
;     }
;     if (nxt < ntiles) gl(nxt);
;     asm volatile("s_waitcnt lgkmcnt(0)\n\ts_barrier" ::: "memory");
; __device__ __forceinline__ void convert_set(unsigned char* ws, int set, int gi, int ng, float* lds, int wv_) {
;     ...
;     conv_run(inp(ws, 12) + (size_t)D_ * D_, (u16*)(ws + OFF_WG1), D_, D_, 0, base, lds, gi, ng, wv_);
.LBB0_1518:
	v_add_u32_e32 v23, 0x4100, v20
	s_add_i32 s14, s15, 0x80
	s_waitcnt lgkmcnt(0)
	s_barrier
	s_waitcnt vmcnt(5)
	ds_write2_b32 v20, v0, v1 offset1:1
	ds_write2_b32 v20, v2, v3 offset0:2 offset1:3
	s_waitcnt vmcnt(4)
	ds_write2_b32 v20, v4, v5 offset0:4 offset1:5
	ds_write2_b32 v20, v6, v7 offset0:6 offset1:7
	s_waitcnt vmcnt(3)
	ds_write2_b32 v23, v8, v9 offset1:1
	v_add_u32_e32 v23, 0x4108, v20
	s_cmpk_gt_i32 s15, 0x17f
	ds_write2_b32 v23, v10, v11 offset1:1
	v_add_u32_e32 v23, 0x4110, v20
	s_cselect_b64 s[10:11], -1, 0
	s_waitcnt vmcnt(2)
	ds_write2_b32 v23, v12, v13 offset1:1
	v_add_u32_e32 v23, 0x4118, v20
	s_and_b64 vcc, exec, s[10:11]
	ds_write2_b32 v23, v14, v15 offset1:1
	s_cbranch_vccnz .LBB0_1517
	s_ashr_i32 s16, s14, 31
	s_lshr_b32 s16, s16, 28
	s_add_i32 s16, s14, s16
	s_ashr_i32 s18, s16, 4
	s_lshl_b32 s16, s18, 6
	v_add_u32_e32 v0, s13, v18
	s_lshl_b32 s18, s18, 11
	v_subrev_u32_e32 v8, s18, v0
	v_add_u32_e32 v0, 0x4000, v8
	v_add_u32_e32 v8, 0x4040, v8
	v_ashrrev_i32_e32 v1, 31, v0
	v_ashrrev_i32_e32 v9, 31, v8
	s_ashr_i32 s17, s16, 31
	v_lshlrev_b64 v[0:1], 13, v[0:1]
	v_lshlrev_b64 v[8:9], 13, v[8:9]
	v_lshl_add_u64 v[0:1], s[6:7], 0, v[0:1]
	s_lshl_b64 s[16:17], s[16:17], 2
	v_lshl_add_u64 v[8:9], s[6:7], 0, v[8:9]
	v_lshl_add_u64 v[0:1], v[0:1], 0, s[16:17]
	v_lshl_add_u64 v[8:9], v[8:9], 0, s[16:17]
	v_lshl_add_u64 v[4:5], v[0:1], 0, v[166:167]
	v_lshl_add_u64 v[12:13], v[8:9], 0, v[166:167]
	global_load_dwordx4 v[0:3], v[4:5], off nt
	s_nop 0
	global_load_dwordx4 v[4:7], v[4:5], off offset:16 nt
	s_nop 0
	global_load_dwordx4 v[8:11], v[12:13], off nt
	s_nop 0
	global_load_dwordx4 v[12:15], v[12:13], off offset:16 nt
	s_branch .LBB0_1517
.LBB0_1520:
	s_load_dwordx2 s[6:7], s[0:1], 0x60
	v_mbcnt_lo_u32_b32 v19, -1, 0
	v_mbcnt_hi_u32_b32 v19, -1, v19
	v_readlane_b32 s8, v252, 34
	v_or_b32_e32 v16, s60, v19
	v_ashrrev_i32_e32 v18, 3, v16
	s_waitcnt vmcnt(3)
	v_add_u32_e32 v8, s8, v18
	v_lshlrev_b32_e32 v0, 3, v19
	v_ashrrev_i32_e32 v9, 31, v8
	v_and_b32_e32 v22, 56, v0
	v_lshlrev_b64 v[0:1], 13, v[8:9]
	v_add_u32_e32 v8, 64, v8
	s_waitcnt lgkmcnt(0)
	s_add_u32 s6, s6, 0x1000000
	v_ashrrev_i32_e32 v9, 31, v8
	s_addc_u32 s7, s7, 0
	v_lshlrev_b64 v[8:9], 13, v[8:9]
	v_lshl_add_u64 v[0:1], s[6:7], 0, v[0:1]
	v_lshl_add_u64 v[8:9], s[6:7], 0, v[8:9]
	v_lshl_add_u64 v[0:1], v[0:1], 0, s[4:5]
	v_lshlrev_b32_e32 v166, 2, v22
	v_lshl_add_u64 v[8:9], v[8:9], 0, s[4:5]
	v_lshl_add_u64 v[4:5], v[0:1], 0, v[166:167]
	s_waitcnt vmcnt(2)
	v_lshl_add_u64 v[12:13], v[8:9], 0, v[166:167]
	s_barrier
	global_load_dwordx4 v[0:3], v[4:5], off nt
	s_nop 0
	global_load_dwordx4 v[4:7], v[4:5], off offset:16 nt
	s_nop 0
	global_load_dwordx4 v[8:11], v[12:13], off nt
	s_nop 0
	global_load_dwordx4 v[12:15], v[12:13], off offset:16 nt
	v_ashrrev_i32_e32 v23, 2, v16
	v_and_b32_e32 v17, 63, v19
	v_bfe_u32 v21, v19, 2, 4
	v_and_b32_e32 v16, -16, v23
	s_movk_i32 s4, 0x104
	v_or_b32_e32 v23, 15, v23
	v_lshlrev_b32_e32 v27, 6, v19
	v_lshlrev_b32_e32 v19, 4, v19
	s_add_u32 s2, s2, 0xf740000
	v_add_u32_e32 v20, 0, v166
	v_lshl_add_u32 v24, v17, 2, 0
	v_mul_lo_u32 v25, v16, s4
	v_mul_lo_u32 v26, v18, s4
	v_mul_lo_u32 v23, v23, s4
	v_and_b32_e32 v27, 0x80, v27
	v_and_b32_e32 v19, 16, v19
	s_addc_u32 s3, s3, 0
	v_ashrrev_i32_e32 v17, 31, v16
	v_or3_b32 v19, v27, v21, v19
	v_add_u32_e32 v20, v20, v26
	v_lshlrev_b32_e32 v166, 2, v22
	v_add_u32_e32 v21, v24, v25
	v_add_u32_e32 v22, v24, v23
	v_readlane_b32 s9, v252, 33
	v_readlane_b32 s16, v253, 40
	v_readlane_b32 s14, v253, 42
	v_readlane_b32 s13, v253, 53
	v_readlane_b32 s17, v253, 41
	v_readlane_b32 s15, v253, 43
	s_waitcnt vmcnt(0)
	s_branch .LBB0_1522

; __device__ __forceinline__ void conv_run(const float* __restrict__ src, u16* __restrict__ dst, int K, int N, int mode, int& base,
;                                          float* lds, int gi, int ng, int wv_) {
;     ...
;   while (lt < ntiles) {
;     const int nxt = lt + ng;
;     const int k0 = (lt % nk) * 128, n0 = (lt / nk) * 64;
;     asm volatile("s_waitcnt lgkmcnt(0)\n\ts_barrier" ::: "memory");
; #pragma unroll
;     for (int i = 0; i < 2; ++i) {
;       const int kl = (t >> 3) + 64 * i, c8 = (t & 7) * 8;
;       float* d = lds + kl * 65 + c8;
;       d[0] = ra[i].x; d[1] = ra[i].y; d[2] = ra[i].z; d[3] = ra[i].w; d[4] = rb[i].x; d[5] = rb[i].y; d[6] = rb[i].z; d[7] = rb[i].w;
;     }
;     if (nxt < ntiles) gl(nxt);
;     asm volatile("s_waitcnt lgkmcnt(0)\n\ts_barrier" ::: "memory");
.LBB0_1522:
	v_add_u32_e32 v23, 0x4100, v20
	s_add_i32 s8, s9, 0x80
	s_waitcnt lgkmcnt(0)
	s_barrier
	s_waitcnt vmcnt(5)
	ds_write2_b32 v20, v0, v1 offset1:1
	ds_write2_b32 v20, v2, v3 offset0:2 offset1:3
	s_waitcnt vmcnt(4)
	ds_write2_b32 v20, v4, v5 offset0:4 offset1:5
	ds_write2_b32 v20, v6, v7 offset0:6 offset1:7
	s_waitcnt vmcnt(3)
	ds_write2_b32 v23, v8, v9 offset1:1
	v_add_u32_e32 v23, 0x4108, v20
	s_cmpk_gt_i32 s9, 0x17f
	ds_write2_b32 v23, v10, v11 offset1:1
	v_add_u32_e32 v23, 0x4110, v20
	s_cselect_b64 s[4:5], -1, 0
	s_waitcnt vmcnt(2)
	ds_write2_b32 v23, v12, v13 offset1:1
	v_add_u32_e32 v23, 0x4118, v20
	s_and_b64 vcc, exec, s[4:5]
	ds_write2_b32 v23, v14, v15 offset1:1
	s_cbranch_vccnz .LBB0_1521
	s_ashr_i32 s10, s8, 31
	s_lshr_b32 s10, s10, 28
	s_add_i32 s10, s8, s10
	s_ashr_i32 s13, s10, 4
	s_lshl_b32 s10, s13, 6
	v_add_u32_e32 v0, s12, v18
	s_lshl_b32 s13, s13, 11
	v_subrev_u32_e32 v8, s13, v0
	v_add_u32_e32 v0, 0x4000, v8
	v_add_u32_e32 v8, 0x4040, v8
	v_ashrrev_i32_e32 v1, 31, v0
	v_ashrrev_i32_e32 v9, 31, v8
	s_ashr_i32 s11, s10, 31
	v_lshlrev_b64 v[0:1], 13, v[0:1]
	v_lshlrev_b64 v[8:9], 13, v[8:9]
	v_lshl_add_u64 v[0:1], s[6:7], 0, v[0:1]
	s_lshl_b64 s[10:11], s[10:11], 2
	v_lshl_add_u64 v[8:9], s[6:7], 0, v[8:9]
	v_lshl_add_u64 v[0:1], v[0:1], 0, s[10:11]
	v_lshl_add_u64 v[8:9], v[8:9], 0, s[10:11]
	v_lshl_add_u64 v[4:5], v[0:1], 0, v[166:167]
	v_lshl_add_u64 v[12:13], v[8:9], 0, v[166:167]
	global_load_dwordx4 v[0:3], v[4:5], off nt
	s_nop 0
	global_load_dwordx4 v[4:7], v[4:5], off offset:16 nt
	s_nop 0
	global_load_dwordx4 v[8:11], v[12:13], off nt
	s_nop 0
	global_load_dwordx4 v[12:15], v[12:13], off offset:16 nt
	v_readlane_b32 s13, v253, 53
	s_branch .LBB0_1521
